# P5,P6,P11,P12 tile stores write-through (sc1) and the release write-back of the barrier after those phases dropped; on top of flat barrier release
# speedup vs baseline: 1.0074x; 1.0074x over previous
; #define GAS __attribute__((address_space(1)))
; #define WG_BAR() asm volatile("s_waitcnt lgkmcnt(0)\n\ts_barrier" ::: "memory")
; template <class RowEpi, int MTL>
; __device__ __forceinline__ void small_gemm_t(Frame& F, const bf16* A  , const bf16* Bt, int N, int K, const RowEpi& R, int i_lo, int i_hi) {
;     ...
;         const int ar0 = rb * 16 * MTL + fr, ak0 = w * kw + 8 * fq;
;         const int bp0 = pn * 256 + 32 * wc + fr, bk0 = w * kw + 8 * fq;
; #pragma unroll 4
;         for (int k = 0; k < kw; k += 32) {
;             bf16x8 a[MTL], b[2][2];
; #pragma unroll
;             for (int m = 0; m < MTL; ++m) a[m] = *(const GAS bf16x8*)(A + wt_off(ar0 + 16 * m, ak0 + k, K));
; #pragma unroll
;             for (int bj = 0; bj < 2; ++bj)
; #pragma unroll
;                 for (int n = 0; n < 2; ++n) b[bj][n] = *(const GAS bf16x8*)(Bt + wt_off(bp0 + 128 * bj + 16 * n, bk0 + k, K));
; #pragma unroll
;             for (int m = 0; m < MTL; ++m)
; #pragma unroll
;                 for (int bj = 0; bj < 2; ++bj)
; #pragma unroll
;                     for (int n = 0; n < 2; ++n) acc[m][bj][n] = __builtin_amdgcn_mfma_f32_16x16x32_bf16(b[bj][n], a[m], acc[m][bj][n], 0, 0, 0);
;         }
; #pragma unroll
;         for (int m = 0; m < MTL; ++m)
; #pragma unroll
;             for (int bj = 0; bj < 2; ++bj)
; #pragma unroll
;                 for (int n = 0; n < 2; ++n) part[(w * (4 * MTL) + m * 4 + bj * 2 + n) * 64 + lane] = acc[m][bj][n];
;         WG_BAR();
.LBB0_902:
	v_add_u32_e32 v36, s23, v29
	v_lshrrev_b32_e32 v20, 6, v36
	v_add_u32_e32 v38, 32, v36
	v_add_u32_e32 v41, 0x60, v36
	v_lshlrev_b64 v[42:43], 15, v[20:21]
	v_mov_b32_e32 v37, v21
	v_mov_b32_e32 v39, v21
	v_add_u32_e32 v62, 64, v36
	v_add_u32_e32 v40, s13, v20
	v_lshrrev_b32_e32 v36, 6, v38
	v_bfe_u32 v20, v38, 5, 1
	v_lshlrev_b32_e32 v45, 1, v38
	v_lshrrev_b32_e32 v38, 6, v41
	v_lshlrev_b32_e32 v48, 1, v41
	v_lshl_add_u64 v[42:43], s[20:21], 0, v[42:43]
	v_add_u32_e32 v44, s13, v36
	v_lshlrev_b64 v[36:37], 15, v[36:37]
	v_add_u32_e32 v46, s13, v38
	v_and_b32_e32 v53, 48, v48
	v_lshlrev_b64 v[38:39], 15, v[38:39]
	v_lshl_add_u64 v[48:49], v[42:43], 0, v[24:25]
	v_lshl_add_u64 v[60:61], s[20:21], 0, v[36:37]
	v_lshl_add_u64 v[72:73], s[20:21], 0, v[38:39]
	global_load_dwordx4 v[36:39], v[48:49], off offset:2048
	v_bfe_u32 v47, v41, 5, 1
	v_ashrrev_i32_e32 v41, 31, v40
	v_or_b32_e32 v50, s16, v20
	v_and_b32_e32 v51, 48, v45
	v_or_b32_e32 v52, s16, v47
	v_lshlrev_b64 v[40:41], 15, v[40:41]
	v_lshl_add_u64 v[42:43], v[42:43], 0, s[18:19]
	v_or_b32_e32 v20, s22, v20
	v_or_b32_e32 v54, s22, v47
	v_ashrrev_i32_e32 v45, 31, v44
	v_or_b32_e32 v63, v51, v30
	v_lshlrev_b32_e32 v55, 10, v50
	v_ashrrev_i32_e32 v47, 31, v46
	v_or_b32_e32 v70, v53, v30
	v_lshlrev_b32_e32 v82, 10, v52
	v_lshl_add_u64 v[40:41], v[22:23], 0, v[40:41]
	v_lshl_add_u64 v[50:51], v[42:43], 0, v[24:25]
	v_lshl_add_u64 v[52:53], v[42:43], 0, v[26:27]
	v_lshlrev_b32_e32 v64, 10, v20
	v_lshlrev_b32_e32 v83, 10, v54
	v_lshlrev_b64 v[56:57], 15, v[44:45]
	v_bitop3_b32 v20, v63, v55, v31 bitop3:0xde
	v_lshlrev_b64 v[58:59], 15, v[46:47]
	global_load_dwordx4 v[40:43], v[40:41], off
	s_nop 0
	global_load_dwordx4 v[44:47], v[48:49], off
	s_nop 0
	global_load_dwordx4 v[48:51], v[50:51], off
	s_nop 0
	global_load_dwordx4 v[52:55], v[52:53], off
	v_lshl_add_u64 v[56:57], s[4:5], 0, v[56:57]
	v_lshl_add_u64 v[56:57], v[56:57], 0, v[20:21]
	v_bitop3_b32 v20, v63, v64, v31 bitop3:0xde
	v_mov_b32_e32 v69, v21
	v_lshl_add_u64 v[74:75], v[60:61], 0, s[18:19]
	v_lshl_add_u64 v[64:65], v[60:61], 0, v[20:21]
	v_or_b32_e32 v68, 0x800, v20
	v_lshl_add_u64 v[78:79], s[4:5], 0, v[58:59]
	global_load_dwordx4 v[56:59], v[56:57], off
	v_lshl_add_u64 v[66:67], v[74:75], 0, v[20:21]
	v_lshrrev_b32_e32 v20, 6, v62
	global_load_dwordx4 v[60:63], v[64:65], off offset:2048
	v_lshl_add_u64 v[68:69], v[74:75], 0, v[68:69]
	v_add_u32_e32 v74, s13, v20
	v_lshlrev_b64 v[80:81], 15, v[20:21]
	v_ashrrev_i32_e32 v75, 31, v74
	v_bitop3_b32 v20, v70, v82, v31 bitop3:0xde
	v_mov_b32_e32 v71, v21
	v_lshl_add_u64 v[76:77], v[72:73], 0, s[18:19]
	s_add_i32 s33, s23, 0x80
	s_addk_i32 s23, 0x60
	s_cmpk_lt_u32 s23, 0x1e0
	s_mov_b32 s23, s33
	s_waitcnt vmcnt(4)
	v_mfma_f32_16x16x32_bf16 v[2:5], v[44:47], v[40:43], v[2:5]
	v_mfma_f32_16x16x32_bf16 v[6:9], v[36:39], v[40:43], v[6:9]
	global_load_dwordx4 v[36:39], v[64:65], off
	s_nop 0
	global_load_dwordx4 v[64:67], v[66:67], off
	s_nop 0
	global_load_dwordx4 v[44:47], v[68:69], off
	s_waitcnt vmcnt(5)
	v_mfma_f32_16x16x32_bf16 v[14:17], v[52:55], v[40:43], v[14:17]
	v_lshl_add_u64 v[52:53], v[78:79], 0, v[20:21]
	v_bitop3_b32 v20, v70, v83, v31 bitop3:0xde
	v_or_b32_e32 v70, 0x800, v20
	v_mfma_f32_16x16x32_bf16 v[10:13], v[48:51], v[40:43], v[10:13]
	v_lshl_add_u64 v[40:41], s[20:21], 0, v[80:81]
	v_lshlrev_b64 v[42:43], 15, v[74:75]
	v_lshl_add_u64 v[54:55], v[40:41], 0, s[18:19]
	s_waitcnt vmcnt(3)
	v_mfma_f32_16x16x32_bf16 v[6:9], v[60:63], v[56:59], v[6:9]
	v_lshl_add_u64 v[48:49], v[40:41], 0, v[24:25]
	v_lshl_add_u64 v[40:41], v[22:23], 0, v[42:43]
	v_lshl_add_u64 v[60:61], v[54:55], 0, v[24:25]
	global_load_dwordx4 v[40:43], v[40:41], off
	s_waitcnt vmcnt(3)
	v_mfma_f32_16x16x32_bf16 v[2:5], v[36:39], v[56:59], v[2:5]
	global_load_dwordx4 v[36:39], v[48:49], off offset:2048
	s_waitcnt vmcnt(2)
	v_mfma_f32_16x16x32_bf16 v[14:17], v[44:47], v[56:59], v[14:17]
	global_load_dwordx4 v[44:47], v[60:61], off
	s_nop 0
	global_load_dwordx4 v[48:51], v[48:49], off
	v_mfma_f32_16x16x32_bf16 v[10:13], v[64:67], v[56:59], v[10:13]
	v_lshl_add_u64 v[56:57], v[72:73], 0, v[20:21]
	v_lshl_add_u64 v[58:59], v[76:77], 0, v[20:21]
	s_waitcnt vmcnt(2)
	v_mfma_f32_16x16x32_bf16 v[6:9], v[36:39], v[40:43], v[6:9]
	global_load_dwordx4 v[36:39], v[56:57], off offset:2048
	s_waitcnt vmcnt(1)
	v_mfma_f32_16x16x32_bf16 v[2:5], v[48:51], v[40:43], v[2:5]
	v_lshl_add_u64 v[48:49], v[54:55], 0, v[26:27]
	v_mfma_f32_16x16x32_bf16 v[10:13], v[44:47], v[40:43], v[10:13]
	global_load_dwordx4 v[44:47], v[48:49], off
	s_nop 0
	global_load_dwordx4 v[48:51], v[52:53], off
	s_waitcnt vmcnt(1)
	v_mfma_f32_16x16x32_bf16 v[14:17], v[44:47], v[40:43], v[14:17]
	global_load_dwordx4 v[40:43], v[56:57], off
	v_lshl_add_u64 v[44:45], v[76:77], 0, v[70:71]
	s_waitcnt vmcnt(1)
	v_mfma_f32_16x16x32_bf16 v[6:9], v[36:39], v[48:51], v[6:9]
	global_load_dwordx4 v[36:39], v[58:59], off
	s_waitcnt vmcnt(1)
	v_mfma_f32_16x16x32_bf16 v[2:5], v[40:43], v[48:51], v[2:5]
	global_load_dwordx4 v[40:43], v[44:45], off
	s_waitcnt vmcnt(1)
	v_mfma_f32_16x16x32_bf16 v[10:13], v[36:39], v[48:51], v[10:13]
	s_waitcnt vmcnt(0)
	v_mfma_f32_16x16x32_bf16 v[14:17], v[40:43], v[48:51], v[14:17]
	s_cbranch_scc1 .LBB0_902
	s_nop 1
	ds_write_b128 v34, v[2:5]
	ds_write_b128 v34, v[6:9] offset:1024
	s_nop 0
	ds_write_b128 v34, v[10:13] offset:2048
	s_nop 0
	ds_write_b128 v34, v[14:17] offset:3072
	s_waitcnt lgkmcnt(0)
	s_barrier
	s_andn2_b64 vcc, exec, s[14:15]
	s_cbranch_vccnz .LBB0_898
; #define GAS __attribute__((address_space(1)))
; __device__ __forceinline__ float bflo(unsigned w) { return __uint_as_float(w << 16); }
; __device__ __forceinline__ float bfhi(unsigned w) { return __uint_as_float(w & 0xffff0000u); }
;     template <int NR> __device__ __forceinline__ void rows(const int (&rowb)[NR], int fr, const float (&rstd)[NR], const f32x4 (&a)[NR][2][2], int pn, int wc, int fq) const {
;     ...
;                 for (int bj = 0; bj < 2; ++bj) w[i][bj] = *(const GAS v4u*)((const char*)XN + tile_ub(rowb[i], c0b + 32 * bj, DM) + ltb);
; #pragma unroll
;             for (int i = 0; i < NR; ++i)
; #pragma unroll
;                 for (int bj = 0; bj < 2; ++bj) { bs[i][bj][0] = (f32x4){bflo(w[i][bj].x), bfhi(w[i][bj].x), bflo(w[i][bj].y), bfhi(w[i][bj].y)}; bs[i][bj][1] = (f32x4){bflo(w[i][bj].z), bfhi(w[i][bj].z), bflo(w[i][bj].w), bfhi(w[i][bj].w)}; }
; template <class RowEpi, int MTL>
; __device__ __forceinline__ void small_gemm_t(Frame& F, const bf16* A  , const bf16* Bt, int N, int K, const RowEpi& R, int i_lo, int i_hi) {
;     ...
;         if (w < MTL) {
;             f32x4 s[2][2];
; #pragma unroll
;             for (int bj = 0; bj < 2; ++bj)
; #pragma unroll
;                 for (int n = 0; n < 2; ++n) { f32x4 t = (f32x4){0.f, 0.f, 0.f, 0.f};
; #pragma unroll
;                     for (int ww = 0; ww < 8; ++ww) t += part[(ww * (4 * MTL) + w * 4 + bj * 2 + n) * 64 + lane];
;                     s[bj][n] = t; }
	s_add_i32 s12, s0, s12
	s_ashr_i32 s4, s3, 6
	s_lshr_b32 s16, s12, 8
	s_ashr_i32 s5, s4, 31
	s_lshl_b32 s3, s12, 7
	s_lshl_b64 s[20:21], s[16:17], 19
	s_lshl_b64 s[4:5], s[4:5], 15
	s_and_b32 s13, s3, 0x4000
	s_add_u32 s16, s50, s20
	ds_read_b128 v[2:5], v34
	ds_read_b128 v[6:9], v34 offset:4096
	ds_read_b128 v[10:13], v34 offset:8192
	ds_read_b128 v[14:17], v34 offset:1024
	s_addc_u32 s20, s51, s21
	s_add_u32 s4, s16, s4
	s_waitcnt lgkmcnt(3)
	v_pk_add_f32 v[22:23], v[4:5], 0 op_sel_hi:[1,0]
	v_pk_add_f32 v[24:25], v[2:3], 0 op_sel_hi:[1,0]
	s_addc_u32 s5, s20, s5
	ds_read_b128 v[2:5], v34 offset:5120
	s_waitcnt lgkmcnt(3)
	v_pk_add_f32 v[26:27], v[22:23], v[8:9]
	v_pk_add_f32 v[36:37], v[24:25], v[6:7]
	ds_read_b128 v[6:9], v34 offset:12288
	ds_read_b128 v[22:25], v34 offset:9216
	s_add_u32 s4, s4, s13
	s_addc_u32 s5, s5, 0
	v_lshl_add_u64 v[40:41], s[4:5], 0, v[18:19]
	s_and_b32 s16, s3, 0x3800
	s_waitcnt lgkmcnt(4)
	v_pk_add_f32 v[26:27], v[26:27], v[12:13]
	v_pk_add_f32 v[36:37], v[36:37], v[10:11]
	v_lshl_add_u64 v[52:53], v[40:41], 0, s[16:17]
	ds_read_b128 v[10:13], v34 offset:13312
	s_waitcnt lgkmcnt(2)
	v_pk_add_f32 v[26:27], v[26:27], v[8:9]
	v_pk_add_f32 v[48:49], v[36:37], v[6:7]
	ds_read_b128 v[6:9], v34 offset:16384
	ds_read_b128 v[36:39], v34 offset:20480
	global_load_dwordx4 v[40:43], v[52:53], off
	ds_read_b128 v[44:47], v34 offset:17408
	v_pk_add_f32 v[16:17], v[16:17], 0 op_sel_hi:[1,0]
	s_waitcnt lgkmcnt(2)
	v_pk_add_f32 v[26:27], v[26:27], v[8:9]
	v_pk_add_f32 v[54:55], v[48:49], v[6:7]
	s_waitcnt lgkmcnt(1)
	v_pk_add_f32 v[26:27], v[26:27], v[38:39]
	v_pk_add_f32 v[60:61], v[54:55], v[36:37]
	global_load_dwordx4 v[36:39], v[52:53], off offset:1024
	ds_read_b128 v[6:9], v34 offset:21504
	ds_read_b128 v[48:51], v34 offset:24576
	v_pk_add_f32 v[14:15], v[14:15], 0 op_sel_hi:[1,0]
	ds_read_b128 v[52:55], v34 offset:28672
	ds_read_b128 v[56:59], v34 offset:25600
	v_pk_add_f32 v[4:5], v[16:17], v[4:5]
	v_pk_add_f32 v[2:3], v[14:15], v[2:3]
	v_pk_add_f32 v[4:5], v[4:5], v[24:25]
	v_pk_add_f32 v[2:3], v[2:3], v[22:23]
	v_pk_add_f32 v[4:5], v[4:5], v[12:13]
	v_pk_add_f32 v[2:3], v[2:3], v[10:11]
	s_waitcnt lgkmcnt(4)
	v_pk_add_f32 v[4:5], v[4:5], v[46:47]
	v_pk_add_f32 v[2:3], v[2:3], v[44:45]
	s_waitcnt lgkmcnt(2)
	v_pk_add_f32 v[26:27], v[26:27], v[50:51]
	v_pk_add_f32 v[60:61], v[60:61], v[48:49]
	ds_read_b128 v[48:51], v34 offset:29696
	v_pk_add_f32 v[4:5], v[4:5], v[8:9]
	v_pk_add_f32 v[2:3], v[2:3], v[6:7]
	s_waitcnt lgkmcnt(1)
	v_pk_add_f32 v[6:7], v[4:5], v[58:59]
	v_pk_add_f32 v[8:9], v[2:3], v[56:57]
	ds_read_b128 v[2:5], v34 offset:2048
	s_waitcnt lgkmcnt(1)
	v_pk_add_f32 v[62:63], v[6:7], v[50:51]
	v_pk_add_f32 v[64:65], v[8:9], v[48:49]
	ds_read_b128 v[6:9], v34 offset:6144
	ds_read_b128 v[10:13], v34 offset:3072
	v_pk_add_f32 v[26:27], v[26:27], v[54:55]
	s_waitcnt lgkmcnt(2)
	v_pk_add_f32 v[22:23], v[4:5], 0 op_sel_hi:[1,0]
	v_pk_add_f32 v[24:25], v[2:3], 0 op_sel_hi:[1,0]
	ds_read_b128 v[2:5], v34 offset:10240
	ds_read_b128 v[14:17], v34 offset:7168
	s_waitcnt lgkmcnt(3)
	v_pk_add_f32 v[44:45], v[22:23], v[8:9]
	v_pk_add_f32 v[46:47], v[24:25], v[6:7]
	ds_read_b128 v[6:9], v34 offset:14336
	ds_read_b128 v[22:25], v34 offset:11264
	s_waitcnt lgkmcnt(3)
	v_pk_add_f32 v[48:49], v[44:45], v[4:5]
	v_pk_add_f32 v[50:51], v[46:47], v[2:3]
	ds_read_b128 v[2:5], v34 offset:18432
	ds_read_b128 v[44:47], v34 offset:15360
	v_pk_add_f32 v[60:61], v[60:61], v[52:53]
	s_waitcnt lgkmcnt(3)
	v_pk_add_f32 v[52:53], v[48:49], v[8:9]
	v_pk_add_f32 v[54:55], v[50:51], v[6:7]
	ds_read_b128 v[6:9], v34 offset:22528
	ds_read_b128 v[48:51], v34 offset:19456
	s_waitcnt lgkmcnt(3)
	v_pk_add_f32 v[56:57], v[52:53], v[4:5]
	v_pk_add_f32 v[58:59], v[54:55], v[2:3]
	ds_read_b128 v[2:5], v34 offset:26624
	ds_read_b128 v[52:55], v34 offset:23552
	v_pk_add_f32 v[12:13], v[12:13], 0 op_sel_hi:[1,0]
	v_pk_add_f32 v[10:11], v[10:11], 0 op_sel_hi:[1,0]
	s_waitcnt lgkmcnt(3)
; __device__ __forceinline__ void st_bf8(bf16* p, const f32x4 a, const f32x4 b) { *(GAS v4u*)p = (v4u){pk2(a.x, a.y), pk2(a.z, a.w), pk2(b.x, b.y), pk2(b.z, b.w)}; }
; __device__ __forceinline__ float sq4(const f32x4 a) { return (a.x * a.x + a.y * a.y) + (a.z * a.z + a.w * a.w); }
; __device__ __forceinline__ void row_atomic(float* rs, int row, float s, int fq) { s += __shfl_xor(s, 16); s += __shfl_xor(s, 32); if (fq == 0) atomicAdd(rs + row, s); }
; __device__ __forceinline__ void nt_store4(float* p, f32x4 v) { __builtin_nontemporal_store(v, (f32x4*)p); }
;     template <int NR> __device__ __forceinline__ void rows(const int (&rowb)[NR], int fr, const float (&rstd)[NR], const f32x4 (&a)[NR][2][2], int pn, int wc, int fq) const {
;     ...
; #pragma unroll
;         for (int i = 0; i < NR; ++i) {
;             const float rr = rstd[i];
;             float ss = 0.f;
; #pragma unroll
;             for (int bj = 0; bj < 2; ++bj) {
;                 const size_t off = (size_t)(rowb[i] + fr) * DM + c0 + 32 * bj;
;                 const f32x4 u = bs[i][bj][0] + a[i][bj][0] * rr, v = bs[i][bj][1] + a[i][bj][1] * rr;
;                 if (Yout) { nt_store4(Yout + off, u); nt_store4(Yout + off + 4, v); }
;                 if (wr_xn) st_bf8((bf16*)((char*)XN + tile_ub(rowb[i], c0b + 32 * bj, DM) + ltb), u, v);
;                 ss += sq4(u) + sq4(v);
;             }
;             if (rs_out) row_atomic(rs_out, rowb[i] + fr, ss, fq);
;         }
	v_pk_add_f32 v[66:67], v[56:57], v[8:9]
	v_pk_add_f32 v[68:69], v[58:59], v[6:7]
	ds_read_b128 v[6:9], v34 offset:30720
	ds_read_b128 v[56:59], v34 offset:27648
	v_pk_add_f32 v[12:13], v[12:13], v[16:17]
	v_pk_add_f32 v[10:11], v[10:11], v[14:15]
	s_waitcnt lgkmcnt(3)
	v_pk_add_f32 v[66:67], v[66:67], v[4:5]
	v_pk_add_f32 v[68:69], v[68:69], v[2:3]
	ds_read_b128 v[2:5], v34 offset:31744
	v_pk_add_f32 v[12:13], v[12:13], v[24:25]
	v_pk_add_f32 v[10:11], v[10:11], v[22:23]
	v_pk_add_f32 v[12:13], v[12:13], v[46:47]
	v_pk_add_f32 v[10:11], v[10:11], v[44:45]
	v_pk_add_f32 v[12:13], v[12:13], v[50:51]
	v_pk_add_f32 v[10:11], v[10:11], v[48:49]
	s_waitcnt lgkmcnt(3)
	v_pk_add_f32 v[12:13], v[12:13], v[54:55]
	v_pk_add_f32 v[10:11], v[10:11], v[52:53]
	s_waitcnt lgkmcnt(1)
	v_pk_add_f32 v[12:13], v[12:13], v[58:59]
	v_pk_add_f32 v[10:11], v[10:11], v[56:57]
	s_waitcnt lgkmcnt(0)
	v_pk_add_f32 v[4:5], v[12:13], v[4:5]
	v_pk_add_f32 v[10:11], v[10:11], v[2:3]
	v_pk_add_f32 v[8:9], v[66:67], v[8:9]
	v_pk_add_f32 v[6:7], v[68:69], v[6:7]
	s_add_u32 s4, s4, s16
	s_addc_u32 s5, s5, 0
	s_waitcnt vmcnt(1)
	v_lshlrev_b32_e32 v2, 16, v40
	v_and_b32_e32 v3, 0xffff0000, v40
	v_lshlrev_b32_e32 v12, 16, v41
	v_and_b32_e32 v13, 0xffff0000, v41
	v_pk_add_f32 v[12:13], v[26:27], v[12:13]
	v_pk_add_f32 v[26:27], v[60:61], v[2:3]
	v_lshlrev_b32_e32 v14, 16, v42
	v_and_b32_e32 v15, 0xffff0000, v42
	v_lshlrev_b32_e32 v16, 16, v43
	v_and_b32_e32 v17, 0xffff0000, v43
	v_cvt_pk_bf16_f32 v3, v12, v13
	v_mul_f32_e32 v20, v27, v27
	v_mul_f32_e32 v13, v13, v13
	v_pk_add_f32 v[16:17], v[62:63], v[16:17]
	v_pk_add_f32 v[14:15], v[64:65], v[14:15]
	v_fmac_f32_e32 v20, v26, v26
	v_fmac_f32_e32 v13, v12, v12
	v_add_f32_e32 v12, v20, v13
	v_mul_f32_e32 v13, v15, v15
	v_mul_f32_e32 v20, v17, v17
	s_waitcnt vmcnt(0)
	v_lshlrev_b32_e32 v22, 16, v36
	v_and_b32_e32 v23, 0xffff0000, v36
	v_lshlrev_b32_e32 v24, 16, v37
	v_and_b32_e32 v25, 0xffff0000, v37
	v_fmac_f32_e32 v13, v14, v14
	v_fmac_f32_e32 v20, v16, v16
	v_lshlrev_b32_e32 v36, 16, v38
	v_and_b32_e32 v37, 0xffff0000, v38
	v_lshlrev_b32_e32 v38, 16, v39
	v_and_b32_e32 v39, 0xffff0000, v39
	v_add_f32_e32 v13, v13, v20
	v_pk_add_f32 v[8:9], v[8:9], v[24:25]
	v_pk_add_f32 v[6:7], v[6:7], v[22:23]
	v_add_f32_e32 v20, v12, v13
	v_pk_add_f32 v[12:13], v[4:5], v[38:39]
	v_mul_f32_e32 v4, v7, v7
	v_mul_f32_e32 v5, v9, v9
	v_pk_add_f32 v[10:11], v[10:11], v[36:37]
	v_fmac_f32_e32 v4, v6, v6
	v_fmac_f32_e32 v5, v8, v8
	v_add_f32_e32 v4, v4, v5
	v_mul_f32_e32 v5, v11, v11
	v_mul_f32_e32 v22, v13, v13
	v_fmac_f32_e32 v5, v10, v10
	v_fmac_f32_e32 v22, v12, v12
	v_add_f32_e32 v5, v5, v22
	v_add_f32_e32 v4, v4, v5
	v_and_b32_e32 v5, 64, v35
	v_add_f32_e32 v20, v20, v4
	v_xor_b32_e32 v4, 16, v35
	v_add_u32_e32 v22, 64, v5
	v_cmp_lt_i32_e32 vcc, v4, v22
	v_lshl_add_u64 v[40:41], s[4:5], 0, v[18:19]
	v_cvt_pk_bf16_f32 v2, v26, v27
	v_cndmask_b32_e32 v4, v35, v4, vcc
	v_lshlrev_b32_e32 v4, 2, v4
	ds_bpermute_b32 v23, v4, v20
	v_cvt_pk_bf16_f32 v4, v14, v15
	v_cvt_pk_bf16_f32 v5, v16, v17
	global_store_dwordx4 v[40:41], v[2:5], off sc1
	s_nop 1
	v_xor_b32_e32 v3, 32, v35
	v_cmp_lt_i32_e32 vcc, v3, v22
	s_waitcnt lgkmcnt(0)
	v_add_f32_e32 v2, v20, v23
	v_cvt_pk_bf16_f32 v4, v6, v7
	v_cndmask_b32_e32 v3, v35, v3, vcc
	v_lshlrev_b32_e32 v3, 2, v3
	ds_bpermute_b32 v3, v3, v2
	v_cvt_pk_bf16_f32 v5, v8, v9
	v_cvt_pk_bf16_f32 v6, v10, v11
	v_cvt_pk_bf16_f32 v7, v12, v13
	global_store_dwordx4 v[40:41], v[4:7], off offset:1024 sc1
	s_and_saveexec_b64 s[4:5], s[6:7]
	s_cbranch_execz .LBB0_897
	v_or_b32_e32 v20, s12, v160
	v_lshl_add_u64 v[4:5], v[20:21], 2, s[26:27]
	s_waitcnt lgkmcnt(0)
	v_add_f32_e32 v2, v2, v3
	global_atomic_add_f32 v[4:5], v2, off
	s_branch .LBB0_897

; __device__ __forceinline__ void st_bf8(bf16* p, const f32x4 a, const f32x4 b) { *(GAS v4u*)p = (v4u){pk2(a.x, a.y), pk2(a.z, a.w), pk2(b.x, b.y), pk2(b.z, b.w)}; }
; __device__ __forceinline__ float sq4(const f32x4 a) { return (a.x * a.x + a.y * a.y) + (a.z * a.z + a.w * a.w); }
; __device__ __forceinline__ void row_atomic(float* rs, int row, float s, int fq) { s += __shfl_xor(s, 16); s += __shfl_xor(s, 32); if (fq == 0) atomicAdd(rs + row, s); }
; __device__ __forceinline__ void nt_store4(float* p, f32x4 v) { __builtin_nontemporal_store(v, (f32x4*)p); }
;     template <int NR> __device__ __forceinline__ void rows(const int (&rowb)[NR], int fr, const float (&rstd)[NR], const f32x4 (&a)[NR][2][2], int pn, int wc, int fq) const {
;     ...
; #pragma unroll
;         for (int i = 0; i < NR; ++i) {
;             const float rr = rstd[i];
;             float ss = 0.f;
; #pragma unroll
;             for (int bj = 0; bj < 2; ++bj) {
;                 const size_t off = (size_t)(rowb[i] + fr) * DM + c0 + 32 * bj;
;                 const f32x4 u = bs[i][bj][0] + a[i][bj][0] * rr, v = bs[i][bj][1] + a[i][bj][1] * rr;
;                 if (Yout) { nt_store4(Yout + off, u); nt_store4(Yout + off + 4, v); }
;                 if (wr_xn) st_bf8((bf16*)((char*)XN + tile_ub(rowb[i], c0b + 32 * bj, DM) + ltb), u, v);
;                 ss += sq4(u) + sq4(v);
;             }
;             if (rs_out) row_atomic(rs_out, rowb[i] + fr, ss, fq);
;         }
.LBB0_965:
	s_waitcnt vmcnt(0) lgkmcnt(0)
	v_pk_fma_f32 v[126:127], v[126:127], v[210:211], v[186:187] op_sel_hi:[1,0,1]
	v_pk_fma_f32 v[128:129], v[128:129], v[210:211], v[188:189] op_sel_hi:[1,0,1]
	v_pk_fma_f32 v[186:187], v[124:125], v[210:211], v[192:193] op_sel_hi:[1,0,1]
	v_pk_fma_f32 v[124:125], v[122:123], v[210:211], v[190:191] op_sel_hi:[1,0,1]
	v_cvt_pk_bf16_f32 v122, v126, v127
	v_mul_f32_e32 v127, v127, v127
	v_fmac_f32_e32 v127, v126, v126
	v_mul_f32_e32 v126, v129, v129
	v_fmac_f32_e32 v126, v128, v128
	v_cvt_pk_bf16_f32 v123, v128, v129
	v_add_f32_e32 v126, v127, v126
	v_mul_f32_e32 v127, v125, v125
	v_mul_f32_e32 v128, v187, v187
	v_fmac_f32_e32 v127, v124, v124
	v_fmac_f32_e32 v128, v186, v186
	v_pk_fma_f32 v[120:121], v[120:121], v[210:211], v[180:181] op_sel_hi:[1,0,1]
	v_pk_fma_f32 v[118:119], v[118:119], v[210:211], v[178:179] op_sel_hi:[1,0,1]
	v_add_f32_e32 v127, v127, v128
	v_pk_fma_f32 v[128:129], v[114:115], v[210:211], v[182:183] op_sel_hi:[1,0,1]
	v_mul_f32_e32 v114, v119, v119
	v_mul_f32_e32 v115, v121, v121
	v_add_f32_e32 v190, v127, v126
	v_pk_fma_f32 v[126:127], v[116:117], v[210:211], v[184:185] op_sel_hi:[1,0,1]
	v_fmac_f32_e32 v114, v118, v118
	v_fmac_f32_e32 v115, v120, v120
	v_add_f32_e32 v114, v114, v115
	v_mul_f32_e32 v115, v129, v129
	v_mul_f32_e32 v116, v127, v127
	v_fmac_f32_e32 v115, v128, v128
	v_fmac_f32_e32 v116, v126, v126
	v_add_f32_e32 v115, v115, v116
	v_and_b32_e32 v116, 64, v218
	v_add_f32_e32 v114, v115, v114
	v_xor_b32_e32 v115, 16, v218
	v_add_u32_e32 v117, 64, v116
	v_cmp_lt_i32_e32 vcc, v115, v117
	v_add_f32_e32 v114, v114, v190
	s_add_u32 s4, s50, s4
	v_cndmask_b32_e32 v115, v218, v115, vcc
	v_lshlrev_b32_e32 v178, 2, v115
	ds_bpermute_b32 v115, v178, v114
	s_addc_u32 s5, s51, s5
	s_add_u32 s4, s4, s78
	s_addc_u32 s5, s5, s79
	s_add_u32 s4, s4, s54
	s_waitcnt lgkmcnt(0)
	v_add_f32_e32 v114, v114, v115
	v_xor_b32_e32 v115, 32, v218
	v_cmp_lt_i32_e32 vcc, v115, v117
	s_addc_u32 s5, s5, s82
	s_add_u32 s4, s4, s34
	v_cndmask_b32_e32 v115, v218, v115, vcc
	v_lshlrev_b32_e32 v179, 2, v115
	ds_bpermute_b32 v115, v179, v114
	s_addc_u32 s5, s5, s35
	v_cmp_eq_u32_e64 s[6:7], 0, v203
	v_lshl_add_u64 v[188:189], s[4:5], 0, v[196:197]
	v_cvt_pk_bf16_f32 v124, v124, v125
	v_cvt_pk_bf16_f32 v125, v186, v187
	v_cvt_pk_bf16_f32 v116, v118, v119
	v_cvt_pk_bf16_f32 v117, v120, v121
	v_cvt_pk_bf16_f32 v118, v128, v129
	v_cvt_pk_bf16_f32 v119, v126, v127
	global_store_dwordx4 v[188:189], v[122:125], off sc1
	global_store_dwordx4 v[188:189], v[116:119], off offset:1024 sc1
	s_and_saveexec_b64 s[4:5], s[6:7]
	s_cbranch_execz .LBB0_967
	v_ashrrev_i32_e32 v213, 31, v212
	s_waitcnt lgkmcnt(0)
	v_add_f32_e32 v116, v114, v115
	v_lshl_add_u64 v[114:115], v[212:213], 2, s[10:11]
	global_atomic_add_f32 v[114:115], v116, off
.LBB0_967:
	s_or_b64 exec, exec, s[4:5]
	v_mov_b32_e32 v114, v211
	s_waitcnt lgkmcnt(0)
	v_pk_fma_f32 v[110:111], v[110:111], v[114:115], v[170:171] op_sel_hi:[1,0,1]
	v_pk_fma_f32 v[112:113], v[112:113], v[114:115], v[172:173] op_sel_hi:[1,0,1]
	v_pk_fma_f32 v[116:117], v[108:109], v[114:115], v[176:177] op_sel_hi:[1,0,1]
	v_pk_fma_f32 v[108:109], v[106:107], v[114:115], v[174:175] op_sel_hi:[1,0,1]
	v_cvt_pk_bf16_f32 v106, v110, v111
	v_mul_f32_e32 v111, v111, v111
	v_fmac_f32_e32 v111, v110, v110
	v_mul_f32_e32 v110, v113, v113
	v_fmac_f32_e32 v110, v112, v112
	v_cvt_pk_bf16_f32 v107, v112, v113
	v_add_f32_e32 v110, v111, v110
	v_mul_f32_e32 v111, v109, v109
	v_mul_f32_e32 v112, v117, v117
	v_fmac_f32_e32 v111, v108, v108
	v_fmac_f32_e32 v112, v116, v116
	v_add_f32_e32 v111, v111, v112
	v_add_f32_e32 v115, v111, v110
	v_pk_fma_f32 v[104:105], v[104:105], v[114:115], v[164:165] op_sel_hi:[1,0,1]
	v_pk_fma_f32 v[102:103], v[102:103], v[114:115], v[162:163] op_sel_hi:[1,0,1]
	v_pk_fma_f32 v[112:113], v[98:99], v[114:115], v[166:167] op_sel_hi:[1,0,1]
	v_mul_f32_e32 v98, v103, v103
	v_mul_f32_e32 v99, v105, v105
	v_pk_fma_f32 v[110:111], v[100:101], v[114:115], v[168:169] op_sel_hi:[1,0,1]
	v_fmac_f32_e32 v98, v102, v102
	v_fmac_f32_e32 v99, v104, v104
	v_add_f32_e32 v98, v98, v99
	v_mul_f32_e32 v99, v113, v113
	v_mul_f32_e32 v100, v111, v111
	v_fmac_f32_e32 v99, v112, v112
	v_fmac_f32_e32 v100, v110, v110
	v_add_f32_e32 v99, v99, v100
	v_add_f32_e32 v98, v99, v98
	s_ashr_i32 s4, s71, 8
	v_add_f32_e32 v98, v98, v115
	s_ashr_i32 s5, s4, 31
	s_lshl_b32 s34, s71, 7
	ds_bpermute_b32 v99, v178, v98
	s_lshl_b64 s[4:5], s[4:5], 19
	s_and_b32 s35, s34, 0x4000
	s_and_b32 s34, s34, 0x2800
	s_add_u32 s4, s50, s4
	s_addc_u32 s5, s51, s5
	s_add_u32 s4, s4, s78
	s_addc_u32 s5, s5, s79
	s_waitcnt lgkmcnt(0)
	v_add_f32_e32 v98, v98, v99
	s_add_u32 s4, s4, s35
	ds_bpermute_b32 v99, v179, v98
	s_addc_u32 s5, s5, 0
	s_add_u32 s4, s4, s34
	s_addc_u32 s5, s5, 0
	v_lshl_add_u64 v[118:119], s[4:5], 0, v[196:197]
	v_cvt_pk_bf16_f32 v108, v108, v109
	v_cvt_pk_bf16_f32 v109, v116, v117
	v_cvt_pk_bf16_f32 v100, v102, v103
	v_cvt_pk_bf16_f32 v101, v104, v105
	v_cvt_pk_bf16_f32 v102, v112, v113
	v_cvt_pk_bf16_f32 v103, v110, v111
	global_store_dwordx4 v[118:119], v[106:109], off sc1
	global_store_dwordx4 v[118:119], v[100:103], off offset:1024 sc1
	s_and_saveexec_b64 s[4:5], s[6:7]
	s_cbranch_execz .LBB0_969
	v_ashrrev_i32_e32 v209, 31, v208
	s_waitcnt lgkmcnt(0)
	v_add_f32_e32 v100, v98, v99
	v_lshl_add_u64 v[98:99], v[208:209], 2, s[10:11]
	global_atomic_add_f32 v[98:99], v100, off
; __device__ __forceinline__ void st_bf8(bf16* p, const f32x4 a, const f32x4 b) { *(GAS v4u*)p = (v4u){pk2(a.x, a.y), pk2(a.z, a.w), pk2(b.x, b.y), pk2(b.z, b.w)}; }
; __device__ __forceinline__ float sq4(const f32x4 a) { return (a.x * a.x + a.y * a.y) + (a.z * a.z + a.w * a.w); }
; __device__ __forceinline__ void row_atomic(float* rs, int row, float s, int fq) { s += __shfl_xor(s, 16); s += __shfl_xor(s, 32); if (fq == 0) atomicAdd(rs + row, s); }
; __device__ __forceinline__ void nt_store4(float* p, f32x4 v) { __builtin_nontemporal_store(v, (f32x4*)p); }
;     template <int NR> __device__ __forceinline__ void rows(const int (&rowb)[NR], int fr, const float (&rstd)[NR], const f32x4 (&a)[NR][2][2], int pn, int wc, int fq) const {
;     ...
; #pragma unroll
;         for (int i = 0; i < NR; ++i) {
;             const float rr = rstd[i];
;             float ss = 0.f;
; #pragma unroll
;             for (int bj = 0; bj < 2; ++bj) {
;                 const size_t off = (size_t)(rowb[i] + fr) * DM + c0 + 32 * bj;
;                 const f32x4 u = bs[i][bj][0] + a[i][bj][0] * rr, v = bs[i][bj][1] + a[i][bj][1] * rr;
;                 if (Yout) { nt_store4(Yout + off, u); nt_store4(Yout + off + 4, v); }
;                 if (wr_xn) st_bf8((bf16*)((char*)XN + tile_ub(rowb[i], c0b + 32 * bj, DM) + ltb), u, v);
;                 ss += sq4(u) + sq4(v);
;             }
;             if (rs_out) row_atomic(rs_out, rowb[i] + fr, ss, fq);
;         }
.LBB0_969:
	s_or_b64 exec, exec, s[4:5]
	v_pk_fma_f32 v[94:95], v[94:95], v[204:205], v[154:155] op_sel_hi:[1,0,1]
	v_pk_fma_f32 v[96:97], v[96:97], v[204:205], v[156:157] op_sel_hi:[1,0,1]
	s_waitcnt lgkmcnt(0)
	v_pk_fma_f32 v[98:99], v[92:93], v[204:205], v[160:161] op_sel_hi:[1,0,1]
	v_pk_fma_f32 v[92:93], v[90:91], v[204:205], v[158:159] op_sel_hi:[1,0,1]
	v_cvt_pk_bf16_f32 v90, v94, v95
	v_mul_f32_e32 v95, v95, v95
	v_fmac_f32_e32 v95, v94, v94
	v_mul_f32_e32 v94, v97, v97
	v_fmac_f32_e32 v94, v96, v96
	v_cvt_pk_bf16_f32 v91, v96, v97
	v_add_f32_e32 v94, v95, v94
	v_mul_f32_e32 v95, v93, v93
	v_mul_f32_e32 v96, v99, v99
	v_fmac_f32_e32 v95, v92, v92
	v_fmac_f32_e32 v96, v98, v98
	v_pk_fma_f32 v[88:89], v[88:89], v[204:205], v[148:149] op_sel_hi:[1,0,1]
	v_pk_fma_f32 v[86:87], v[86:87], v[204:205], v[146:147] op_sel_hi:[1,0,1]
	v_add_f32_e32 v95, v95, v96
	v_pk_fma_f32 v[96:97], v[82:83], v[204:205], v[150:151] op_sel_hi:[1,0,1]
	v_mul_f32_e32 v82, v87, v87
	v_mul_f32_e32 v83, v89, v89
	v_add_f32_e32 v102, v94, v95
	v_pk_fma_f32 v[94:95], v[84:85], v[204:205], v[152:153] op_sel_hi:[1,0,1]
	v_fmac_f32_e32 v82, v86, v86
	v_fmac_f32_e32 v83, v88, v88
	v_add_f32_e32 v82, v82, v83
	v_mul_f32_e32 v83, v97, v97
	v_mul_f32_e32 v84, v95, v95
	v_fmac_f32_e32 v83, v96, v96
	v_fmac_f32_e32 v84, v94, v94
	v_add_f32_e32 v83, v83, v84
	v_add_f32_e32 v82, v82, v83
	s_ashr_i32 s4, s69, 8
	v_add_f32_e32 v82, v102, v82
	s_ashr_i32 s5, s4, 31
	s_lshl_b32 s34, s69, 7
	ds_bpermute_b32 v83, v178, v82
	s_lshl_b64 s[4:5], s[4:5], 19
	s_and_b32 s35, s34, 0x4000
	s_and_b32 s34, s34, 0x3000
	s_add_u32 s4, s50, s4
	s_addc_u32 s5, s51, s5
	s_add_u32 s4, s4, s78
	s_addc_u32 s5, s5, s79
	s_waitcnt lgkmcnt(0)
	v_add_f32_e32 v82, v82, v83
	s_add_u32 s4, s4, s35
	ds_bpermute_b32 v83, v179, v82
	s_addc_u32 s5, s5, 0
	s_add_u32 s4, s4, s34
	s_addc_u32 s5, s5, 0
	v_lshl_add_u64 v[100:101], s[4:5], 0, v[196:197]
	v_cvt_pk_bf16_f32 v92, v92, v93
	v_cvt_pk_bf16_f32 v93, v98, v99
	v_cvt_pk_bf16_f32 v84, v86, v87
	v_cvt_pk_bf16_f32 v85, v88, v89
	v_cvt_pk_bf16_f32 v86, v96, v97
	v_cvt_pk_bf16_f32 v87, v94, v95
	global_store_dwordx4 v[100:101], v[90:93], off sc1
	global_store_dwordx4 v[100:101], v[84:87], off offset:1024 sc1
	s_and_saveexec_b64 s[4:5], s[6:7]
	s_cbranch_execz .LBB0_971
	v_ashrrev_i32_e32 v207, 31, v206
	s_waitcnt lgkmcnt(0)
	v_add_f32_e32 v84, v82, v83
	v_lshl_add_u64 v[82:83], v[206:207], 2, s[10:11]
	global_atomic_add_f32 v[82:83], v84, off
.LBB0_971:
	s_or_b64 exec, exec, s[4:5]
	v_mov_b32_e32 v82, v205
	s_waitcnt lgkmcnt(0)
	v_pk_fma_f32 v[78:79], v[78:79], v[82:83], v[138:139] op_sel_hi:[1,0,1]
	v_pk_fma_f32 v[80:81], v[80:81], v[82:83], v[140:141] op_sel_hi:[1,0,1]
	v_pk_fma_f32 v[84:85], v[76:77], v[82:83], v[144:145] op_sel_hi:[1,0,1]
	v_pk_fma_f32 v[76:77], v[74:75], v[82:83], v[142:143] op_sel_hi:[1,0,1]
	v_cvt_pk_bf16_f32 v74, v78, v79
	v_mul_f32_e32 v79, v79, v79
	v_fmac_f32_e32 v79, v78, v78
	v_mul_f32_e32 v78, v81, v81
	v_fmac_f32_e32 v78, v80, v80
	v_cvt_pk_bf16_f32 v75, v80, v81
	v_add_f32_e32 v78, v79, v78
	v_mul_f32_e32 v79, v77, v77
	v_mul_f32_e32 v80, v85, v85
	v_fmac_f32_e32 v79, v76, v76
	v_fmac_f32_e32 v80, v84, v84
	v_add_f32_e32 v79, v79, v80
	v_add_f32_e32 v83, v78, v79
	v_pk_fma_f32 v[72:73], v[72:73], v[82:83], v[132:133] op_sel_hi:[1,0,1]
	v_pk_fma_f32 v[70:71], v[70:71], v[82:83], v[130:131] op_sel_hi:[1,0,1]
	v_pk_fma_f32 v[80:81], v[66:67], v[82:83], v[134:135] op_sel_hi:[1,0,1]
	v_mul_f32_e32 v66, v71, v71
	v_mul_f32_e32 v67, v73, v73
	v_pk_fma_f32 v[78:79], v[68:69], v[82:83], v[136:137] op_sel_hi:[1,0,1]
	v_fmac_f32_e32 v66, v70, v70
	v_fmac_f32_e32 v67, v72, v72
	v_add_f32_e32 v66, v66, v67
	v_mul_f32_e32 v67, v81, v81
	v_mul_f32_e32 v68, v79, v79
	v_fmac_f32_e32 v67, v80, v80
	v_fmac_f32_e32 v68, v78, v78
	v_add_f32_e32 v67, v67, v68
	v_add_f32_e32 v66, v66, v67
	s_ashr_i32 s4, s47, 8
	v_add_f32_e32 v66, v83, v66
	s_ashr_i32 s5, s4, 31
	s_lshl_b32 s34, s47, 7
	ds_bpermute_b32 v67, v178, v66
	s_lshl_b64 s[4:5], s[4:5], 19
	s_and_b32 s35, s34, 0x4000
	s_and_b32 s34, s34, 0x3800
	s_add_u32 s4, s50, s4
	s_addc_u32 s5, s51, s5
	s_add_u32 s4, s4, s78
	s_addc_u32 s5, s5, s79
	s_waitcnt lgkmcnt(0)
	v_add_f32_e32 v66, v66, v67
	s_add_u32 s4, s4, s35
	ds_bpermute_b32 v67, v179, v66
	s_addc_u32 s5, s5, 0
	s_add_u32 s4, s4, s34
	s_addc_u32 s5, s5, 0
	v_lshl_add_u64 v[86:87], s[4:5], 0, v[196:197]
	v_cvt_pk_bf16_f32 v76, v76, v77
	v_cvt_pk_bf16_f32 v77, v84, v85
	v_cvt_pk_bf16_f32 v68, v70, v71
	v_cvt_pk_bf16_f32 v69, v72, v73
	v_cvt_pk_bf16_f32 v70, v80, v81
	v_cvt_pk_bf16_f32 v71, v78, v79
	global_store_dwordx4 v[86:87], v[74:77], off sc1
	global_store_dwordx4 v[86:87], v[68:71], off offset:1024 sc1
	s_and_saveexec_b64 s[4:5], s[6:7]
	s_cbranch_execz .LBB0_973
	v_ashrrev_i32_e32 v203, 31, v202
	s_waitcnt lgkmcnt(0)
	v_add_f32_e32 v68, v66, v67
	v_lshl_add_u64 v[66:67], v[202:203], 2, s[10:11]
	global_atomic_add_f32 v[66:67], v68, off

; __device__ __forceinline__ void st_bf8(bf16* p, const f32x4 a, const f32x4 b) { *(GAS v4u*)p = (v4u){pk2(a.x, a.y), pk2(a.z, a.w), pk2(b.x, b.y), pk2(b.z, b.w)}; }
; __device__ __forceinline__ float sq4(const f32x4 a) { return (a.x * a.x + a.y * a.y) + (a.z * a.z + a.w * a.w); }
; __device__ __forceinline__ void row_atomic(float* rs, int row, float s, int fq) { s += __shfl_xor(s, 16); s += __shfl_xor(s, 32); if (fq == 0) atomicAdd(rs + row, s); }
; __device__ __forceinline__ void nt_store4(float* p, f32x4 v) { __builtin_nontemporal_store(v, (f32x4*)p); }
;     template <int NR> __device__ __forceinline__ void rows(const int (&rowb)[NR], int fr, const float (&rstd)[NR], const f32x4 (&a)[NR][2][2], int pn, int wc, int fq) const {
;     ...
; #pragma unroll
;         for (int i = 0; i < NR; ++i) {
;             const float rr = rstd[i];
;             float ss = 0.f;
; #pragma unroll
;             for (int bj = 0; bj < 2; ++bj) {
;                 const size_t off = (size_t)(rowb[i] + fr) * DM + c0 + 32 * bj;
;                 const f32x4 u = bs[i][bj][0] + a[i][bj][0] * rr, v = bs[i][bj][1] + a[i][bj][1] * rr;
;                 if (Yout) { nt_store4(Yout + off, u); nt_store4(Yout + off + 4, v); }
;                 if (wr_xn) st_bf8((bf16*)((char*)XN + tile_ub(rowb[i], c0b + 32 * bj, DM) + ltb), u, v);
;                 ss += sq4(u) + sq4(v);
;             }
;             if (rs_out) row_atomic(rs_out, rowb[i] + fr, ss, fq);
;         }
.LBB0_976:
	s_waitcnt vmcnt(14) lgkmcnt(1)
	v_pk_fma_f32 v[62:63], v[62:63], v[138:139], v[122:123] op_sel_hi:[1,0,1]
	v_pk_fma_f32 v[64:65], v[64:65], v[138:139], v[124:125] op_sel_hi:[1,0,1]
	v_pk_fma_f32 v[122:123], v[60:61], v[138:139], v[128:129] op_sel_hi:[1,0,1]
	v_pk_fma_f32 v[60:61], v[58:59], v[138:139], v[126:127] op_sel_hi:[1,0,1]
	v_cvt_pk_bf16_f32 v58, v62, v63
	v_mul_f32_e32 v63, v63, v63
	v_fmac_f32_e32 v63, v62, v62
	v_mul_f32_e32 v62, v65, v65
	v_fmac_f32_e32 v62, v64, v64
	v_cvt_pk_bf16_f32 v59, v64, v65
	v_add_f32_e32 v62, v63, v62
	v_mul_f32_e32 v63, v61, v61
	v_mul_f32_e32 v64, v123, v123
	v_fmac_f32_e32 v63, v60, v60
	v_fmac_f32_e32 v64, v122, v122
	s_waitcnt vmcnt(12)
	v_pk_fma_f32 v[56:57], v[56:57], v[138:139], v[116:117] op_sel_hi:[1,0,1]
	v_pk_fma_f32 v[54:55], v[54:55], v[138:139], v[114:115] op_sel_hi:[1,0,1]
	v_add_f32_e32 v63, v63, v64
	v_pk_fma_f32 v[64:65], v[50:51], v[138:139], v[118:119] op_sel_hi:[1,0,1]
	v_mul_f32_e32 v50, v55, v55
	v_mul_f32_e32 v51, v57, v57
	v_add_f32_e32 v126, v63, v62
	v_pk_fma_f32 v[62:63], v[52:53], v[138:139], v[120:121] op_sel_hi:[1,0,1]
	v_fmac_f32_e32 v50, v54, v54
	v_fmac_f32_e32 v51, v56, v56
	v_add_f32_e32 v50, v50, v51
	v_mul_f32_e32 v51, v65, v65
	v_mul_f32_e32 v52, v63, v63
	v_fmac_f32_e32 v51, v64, v64
	v_fmac_f32_e32 v52, v62, v62
	v_add_f32_e32 v51, v51, v52
	v_add_f32_e32 v50, v51, v50
	v_add_f32_e32 v50, v50, v126
	ds_bpermute_b32 v51, v178, v50
	s_add_u32 s4, s50, s4
	s_addc_u32 s5, s51, s5
	s_add_u32 s4, s4, s78
	s_addc_u32 s5, s5, s79
	s_waitcnt lgkmcnt(0)
	v_add_f32_e32 v50, v50, v51
	s_add_u32 s4, s4, s54
	ds_bpermute_b32 v51, v179, v50
	s_addc_u32 s5, s5, s82
	s_add_u32 s4, s4, s8
	s_addc_u32 s5, s5, s9
	v_lshl_add_u64 v[124:125], s[4:5], 0, v[196:197]
	v_cvt_pk_bf16_f32 v60, v60, v61
	v_cvt_pk_bf16_f32 v61, v122, v123
	v_cvt_pk_bf16_f32 v52, v54, v55
	v_cvt_pk_bf16_f32 v53, v56, v57
	v_cvt_pk_bf16_f32 v54, v64, v65
	v_cvt_pk_bf16_f32 v55, v62, v63
	global_store_dwordx4 v[124:125], v[58:61], off sc1
	global_store_dwordx4 v[124:125], v[52:55], off offset:1024 sc1
	s_and_saveexec_b64 s[4:5], s[6:7]
	s_cbranch_execz .LBB0_978
	v_ashrrev_i32_e32 v141, 31, v140
	s_waitcnt lgkmcnt(0)
	v_add_f32_e32 v52, v50, v51
	v_lshl_add_u64 v[50:51], v[140:141], 2, s[10:11]
	global_atomic_add_f32 v[50:51], v52, off
.LBB0_978:
	s_or_b64 exec, exec, s[4:5]
	v_mov_b32_e32 v50, v139
	s_waitcnt vmcnt(12) lgkmcnt(0)
	v_pk_fma_f32 v[46:47], v[46:47], v[50:51], v[106:107] op_sel_hi:[1,0,1]
	v_pk_fma_f32 v[48:49], v[48:49], v[50:51], v[108:109] op_sel_hi:[1,0,1]
	v_pk_fma_f32 v[52:53], v[44:45], v[50:51], v[112:113] op_sel_hi:[1,0,1]
	v_pk_fma_f32 v[44:45], v[42:43], v[50:51], v[110:111] op_sel_hi:[1,0,1]
	v_cvt_pk_bf16_f32 v42, v46, v47
	v_mul_f32_e32 v47, v47, v47
	v_fmac_f32_e32 v47, v46, v46
	v_mul_f32_e32 v46, v49, v49
	v_fmac_f32_e32 v46, v48, v48
	v_cvt_pk_bf16_f32 v43, v48, v49
	v_add_f32_e32 v46, v47, v46
	v_mul_f32_e32 v47, v45, v45
	v_mul_f32_e32 v48, v53, v53
	v_fmac_f32_e32 v47, v44, v44
	v_fmac_f32_e32 v48, v52, v52
	v_add_f32_e32 v47, v47, v48
	v_add_f32_e32 v51, v47, v46
	s_waitcnt vmcnt(10)
	v_pk_fma_f32 v[40:41], v[40:41], v[50:51], v[100:101] op_sel_hi:[1,0,1]
	v_pk_fma_f32 v[38:39], v[38:39], v[50:51], v[98:99] op_sel_hi:[1,0,1]
	v_pk_fma_f32 v[48:49], v[34:35], v[50:51], v[102:103] op_sel_hi:[1,0,1]
	v_mul_f32_e32 v34, v39, v39
	v_mul_f32_e32 v35, v41, v41
	v_pk_fma_f32 v[46:47], v[36:37], v[50:51], v[104:105] op_sel_hi:[1,0,1]
	v_fmac_f32_e32 v34, v38, v38
	v_fmac_f32_e32 v35, v40, v40
	v_add_f32_e32 v34, v34, v35
	v_mul_f32_e32 v35, v49, v49
	v_mul_f32_e32 v36, v47, v47
	v_fmac_f32_e32 v35, v48, v48
	v_fmac_f32_e32 v36, v46, v46
	v_add_f32_e32 v35, v35, v36
	v_add_f32_e32 v34, v35, v34
	s_ashr_i32 s4, s69, 8
	v_add_f32_e32 v34, v34, v51
	s_ashr_i32 s5, s4, 31
	s_lshl_b32 s8, s69, 7
	ds_bpermute_b32 v35, v178, v34
	s_lshl_b64 s[4:5], s[4:5], 19
	s_and_b32 s9, s8, 0x4000
	s_and_b32 s8, s8, 0x2800
	s_add_u32 s4, s50, s4
	s_addc_u32 s5, s51, s5
	s_add_u32 s4, s4, s78
	s_addc_u32 s5, s5, s79
	s_waitcnt lgkmcnt(0)
	v_add_f32_e32 v34, v34, v35
	s_add_u32 s4, s4, s9
	ds_bpermute_b32 v35, v179, v34
	s_addc_u32 s5, s5, 0
	s_add_u32 s4, s4, s8
	s_addc_u32 s5, s5, 0
	v_lshl_add_u64 v[54:55], s[4:5], 0, v[196:197]
	v_cvt_pk_bf16_f32 v44, v44, v45
	v_cvt_pk_bf16_f32 v45, v52, v53
	v_cvt_pk_bf16_f32 v36, v38, v39
	v_cvt_pk_bf16_f32 v37, v40, v41
	v_cvt_pk_bf16_f32 v38, v48, v49
	v_cvt_pk_bf16_f32 v39, v46, v47
	global_store_dwordx4 v[54:55], v[42:45], off sc1
	global_store_dwordx4 v[54:55], v[36:39], off offset:1024 sc1
	s_and_saveexec_b64 s[4:5], s[6:7]
	s_cbranch_execz .LBB0_980
	v_ashrrev_i32_e32 v137, 31, v136
	s_waitcnt lgkmcnt(0)
	v_add_f32_e32 v36, v34, v35
	v_lshl_add_u64 v[34:35], v[136:137], 2, s[10:11]
	global_atomic_add_f32 v[34:35], v36, off
; __device__ __forceinline__ void st_bf8(bf16* p, const f32x4 a, const f32x4 b) { *(GAS v4u*)p = (v4u){pk2(a.x, a.y), pk2(a.z, a.w), pk2(b.x, b.y), pk2(b.z, b.w)}; }
; __device__ __forceinline__ float sq4(const f32x4 a) { return (a.x * a.x + a.y * a.y) + (a.z * a.z + a.w * a.w); }
; __device__ __forceinline__ void row_atomic(float* rs, int row, float s, int fq) { s += __shfl_xor(s, 16); s += __shfl_xor(s, 32); if (fq == 0) atomicAdd(rs + row, s); }
; __device__ __forceinline__ void nt_store4(float* p, f32x4 v) { __builtin_nontemporal_store(v, (f32x4*)p); }
;     template <int NR> __device__ __forceinline__ void rows(const int (&rowb)[NR], int fr, const float (&rstd)[NR], const f32x4 (&a)[NR][2][2], int pn, int wc, int fq) const {
;     ...
; #pragma unroll
;         for (int i = 0; i < NR; ++i) {
;             const float rr = rstd[i];
;             float ss = 0.f;
; #pragma unroll
;             for (int bj = 0; bj < 2; ++bj) {
;                 const size_t off = (size_t)(rowb[i] + fr) * DM + c0 + 32 * bj;
;                 const f32x4 u = bs[i][bj][0] + a[i][bj][0] * rr, v = bs[i][bj][1] + a[i][bj][1] * rr;
;                 if (Yout) { nt_store4(Yout + off, u); nt_store4(Yout + off + 4, v); }
;                 if (wr_xn) st_bf8((bf16*)((char*)XN + tile_ub(rowb[i], c0b + 32 * bj, DM) + ltb), u, v);
;                 ss += sq4(u) + sq4(v);
;             }
;             if (rs_out) row_atomic(rs_out, rowb[i] + fr, ss, fq);
;         }
.LBB0_980:
	s_or_b64 exec, exec, s[4:5]
	s_waitcnt vmcnt(10)
	v_pk_fma_f32 v[30:31], v[30:31], v[132:133], v[90:91] op_sel_hi:[1,0,1]
	v_pk_fma_f32 v[32:33], v[32:33], v[132:133], v[92:93] op_sel_hi:[1,0,1]
	s_waitcnt lgkmcnt(0)
	v_pk_fma_f32 v[34:35], v[28:29], v[132:133], v[96:97] op_sel_hi:[1,0,1]
	v_pk_fma_f32 v[28:29], v[26:27], v[132:133], v[94:95] op_sel_hi:[1,0,1]
	v_cvt_pk_bf16_f32 v26, v30, v31
	v_mul_f32_e32 v31, v31, v31
	v_fmac_f32_e32 v31, v30, v30
	v_mul_f32_e32 v30, v33, v33
	v_fmac_f32_e32 v30, v32, v32
	v_cvt_pk_bf16_f32 v27, v32, v33
	v_add_f32_e32 v30, v31, v30
	v_mul_f32_e32 v31, v29, v29
	v_mul_f32_e32 v32, v35, v35
	v_fmac_f32_e32 v31, v28, v28
	v_fmac_f32_e32 v32, v34, v34
	s_waitcnt vmcnt(8)
	v_pk_fma_f32 v[24:25], v[24:25], v[132:133], v[84:85] op_sel_hi:[1,0,1]
	v_pk_fma_f32 v[22:23], v[22:23], v[132:133], v[82:83] op_sel_hi:[1,0,1]
	v_add_f32_e32 v31, v31, v32
	v_pk_fma_f32 v[32:33], v[18:19], v[132:133], v[86:87] op_sel_hi:[1,0,1]
	v_mul_f32_e32 v18, v23, v23
	v_mul_f32_e32 v19, v25, v25
	v_add_f32_e32 v38, v30, v31
	v_pk_fma_f32 v[30:31], v[20:21], v[132:133], v[88:89] op_sel_hi:[1,0,1]
	v_fmac_f32_e32 v18, v22, v22
	v_fmac_f32_e32 v19, v24, v24
	v_add_f32_e32 v18, v18, v19
	v_mul_f32_e32 v19, v33, v33
	v_mul_f32_e32 v20, v31, v31
	v_fmac_f32_e32 v19, v32, v32
	v_fmac_f32_e32 v20, v30, v30
	v_add_f32_e32 v19, v19, v20
	v_add_f32_e32 v18, v18, v19
	s_ashr_i32 s4, s47, 8
	v_add_f32_e32 v18, v38, v18
	s_ashr_i32 s5, s4, 31
	s_lshl_b32 s8, s47, 7
	ds_bpermute_b32 v19, v178, v18
	s_lshl_b64 s[4:5], s[4:5], 19
	s_and_b32 s9, s8, 0x4000
	s_and_b32 s8, s8, 0x3000
	s_add_u32 s4, s50, s4
	s_addc_u32 s5, s51, s5
	s_add_u32 s4, s4, s78
	s_addc_u32 s5, s5, s79
	s_waitcnt lgkmcnt(0)
	v_add_f32_e32 v18, v18, v19
	s_add_u32 s4, s4, s9
	ds_bpermute_b32 v19, v179, v18
	s_addc_u32 s5, s5, 0
	s_add_u32 s4, s4, s8
	s_addc_u32 s5, s5, 0
	v_lshl_add_u64 v[36:37], s[4:5], 0, v[196:197]
	v_cvt_pk_bf16_f32 v28, v28, v29
	v_cvt_pk_bf16_f32 v29, v34, v35
	v_cvt_pk_bf16_f32 v20, v22, v23
	v_cvt_pk_bf16_f32 v21, v24, v25
	v_cvt_pk_bf16_f32 v22, v32, v33
	v_cvt_pk_bf16_f32 v23, v30, v31
	global_store_dwordx4 v[36:37], v[26:29], off sc1
	global_store_dwordx4 v[36:37], v[20:23], off offset:1024 sc1
	s_and_saveexec_b64 s[4:5], s[6:7]
	s_cbranch_execz .LBB0_982
	v_ashrrev_i32_e32 v135, 31, v134
	s_waitcnt lgkmcnt(0)
	v_add_f32_e32 v20, v18, v19
	v_lshl_add_u64 v[18:19], v[134:135], 2, s[10:11]
	global_atomic_add_f32 v[18:19], v20, off
.LBB0_982:
	s_or_b64 exec, exec, s[4:5]
	v_mov_b32_e32 v18, v133
	s_waitcnt vmcnt(8) lgkmcnt(0)
	v_pk_fma_f32 v[14:15], v[14:15], v[18:19], v[74:75] op_sel_hi:[1,0,1]
	v_pk_fma_f32 v[16:17], v[16:17], v[18:19], v[76:77] op_sel_hi:[1,0,1]
	v_pk_fma_f32 v[20:21], v[12:13], v[18:19], v[80:81] op_sel_hi:[1,0,1]
	v_pk_fma_f32 v[12:13], v[10:11], v[18:19], v[78:79] op_sel_hi:[1,0,1]
	v_cvt_pk_bf16_f32 v10, v14, v15
	v_mul_f32_e32 v15, v15, v15
	v_fmac_f32_e32 v15, v14, v14
	v_mul_f32_e32 v14, v17, v17
	v_fmac_f32_e32 v14, v16, v16
	v_cvt_pk_bf16_f32 v11, v16, v17
	v_add_f32_e32 v14, v15, v14
	v_mul_f32_e32 v15, v13, v13
	v_mul_f32_e32 v16, v21, v21
	v_fmac_f32_e32 v15, v12, v12
	v_fmac_f32_e32 v16, v20, v20
	v_add_f32_e32 v15, v15, v16
	v_add_f32_e32 v19, v14, v15
	s_waitcnt vmcnt(6)
	v_pk_fma_f32 v[8:9], v[8:9], v[18:19], v[68:69] op_sel_hi:[1,0,1]
	v_pk_fma_f32 v[6:7], v[6:7], v[18:19], v[66:67] op_sel_hi:[1,0,1]
	v_pk_fma_f32 v[16:17], v[2:3], v[18:19], v[70:71] op_sel_hi:[1,0,1]
	v_mul_f32_e32 v2, v7, v7
	v_mul_f32_e32 v3, v9, v9
	v_pk_fma_f32 v[14:15], v[4:5], v[18:19], v[72:73] op_sel_hi:[1,0,1]
	v_fmac_f32_e32 v2, v6, v6
	v_fmac_f32_e32 v3, v8, v8
	v_add_f32_e32 v2, v2, v3
	v_mul_f32_e32 v3, v17, v17
	v_mul_f32_e32 v4, v15, v15
	v_fmac_f32_e32 v3, v16, v16
	v_fmac_f32_e32 v4, v14, v14
	v_add_f32_e32 v3, v3, v4
	v_add_f32_e32 v2, v2, v3
	s_ashr_i32 s4, s46, 8
	v_add_f32_e32 v2, v19, v2
	s_ashr_i32 s5, s4, 31
	s_lshl_b32 s8, s46, 7
	ds_bpermute_b32 v3, v178, v2
	s_lshl_b64 s[4:5], s[4:5], 19
	s_and_b32 s9, s8, 0x4000
	s_and_b32 s8, s8, 0x3800
	s_add_u32 s4, s50, s4
	s_addc_u32 s5, s51, s5
	s_add_u32 s4, s4, s78
	s_addc_u32 s5, s5, s79
	s_waitcnt lgkmcnt(0)
	v_add_f32_e32 v2, v2, v3
	s_add_u32 s4, s4, s9
	ds_bpermute_b32 v3, v179, v2
	s_addc_u32 s5, s5, 0
	s_add_u32 s4, s4, s8
	s_addc_u32 s5, s5, 0
	v_lshl_add_u64 v[22:23], s[4:5], 0, v[196:197]
	v_cvt_pk_bf16_f32 v12, v12, v13
	v_cvt_pk_bf16_f32 v13, v20, v21
	v_cvt_pk_bf16_f32 v4, v6, v7
	v_cvt_pk_bf16_f32 v5, v8, v9
	v_cvt_pk_bf16_f32 v6, v16, v17
	v_cvt_pk_bf16_f32 v7, v14, v15
	global_store_dwordx4 v[22:23], v[10:13], off sc1
	global_store_dwordx4 v[22:23], v[4:7], off offset:1024 sc1
	s_and_saveexec_b64 s[4:5], s[6:7]
	s_cbranch_execz .LBB0_984
	v_ashrrev_i32_e32 v131, 31, v130
	s_waitcnt lgkmcnt(0)
	v_add_f32_e32 v4, v2, v3
	v_lshl_add_u64 v[2:3], v[130:131], 2, s[10:11]
	global_atomic_add_f32 v[2:3], v4, off

; #define GAS __attribute__((address_space(1)))
; #define WG_BAR() asm volatile("s_waitcnt lgkmcnt(0)\n\ts_barrier" ::: "memory")
; template <class RowEpi, int MTL>
; __device__ __forceinline__ void small_gemm_t(Frame& F, const bf16* A  , const bf16* Bt, int N, int K, const RowEpi& R, int i_lo, int i_hi) {
;     ...
;         const int ar0 = rb * 16 * MTL + fr, ak0 = w * kw + 8 * fq;
;         const int bp0 = pn * 256 + 32 * wc + fr, bk0 = w * kw + 8 * fq;
; #pragma unroll 4
;         for (int k = 0; k < kw; k += 32) {
;             bf16x8 a[MTL], b[2][2];
; #pragma unroll
;             for (int m = 0; m < MTL; ++m) a[m] = *(const GAS bf16x8*)(A + wt_off(ar0 + 16 * m, ak0 + k, K));
; #pragma unroll
;             for (int bj = 0; bj < 2; ++bj)
; #pragma unroll
;                 for (int n = 0; n < 2; ++n) b[bj][n] = *(const GAS bf16x8*)(Bt + wt_off(bp0 + 128 * bj + 16 * n, bk0 + k, K));
; #pragma unroll
;             for (int m = 0; m < MTL; ++m)
; #pragma unroll
;                 for (int bj = 0; bj < 2; ++bj)
; #pragma unroll
;                     for (int n = 0; n < 2; ++n) acc[m][bj][n] = __builtin_amdgcn_mfma_f32_16x16x32_bf16(b[bj][n], a[m], acc[m][bj][n], 0, 0, 0);
;         }
; #pragma unroll
;         for (int m = 0; m < MTL; ++m)
; #pragma unroll
;             for (int bj = 0; bj < 2; ++bj)
; #pragma unroll
;                 for (int n = 0; n < 2; ++n) part[(w * (4 * MTL) + m * 4 + bj * 2 + n) * 64 + lane] = acc[m][bj][n];
;         WG_BAR();
.LBB0_996:
	v_add_u32_e32 v35, s20, v29
	v_lshrrev_b32_e32 v20, 6, v35
	v_add_u32_e32 v38, 32, v35
	v_add_u32_e32 v62, 64, v35
	v_add_u32_e32 v35, 0x60, v35
	v_lshlrev_b64 v[42:43], 15, v[20:21]
	v_mov_b32_e32 v37, v21
	v_mov_b32_e32 v39, v21
	v_add_u32_e32 v40, s12, v20
	v_lshrrev_b32_e32 v36, 6, v38
	v_bfe_u32 v20, v38, 5, 1
	v_lshlrev_b32_e32 v45, 1, v38
	v_lshrrev_b32_e32 v38, 6, v35
	v_lshl_add_u64 v[42:43], s[18:19], 0, v[42:43]
	v_add_u32_e32 v44, s12, v36
	v_lshlrev_b64 v[36:37], 15, v[36:37]
	v_add_u32_e32 v46, s12, v38
	v_lshlrev_b64 v[38:39], 15, v[38:39]
	v_lshl_add_u64 v[48:49], v[42:43], 0, v[24:25]
	v_lshl_add_u64 v[60:61], s[18:19], 0, v[36:37]
	v_lshl_add_u64 v[72:73], s[18:19], 0, v[38:39]
	global_load_dwordx4 v[36:39], v[48:49], off offset:2048
	v_bfe_u32 v47, v35, 5, 1
	v_ashrrev_i32_e32 v41, 31, v40
	v_or_b32_e32 v50, s13, v20
	v_and_b32_e32 v51, 48, v45
	v_or_b32_e32 v52, s13, v47
	v_or_b32_e32 v53, s14, v47
	v_lshlrev_b64 v[40:41], 15, v[40:41]
	v_lshl_add_u64 v[42:43], v[42:43], 0, s[16:17]
	v_or_b32_e32 v20, s14, v20
	v_ashrrev_i32_e32 v45, 31, v44
	v_or_b32_e32 v63, v51, v30
	v_lshlrev_b32_e32 v54, 10, v50
	v_ashrrev_i32_e32 v47, 31, v46
	v_lshlrev_b32_e32 v70, 10, v52
	v_lshlrev_b32_e32 v82, 10, v53
	v_lshl_add_u64 v[40:41], v[22:23], 0, v[40:41]
	v_lshl_add_u64 v[50:51], v[42:43], 0, v[24:25]
	v_lshl_add_u64 v[52:53], v[42:43], 0, v[26:27]
	v_lshlrev_b32_e32 v64, 10, v20
	v_lshlrev_b64 v[56:57], 15, v[44:45]
	v_bitop3_b32 v20, v63, v54, v28 bitop3:0xde
	v_lshlrev_b64 v[58:59], 15, v[46:47]
	global_load_dwordx4 v[40:43], v[40:41], off
	s_nop 0
	global_load_dwordx4 v[44:47], v[48:49], off
	s_nop 0
	global_load_dwordx4 v[48:51], v[50:51], off
	s_nop 0
	global_load_dwordx4 v[52:55], v[52:53], off
	v_lshl_add_u64 v[56:57], s[4:5], 0, v[56:57]
	v_lshl_add_u64 v[56:57], v[56:57], 0, v[20:21]
	v_bitop3_b32 v20, v63, v64, v28 bitop3:0xde
	v_mov_b32_e32 v69, v21
	v_lshl_add_u64 v[74:75], v[60:61], 0, s[16:17]
	v_lshl_add_u64 v[64:65], v[60:61], 0, v[20:21]
	v_or_b32_e32 v68, 0x800, v20
	v_lshl_add_u64 v[78:79], s[4:5], 0, v[58:59]
	global_load_dwordx4 v[56:59], v[56:57], off
	v_lshl_add_u64 v[66:67], v[74:75], 0, v[20:21]
	v_lshrrev_b32_e32 v20, 6, v62
	global_load_dwordx4 v[60:63], v[64:65], off offset:2048
	v_lshl_add_u64 v[68:69], v[74:75], 0, v[68:69]
	v_add_u32_e32 v74, s12, v20
	v_lshlrev_b64 v[80:81], 15, v[20:21]
	v_ashrrev_i32_e32 v75, 31, v74
	v_lshlrev_b32_e32 v35, 1, v35
	v_and_b32_e32 v35, 48, v35
	v_or_b32_e32 v35, v35, v30
	v_bitop3_b32 v20, v35, v70, v28 bitop3:0xde
	v_mov_b32_e32 v71, v21
	v_lshl_add_u64 v[76:77], v[72:73], 0, s[16:17]
	s_add_i32 s21, s20, 0x80
	s_addk_i32 s20, 0x60
	s_cmpk_lt_u32 s20, 0x1e0
	s_mov_b32 s20, s21
	s_waitcnt vmcnt(4)
	v_mfma_f32_16x16x32_bf16 v[2:5], v[44:47], v[40:43], v[2:5]
	v_mfma_f32_16x16x32_bf16 v[6:9], v[36:39], v[40:43], v[6:9]
	global_load_dwordx4 v[36:39], v[64:65], off
	s_nop 0
	global_load_dwordx4 v[64:67], v[66:67], off
	s_nop 0
	global_load_dwordx4 v[44:47], v[68:69], off
	s_waitcnt vmcnt(5)
	v_mfma_f32_16x16x32_bf16 v[14:17], v[52:55], v[40:43], v[14:17]
	v_lshl_add_u64 v[52:53], v[78:79], 0, v[20:21]
	v_bitop3_b32 v20, v35, v82, v28 bitop3:0xde
	v_or_b32_e32 v70, 0x800, v20
	v_mfma_f32_16x16x32_bf16 v[10:13], v[48:51], v[40:43], v[10:13]
	v_lshl_add_u64 v[40:41], s[18:19], 0, v[80:81]
	v_lshlrev_b64 v[42:43], 15, v[74:75]
	v_lshl_add_u64 v[54:55], v[40:41], 0, s[16:17]
	s_waitcnt vmcnt(3)
	v_mfma_f32_16x16x32_bf16 v[6:9], v[60:63], v[56:59], v[6:9]
	v_lshl_add_u64 v[48:49], v[40:41], 0, v[24:25]
	v_lshl_add_u64 v[40:41], v[22:23], 0, v[42:43]
	v_lshl_add_u64 v[60:61], v[54:55], 0, v[24:25]
	global_load_dwordx4 v[40:43], v[40:41], off
	s_waitcnt vmcnt(3)
	v_mfma_f32_16x16x32_bf16 v[2:5], v[36:39], v[56:59], v[2:5]
	global_load_dwordx4 v[36:39], v[48:49], off offset:2048
	s_waitcnt vmcnt(2)
	v_mfma_f32_16x16x32_bf16 v[14:17], v[44:47], v[56:59], v[14:17]
	global_load_dwordx4 v[44:47], v[60:61], off
	s_nop 0
	global_load_dwordx4 v[48:51], v[48:49], off
	v_mfma_f32_16x16x32_bf16 v[10:13], v[64:67], v[56:59], v[10:13]
	v_lshl_add_u64 v[56:57], v[72:73], 0, v[20:21]
	v_lshl_add_u64 v[58:59], v[76:77], 0, v[20:21]
	s_waitcnt vmcnt(2)
	v_mfma_f32_16x16x32_bf16 v[6:9], v[36:39], v[40:43], v[6:9]
	global_load_dwordx4 v[36:39], v[56:57], off offset:2048
	s_waitcnt vmcnt(1)
	v_mfma_f32_16x16x32_bf16 v[2:5], v[48:51], v[40:43], v[2:5]
	v_lshl_add_u64 v[48:49], v[54:55], 0, v[26:27]
	v_mfma_f32_16x16x32_bf16 v[10:13], v[44:47], v[40:43], v[10:13]
	global_load_dwordx4 v[44:47], v[48:49], off
	s_nop 0
	global_load_dwordx4 v[48:51], v[52:53], off
	s_waitcnt vmcnt(1)
	v_mfma_f32_16x16x32_bf16 v[14:17], v[44:47], v[40:43], v[14:17]
	global_load_dwordx4 v[40:43], v[56:57], off
	v_lshl_add_u64 v[44:45], v[76:77], 0, v[70:71]
	s_waitcnt vmcnt(1)
	v_mfma_f32_16x16x32_bf16 v[6:9], v[36:39], v[48:51], v[6:9]
	global_load_dwordx4 v[36:39], v[58:59], off
	s_waitcnt vmcnt(1)
	v_mfma_f32_16x16x32_bf16 v[2:5], v[40:43], v[48:51], v[2:5]
	global_load_dwordx4 v[40:43], v[44:45], off
	s_waitcnt vmcnt(1)
	v_mfma_f32_16x16x32_bf16 v[10:13], v[36:39], v[48:51], v[10:13]
	s_waitcnt vmcnt(0)
	v_mfma_f32_16x16x32_bf16 v[14:17], v[40:43], v[48:51], v[14:17]
	s_cbranch_scc1 .LBB0_996
	s_nop 1
	ds_write_b128 v33, v[2:5]
	ds_write_b128 v33, v[6:9] offset:1024
	s_nop 0
	ds_write_b128 v33, v[10:13] offset:2048
	s_nop 0
	ds_write_b128 v33, v[14:17] offset:3072
	s_waitcnt lgkmcnt(0)
	s_barrier
	s_andn2_b64 vcc, exec, s[8:9]
	s_cbranch_vccnz .LBB0_992
; #define GAS __attribute__((address_space(1)))
; __device__ __forceinline__ float bflo(unsigned w) { return __uint_as_float(w << 16); }
; __device__ __forceinline__ float bfhi(unsigned w) { return __uint_as_float(w & 0xffff0000u); }
;     template <int NR> __device__ __forceinline__ void rows(const int (&rowb)[NR], int fr, const float (&rstd)[NR], const f32x4 (&a)[NR][2][2], int pn, int wc, int fq) const {
;     ...
;                 for (int bj = 0; bj < 2; ++bj) w[i][bj] = *(const GAS v4u*)((const char*)XN + tile_ub(rowb[i], c0b + 32 * bj, DM) + ltb);
; #pragma unroll
;             for (int i = 0; i < NR; ++i)
; #pragma unroll
;                 for (int bj = 0; bj < 2; ++bj) { bs[i][bj][0] = (f32x4){bflo(w[i][bj].x), bfhi(w[i][bj].x), bflo(w[i][bj].y), bfhi(w[i][bj].y)}; bs[i][bj][1] = (f32x4){bflo(w[i][bj].z), bfhi(w[i][bj].z), bflo(w[i][bj].w), bfhi(w[i][bj].w)}; }
; template <class RowEpi, int MTL>
; __device__ __forceinline__ void small_gemm_t(Frame& F, const bf16* A  , const bf16* Bt, int N, int K, const RowEpi& R, int i_lo, int i_hi) {
;     ...
;         if (w < MTL) {
;             f32x4 s[2][2];
; #pragma unroll
;             for (int bj = 0; bj < 2; ++bj)
; #pragma unroll
;                 for (int n = 0; n < 2; ++n) { f32x4 t = (f32x4){0.f, 0.f, 0.f, 0.f};
; #pragma unroll
;                     for (int ww = 0; ww < 8; ++ww) t += part[(ww * (4 * MTL) + w * 4 + bj * 2 + n) * 64 + lane];
;                     s[bj][n] = t; }
	s_add_i32 s3, s0, s3
	s_ashr_i32 s4, s1, 6
	s_lshr_b32 s14, s3, 8
	s_ashr_i32 s5, s4, 31
	s_lshl_b32 s1, s3, 7
	s_lshl_b64 s[12:13], s[14:15], 19
	s_lshl_b64 s[4:5], s[4:5], 15
	s_and_b32 s14, s1, 0x4000
	s_add_u32 s12, s50, s12
	ds_read_b128 v[2:5], v33
	ds_read_b128 v[6:9], v33 offset:4096
	ds_read_b128 v[10:13], v33 offset:8192
	ds_read_b128 v[14:17], v33 offset:1024
	s_addc_u32 s13, s51, s13
	s_add_u32 s4, s12, s4
	s_waitcnt lgkmcnt(3)
	v_pk_add_f32 v[22:23], v[4:5], 0 op_sel_hi:[1,0]
	v_pk_add_f32 v[24:25], v[2:3], 0 op_sel_hi:[1,0]
	s_addc_u32 s5, s13, s5
	ds_read_b128 v[2:5], v33 offset:5120
	s_waitcnt lgkmcnt(3)
	v_pk_add_f32 v[26:27], v[22:23], v[8:9]
	v_pk_add_f32 v[36:37], v[24:25], v[6:7]
	ds_read_b128 v[6:9], v33 offset:12288
	ds_read_b128 v[22:25], v33 offset:9216
	s_add_u32 s4, s4, s14
	s_addc_u32 s5, s5, 0
	v_lshl_add_u64 v[40:41], s[4:5], 0, v[18:19]
	s_and_b32 s14, s1, 0x3800
	s_waitcnt lgkmcnt(4)
	v_pk_add_f32 v[26:27], v[26:27], v[12:13]
	v_pk_add_f32 v[36:37], v[36:37], v[10:11]
	v_lshl_add_u64 v[52:53], v[40:41], 0, s[14:15]
	ds_read_b128 v[10:13], v33 offset:13312
	s_waitcnt lgkmcnt(2)
	v_pk_add_f32 v[26:27], v[26:27], v[8:9]
	v_pk_add_f32 v[48:49], v[36:37], v[6:7]
	ds_read_b128 v[6:9], v33 offset:16384
	ds_read_b128 v[36:39], v33 offset:20480
	global_load_dwordx4 v[40:43], v[52:53], off
	ds_read_b128 v[44:47], v33 offset:17408
	v_pk_add_f32 v[16:17], v[16:17], 0 op_sel_hi:[1,0]
	s_waitcnt lgkmcnt(2)
	v_pk_add_f32 v[26:27], v[26:27], v[8:9]
	v_pk_add_f32 v[54:55], v[48:49], v[6:7]
	s_waitcnt lgkmcnt(1)
	v_pk_add_f32 v[26:27], v[26:27], v[38:39]
	v_pk_add_f32 v[60:61], v[54:55], v[36:37]
	global_load_dwordx4 v[36:39], v[52:53], off offset:1024
	ds_read_b128 v[6:9], v33 offset:21504
	ds_read_b128 v[48:51], v33 offset:24576
	v_pk_add_f32 v[14:15], v[14:15], 0 op_sel_hi:[1,0]
	ds_read_b128 v[52:55], v33 offset:28672
	ds_read_b128 v[56:59], v33 offset:25600
	v_pk_add_f32 v[4:5], v[16:17], v[4:5]
	v_pk_add_f32 v[2:3], v[14:15], v[2:3]
	v_pk_add_f32 v[4:5], v[4:5], v[24:25]
	v_pk_add_f32 v[2:3], v[2:3], v[22:23]
	v_pk_add_f32 v[4:5], v[4:5], v[12:13]
	v_pk_add_f32 v[2:3], v[2:3], v[10:11]
	s_waitcnt lgkmcnt(4)
	v_pk_add_f32 v[4:5], v[4:5], v[46:47]
	v_pk_add_f32 v[2:3], v[2:3], v[44:45]
	s_waitcnt lgkmcnt(2)
	v_pk_add_f32 v[26:27], v[26:27], v[50:51]
	v_pk_add_f32 v[60:61], v[60:61], v[48:49]
	ds_read_b128 v[48:51], v33 offset:29696
	v_pk_add_f32 v[4:5], v[4:5], v[8:9]
	v_pk_add_f32 v[2:3], v[2:3], v[6:7]
	s_waitcnt lgkmcnt(1)
	v_pk_add_f32 v[6:7], v[4:5], v[58:59]
	v_pk_add_f32 v[8:9], v[2:3], v[56:57]
	ds_read_b128 v[2:5], v33 offset:2048
	s_waitcnt lgkmcnt(1)
	v_pk_add_f32 v[62:63], v[6:7], v[50:51]
	v_pk_add_f32 v[64:65], v[8:9], v[48:49]
	ds_read_b128 v[6:9], v33 offset:6144
	ds_read_b128 v[10:13], v33 offset:3072
	v_pk_add_f32 v[26:27], v[26:27], v[54:55]
	s_waitcnt lgkmcnt(2)
	v_pk_add_f32 v[22:23], v[4:5], 0 op_sel_hi:[1,0]
	v_pk_add_f32 v[24:25], v[2:3], 0 op_sel_hi:[1,0]
	ds_read_b128 v[2:5], v33 offset:10240
	ds_read_b128 v[14:17], v33 offset:7168
	s_waitcnt lgkmcnt(3)
	v_pk_add_f32 v[44:45], v[22:23], v[8:9]
	v_pk_add_f32 v[46:47], v[24:25], v[6:7]
	ds_read_b128 v[6:9], v33 offset:14336
	ds_read_b128 v[22:25], v33 offset:11264
	s_waitcnt lgkmcnt(3)
	v_pk_add_f32 v[48:49], v[44:45], v[4:5]
	v_pk_add_f32 v[50:51], v[46:47], v[2:3]
	ds_read_b128 v[2:5], v33 offset:18432
	ds_read_b128 v[44:47], v33 offset:15360
	v_pk_add_f32 v[60:61], v[60:61], v[52:53]
	s_waitcnt lgkmcnt(3)
	v_pk_add_f32 v[52:53], v[48:49], v[8:9]
	v_pk_add_f32 v[54:55], v[50:51], v[6:7]
	ds_read_b128 v[6:9], v33 offset:22528
	ds_read_b128 v[48:51], v33 offset:19456
	s_waitcnt lgkmcnt(3)
	v_pk_add_f32 v[56:57], v[52:53], v[4:5]
	v_pk_add_f32 v[58:59], v[54:55], v[2:3]
	ds_read_b128 v[2:5], v33 offset:26624
	ds_read_b128 v[52:55], v33 offset:23552
	v_pk_add_f32 v[12:13], v[12:13], 0 op_sel_hi:[1,0]
	v_pk_add_f32 v[10:11], v[10:11], 0 op_sel_hi:[1,0]
	s_waitcnt lgkmcnt(3)
; __device__ __forceinline__ void st_bf8(bf16* p, const f32x4 a, const f32x4 b) { *(GAS v4u*)p = (v4u){pk2(a.x, a.y), pk2(a.z, a.w), pk2(b.x, b.y), pk2(b.z, b.w)}; }
; __device__ __forceinline__ float sq4(const f32x4 a) { return (a.x * a.x + a.y * a.y) + (a.z * a.z + a.w * a.w); }
; __device__ __forceinline__ void row_atomic(float* rs, int row, float s, int fq) { s += __shfl_xor(s, 16); s += __shfl_xor(s, 32); if (fq == 0) atomicAdd(rs + row, s); }
; __device__ __forceinline__ void nt_store4(float* p, f32x4 v) { __builtin_nontemporal_store(v, (f32x4*)p); }
;     template <int NR> __device__ __forceinline__ void rows(const int (&rowb)[NR], int fr, const float (&rstd)[NR], const f32x4 (&a)[NR][2][2], int pn, int wc, int fq) const {
;     ...
; #pragma unroll
;         for (int i = 0; i < NR; ++i) {
;             const float rr = rstd[i];
;             float ss = 0.f;
; #pragma unroll
;             for (int bj = 0; bj < 2; ++bj) {
;                 const size_t off = (size_t)(rowb[i] + fr) * DM + c0 + 32 * bj;
;                 const f32x4 u = bs[i][bj][0] + a[i][bj][0] * rr, v = bs[i][bj][1] + a[i][bj][1] * rr;
;                 if (Yout) { nt_store4(Yout + off, u); nt_store4(Yout + off + 4, v); }
;                 if (wr_xn) st_bf8((bf16*)((char*)XN + tile_ub(rowb[i], c0b + 32 * bj, DM) + ltb), u, v);
;                 ss += sq4(u) + sq4(v);
;             }
;             if (rs_out) row_atomic(rs_out, rowb[i] + fr, ss, fq);
;         }
	v_pk_add_f32 v[66:67], v[56:57], v[8:9]
	v_pk_add_f32 v[68:69], v[58:59], v[6:7]
	ds_read_b128 v[6:9], v33 offset:30720
	ds_read_b128 v[56:59], v33 offset:27648
	v_pk_add_f32 v[12:13], v[12:13], v[16:17]
	v_pk_add_f32 v[10:11], v[10:11], v[14:15]
	s_waitcnt lgkmcnt(3)
	v_pk_add_f32 v[66:67], v[66:67], v[4:5]
	v_pk_add_f32 v[68:69], v[68:69], v[2:3]
	ds_read_b128 v[2:5], v33 offset:31744
	v_pk_add_f32 v[12:13], v[12:13], v[24:25]
	v_pk_add_f32 v[10:11], v[10:11], v[22:23]
	v_pk_add_f32 v[12:13], v[12:13], v[46:47]
	v_pk_add_f32 v[10:11], v[10:11], v[44:45]
	v_pk_add_f32 v[12:13], v[12:13], v[50:51]
	v_pk_add_f32 v[10:11], v[10:11], v[48:49]
	s_waitcnt lgkmcnt(3)
	v_pk_add_f32 v[12:13], v[12:13], v[54:55]
	v_pk_add_f32 v[10:11], v[10:11], v[52:53]
	s_waitcnt lgkmcnt(1)
	v_pk_add_f32 v[12:13], v[12:13], v[58:59]
	v_pk_add_f32 v[10:11], v[10:11], v[56:57]
	s_waitcnt lgkmcnt(0)
	v_pk_add_f32 v[4:5], v[12:13], v[4:5]
	v_pk_add_f32 v[10:11], v[10:11], v[2:3]
	v_pk_add_f32 v[8:9], v[66:67], v[8:9]
	v_pk_add_f32 v[6:7], v[68:69], v[6:7]
	s_add_u32 s4, s4, s14
	s_addc_u32 s5, s5, 0
	s_waitcnt vmcnt(1)
	v_lshlrev_b32_e32 v2, 16, v40
	v_and_b32_e32 v3, 0xffff0000, v40
	v_lshlrev_b32_e32 v12, 16, v41
	v_and_b32_e32 v13, 0xffff0000, v41
	v_pk_add_f32 v[12:13], v[26:27], v[12:13]
	v_pk_add_f32 v[26:27], v[60:61], v[2:3]
	v_lshlrev_b32_e32 v14, 16, v42
	v_and_b32_e32 v15, 0xffff0000, v42
	v_lshlrev_b32_e32 v16, 16, v43
	v_and_b32_e32 v17, 0xffff0000, v43
	v_cvt_pk_bf16_f32 v3, v12, v13
	v_mul_f32_e32 v20, v27, v27
	v_mul_f32_e32 v13, v13, v13
	v_pk_add_f32 v[16:17], v[62:63], v[16:17]
	v_pk_add_f32 v[14:15], v[64:65], v[14:15]
	v_fmac_f32_e32 v20, v26, v26
	v_fmac_f32_e32 v13, v12, v12
	v_add_f32_e32 v12, v20, v13
	v_mul_f32_e32 v13, v15, v15
	v_mul_f32_e32 v20, v17, v17
	s_waitcnt vmcnt(0)
	v_lshlrev_b32_e32 v22, 16, v36
	v_and_b32_e32 v23, 0xffff0000, v36
	v_lshlrev_b32_e32 v24, 16, v37
	v_and_b32_e32 v25, 0xffff0000, v37
	v_fmac_f32_e32 v13, v14, v14
	v_fmac_f32_e32 v20, v16, v16
	v_lshlrev_b32_e32 v36, 16, v38
	v_and_b32_e32 v37, 0xffff0000, v38
	v_lshlrev_b32_e32 v38, 16, v39
	v_and_b32_e32 v39, 0xffff0000, v39
	v_add_f32_e32 v13, v13, v20
	v_pk_add_f32 v[8:9], v[8:9], v[24:25]
	v_pk_add_f32 v[6:7], v[6:7], v[22:23]
	v_add_f32_e32 v20, v12, v13
	v_pk_add_f32 v[12:13], v[4:5], v[38:39]
	v_mul_f32_e32 v4, v7, v7
	v_mul_f32_e32 v5, v9, v9
	v_pk_add_f32 v[10:11], v[10:11], v[36:37]
	v_fmac_f32_e32 v4, v6, v6
	v_fmac_f32_e32 v5, v8, v8
	v_add_f32_e32 v4, v4, v5
	v_mul_f32_e32 v5, v11, v11
	v_mul_f32_e32 v22, v13, v13
	v_fmac_f32_e32 v5, v10, v10
	v_fmac_f32_e32 v22, v12, v12
	v_add_f32_e32 v5, v5, v22
	v_add_f32_e32 v4, v4, v5
	v_and_b32_e32 v5, 64, v34
	v_add_f32_e32 v20, v20, v4
	v_xor_b32_e32 v4, 16, v34
	v_add_u32_e32 v22, 64, v5
	v_cmp_lt_i32_e32 vcc, v4, v22
	v_lshl_add_u64 v[40:41], s[4:5], 0, v[18:19]
	v_cvt_pk_bf16_f32 v2, v26, v27
	v_cndmask_b32_e32 v4, v34, v4, vcc
	v_lshlrev_b32_e32 v4, 2, v4
	ds_bpermute_b32 v23, v4, v20
	v_cvt_pk_bf16_f32 v4, v14, v15
	v_cvt_pk_bf16_f32 v5, v16, v17
	global_store_dwordx4 v[40:41], v[2:5], off sc1
	s_nop 1
	v_xor_b32_e32 v3, 32, v34
	v_cmp_lt_i32_e32 vcc, v3, v22
	s_waitcnt lgkmcnt(0)
	v_add_f32_e32 v2, v20, v23
	v_cvt_pk_bf16_f32 v4, v6, v7
	v_cndmask_b32_e32 v3, v34, v3, vcc
	v_lshlrev_b32_e32 v3, 2, v3
	ds_bpermute_b32 v3, v3, v2
	v_cvt_pk_bf16_f32 v5, v8, v9
	v_cvt_pk_bf16_f32 v6, v10, v11
	v_cvt_pk_bf16_f32 v7, v12, v13
	global_store_dwordx4 v[40:41], v[4:7], off offset:1024 sc1
	s_and_saveexec_b64 s[4:5], s[6:7]
	s_cbranch_execz .LBB0_991
	v_or_b32_e32 v20, s3, v160
	v_lshl_add_u64 v[4:5], v[20:21], 2, s[26:27]
	s_waitcnt lgkmcnt(0)
	v_add_f32_e32 v2, v2, v3
	global_atomic_add_f32 v[4:5], v2, off
	s_branch .LBB0_991

; __device__ __forceinline__ unsigned xb_add(unsigned* p, unsigned v) { return __hip_atomic_fetch_add(p, v, __ATOMIC_RELAXED, __HIP_MEMORY_SCOPE_AGENT); }
; __device__ __forceinline__ void xcd_barrier(const XcdBarrier& b) {
;     ...
;         if (old + 1u == (gen + 1u) * nloc) {
;             __builtin_amdgcn_fence(__ATOMIC_RELEASE, "agent");
;             asm volatile("s_waitcnt vmcnt(0)" ::: "memory");
;             const unsigned og = xb_add(&bar[XB_TOP], 1u);
.LBB0_1033:
	s_andn2_saveexec_b64 s[0:1], s[12:13]
	s_cbranch_execz .LBB0_1053
	s_mov_b64 s[12:13], exec
	s_nop 0
	s_nop 0
	s_waitcnt lgkmcnt(0)
	s_waitcnt vmcnt(0)
	v_mbcnt_lo_u32_b32 v3, s12, 0
	v_mbcnt_hi_u32_b32 v3, s13, v3
	v_cmp_eq_u32_e32 vcc, 0, v3
	s_and_saveexec_b64 s[14:15], vcc
	s_cbranch_execz .LBB0_1036
	s_bcnt1_i32_b64 s0, s[12:13]
	v_mov_b32_e32 v4, 0x7000
	v_mov_b32_e32 v5, s0
	global_atomic_add v4, v4, v5, s[30:31] offset:1024 sc0

; __device__ __forceinline__ void st_bf8(bf16* p, const f32x4 a, const f32x4 b) { *(GAS v4u*)p = (v4u){pk2(a.x, a.y), pk2(a.z, a.w), pk2(b.x, b.y), pk2(b.z, b.w)}; }
; __device__ __forceinline__ float sq4(const f32x4 a) { return (a.x * a.x + a.y * a.y) + (a.z * a.z + a.w * a.w); }
;     template <int NR> __device__ __forceinline__ void rows(const int (&rowb)[NR], int fr, const float (&rstd)[NR], const f32x4 (&a)[NR][2][2], int pn, int wc, int fq) const {
;     ...
;         const int dsh = 2 * g, W = 128 << dsh;
;         bf16* dbase = (bf16*)(qkv_base + (size_t)(which * 3 + g) * QKV_STRIDE) + h * 64 + 8 * fq;
;         float* kvp = out + (g == 0 ? O_KV128P : g == 1 ? O_KV512P : O_KV2048P) + (size_t)(which - 1) * 1024 + h * 64 + 8 * fq;
;         float* kvs = out + (g == 0 ? O_KV128S : g == 1 ? O_KV512S : O_KV2048S) + (size_t)(which - 1) * 1024 + h * 64 + 8 * fq;
; #pragma unroll
;         for (int i = 0; i < NR; ++i) {
;             const float rr = rstd[i];
;             f32x4 v[2][2] = {{a[i][0][0] * rr, a[i][0][1] * rr}, {a[i][1][0] * rr, a[i][1][1] * rr}};
;             if (which < 2) {
;                 float ss = sq4(v[0][0]) + sq4(v[0][1]) + sq4(v[1][0]) + sq4(v[1][1]);
;                 ss += __shfl_xor(ss, 16); ss += __shfl_xor(ss, 32);
;                 float sc = rsqrtf(ss * (1.f / 64.f) + EPS); if (which == 0) sc *= QSCALE;
; #pragma unroll
;                 for (int bj = 0; bj < 2; ++bj)
; #pragma unroll
;                     for (int n = 0; n < 2; ++n) v[bj][n] = v[bj][n] * wv[bj][n] * sc;
;             }
;             const int rw = rowb[i] + fr; int arow = rw, b, t = 0; const bool prompt = rw < MP;
;             if (prompt) { b = rw >> 12; t = rw & 4095; arow = (b << 12) + ((t & ((1 << dsh) - 1)) << (12 - dsh)) + (t >> dsh); } else { b = (rw - MP) >> 3; }
;             bf16* dst = dbase + (size_t)arow * DM;
;             st_bf8(dst, v[0][0], v[0][1]); st_bf8(dst + 32, v[1][0], v[1][1]);
;             if (which >= 1) {
;                 float* o = nullptr;
;                 if (prompt) { if (t >= SEQ - W) o = kvp + (size_t)(b * W + (t - (SEQ - W))) * 2048; }
;                 else o = kvs + (size_t)(rw - MP) * 2048;
;                 if (o) { nt_store4(o, v[0][0]); nt_store4(o + 4, v[0][1]); nt_store4(o + 32, v[1][0]); nt_store4(o + 36, v[1][1]); }
.LBB0_1070:
	s_mul_hi_i32 s5, s4, 0x2aaaaaab
	s_lshr_b32 s14, s5, 31
	s_ashr_i32 s5, s5, 1
	s_add_i32 s14, s5, s14
	s_ashr_i32 s5, s18, 4
	s_mul_hi_i32 s15, s5, 0x55555556
	s_lshr_b32 s16, s15, 31
	s_add_i32 s15, s15, s16
	s_mul_i32 s15, s15, 3
	s_add_i32 s36, s20, s19
	s_sub_i32 s19, s5, s15
	s_mul_i32 s5, s14, 3
	s_add_i32 s5, s5, s19
	s_lshl_b32 s37, s19, 1
	s_mul_hi_i32 s15, s5, 0x2100000
	s_mul_i32 s5, s5, 0x2100000
	s_add_u32 s16, s24, s5
	s_addc_u32 s15, s25, s15
	s_lshl_b32 s5, s18, 6
	s_and_b32 s5, s5, 0x3c0
	s_mul_i32 s17, s5, 0x8200
	s_add_u32 s16, s16, s17
	s_addc_u32 s17, s15, 0
	s_waitcnt vmcnt(1)
	v_lshlrev_b32_e32 v2, 1, v146
	v_mov_b32_e32 v3, v149
	s_waitcnt vmcnt(0)
	v_lshl_add_u64 v[6:7], s[16:17], 0, v[2:3]
	v_or_b32_e32 v2, s36, v147
	v_bitop3_b32 v4, s36, v165, v147 bitop3:0xc8
	s_sub_i32 s16, 12, s37
	s_and_b32 s15, s36, 0xfffff000
	v_lshlrev_b32_e32 v3, s16, v2
	v_lshrrev_b32_e32 v5, s37, v4
	v_and_b32_e32 v3, 0xfff, v3
	v_or_b32_e32 v5, s15, v5
	v_add_u32_e32 v3, v5, v3
	v_cmp_gt_i32_e32 vcc, s1, v2
	v_mov_b32_e32 v9, v149
	s_cmp_lt_i32 s4, 12
	v_cndmask_b32_e32 v8, v2, v3, vcc
	v_lshlrev_b64 v[8:9], 7, v[8:9]
	v_lshl_add_u64 v[10:11], v[6:7], 0, v[8:9]
	v_cvt_pk_bf16_f32 v6, v14, v15
	v_cvt_pk_bf16_f32 v7, v16, v17
	v_cvt_pk_bf16_f32 v8, v18, v19
	v_cvt_pk_bf16_f32 v9, v20, v21
	global_store_dwordx4 v[10:11], v[6:9], off sc1
	s_nop 1
	v_cvt_pk_bf16_f32 v6, v22, v23
	v_cvt_pk_bf16_f32 v7, v24, v25
	v_cvt_pk_bf16_f32 v8, v26, v27
	v_cvt_pk_bf16_f32 v9, v28, v29
	global_store_dwordx4 v[10:11], v[6:9], off offset:64 sc1
	s_cbranch_scc1 .LBB0_1060
	s_add_i32 s14, s14, -1
	s_ashr_i32 s15, s14, 31
	s_cmp_eq_u32 s19, 1
	s_cselect_b64 s[16:17], -1, 0
	s_and_b64 s[38:39], s[16:17], exec
	s_cselect_b32 s4, s22, 0x2ac0000
	s_cmp_eq_u32 s19, 0
	s_cselect_b64 s[18:19], -1, 0
	s_and_b64 s[38:39], s[18:19], exec
	s_cselect_b32 s4, 0x15c0000, s4
	s_lshl_b32 s4, s4, 2
	s_add_u32 s4, s28, s4
	s_addc_u32 s46, s29, 0
	s_lshl_b64 s[38:39], s[14:15], 12
	s_add_u32 s4, s4, s38
	s_addc_u32 s39, s46, s39
	s_lshl_b32 s38, s5, 2
	s_add_u32 s4, s4, s38
	s_addc_u32 s5, s39, 0
	v_add_u32_e32 v2, 0xffffc000, v2
	v_mov_b32_e32 v3, v149
	v_lshl_add_u64 v[6:7], s[4:5], 0, v[148:149]
	v_lshlrev_b64 v[2:3], 13, v[2:3]
	v_lshl_add_u64 v[2:3], v[6:7], 0, v[2:3]
	s_and_saveexec_b64 s[4:5], vcc
	s_cbranch_execz .LBB0_1073
	s_lshl_b64 s[14:15], s[14:15], 10
	s_lshl_b32 s39, 0xffffff80, s37
	s_and_b64 s[16:17], s[16:17], exec
	s_cselect_b32 s46, s23, 0x1ac0000
	s_and_b64 s[16:17], s[18:19], exec
	s_cselect_b32 s16, 0x14c0000, s46
	s_lshl_b32 s16, s16, 2
	s_add_u32 s16, s28, s16
	s_addc_u32 s17, s29, 0
	s_lshl_b64 s[14:15], s[14:15], 2
	s_add_u32 s14, s16, s14
	s_addc_u32 s15, s17, s15
	s_add_u32 s14, s14, s38
	s_addc_u32 s15, s15, 0
	v_lshl_add_u64 v[2:3], s[14:15], 0, v[148:149]
	s_lshr_b32 s14, s36, 12
	s_add_i32 s37, s37, 7
	s_lshl_b32 s14, s14, s37
	v_subrev_u32_e32 v5, s39, v4
	v_add_u32_e32 v5, s14, v5
	v_add_u32_e32 v6, 0xfffff000, v5
	v_ashrrev_i32_e32 v7, 31, v6
	s_add_i32 s15, s39, 0x1000
	v_lshlrev_b64 v[6:7], 13, v[6:7]
	v_lshl_add_u64 v[2:3], v[2:3], 0, v[6:7]
	v_cmp_le_i32_e32 vcc, s15, v4
	s_nop 1
	v_cndmask_b32_e32 v3, 0, v3, vcc
	v_cndmask_b32_e32 v2, 0, v2, vcc
.LBB0_1073:
	s_or_b64 exec, exec, s[4:5]
	v_cmp_ne_u64_e32 vcc, 0, v[2:3]
	s_and_saveexec_b64 s[4:5], vcc
	s_cbranch_execz .LBB0_1059
	global_store_dwordx4 v[2:3], v[14:17], off nt sc1
	global_store_dwordx4 v[2:3], v[18:21], off offset:16 nt sc1
	global_store_dwordx4 v[2:3], v[22:25], off offset:128 nt sc1
	global_store_dwordx4 v[2:3], v[26:29], off offset:144 nt sc1
	s_branch .LBB0_1059

; __device__ __forceinline__ unsigned lane_tb(int fr, int fq) { return (unsigned)((fr * 64 + fq * 16) ^ ((fr >> 3) << 5)); }
; __device__ __forceinline__ void st_bf8(bf16* p, const f32x4 a, const f32x4 b) { *(GAS v4u*)p = (v4u){pk2(a.x, a.y), pk2(a.z, a.w), pk2(b.x, b.y), pk2(b.z, b.w)}; }
;     template <int NR> __device__ __forceinline__ void rows(const int (&rowb)[NR], int fr, const float (&rstd)[NR], const f32x4 (&a)[NR][2][2], int pn, int wc, int fq) const {
; #pragma unroll
;         for (int i = 0; i < NR; ++i) {
;             const float rr = rstd[i];
; #pragma unroll
;             for (int bj = 0; bj < 2; ++bj) {
;                 f32x4 u = a[i][bj][0] * rr, v = a[i][bj][1] * rr;
; #pragma unroll
;                 for (int j = 0; j < 4; ++j) { const float p = fmaxf(u[j], 0.f), q = fmaxf(v[j], 0.f); u[j] = p * p; v[j] = q * q; }
;                 st_bf8((bf16*)((char*)H + tile_ub(rowb[i], (pn << 8) + 64 * wc + 32 * bj, FF) + lane_tb(fr, fq)), u, v);
;             }
;         }
;     }
.LBB0_1127:
	v_mov_b32_e32 v134, v0
	s_lshl_b32 s35, s68, 8
	v_and_b32_e32 v135, 15, v134
	s_lshl_b32 s4, s66, 8
	s_or_b32 s4, s4, s84
	v_lshlrev_b32_e32 v141, 6, v135
	v_lshlrev_b32_e32 v135, 2, v135
	s_add_i32 s34, s35, s83
	v_and_b32_e32 v134, 48, v134
	s_ashr_i32 s4, s4, 6
	v_and_b32_e32 v142, 32, v135
	v_add_u32_e32 v148, s88, v135
	s_ashr_i32 s70, s34, 8
	s_ashr_i32 s5, s4, 31
	v_bitop3_b32 v141, v141, v142, v134 bitop3:0x36
	ds_read2_b32 v[142:143], v148 offset1:16
	s_ashr_i32 s71, s70, 31
	s_lshl_b32 s57, s34, 7
	s_lshl_b64 s[4:5], s[4:5], 15
	s_add_i32 s47, s35, s85
	s_add_i32 s46, s35, s86
	s_add_i32 s35, s35, s87
	s_lshl_b64 s[70:71], s[70:71], 21
	s_and_b32 s59, s57, 0x4000
	s_and_b32 s57, s57, 0x2000
	s_add_u32 s66, s52, s70
	s_addc_u32 s68, s53, s71
	s_add_u32 s66, s66, s4
	s_waitcnt lgkmcnt(0)
	v_pk_mul_f32 v[122:123], v[122:123], v[142:143] op_sel_hi:[1,0]
	s_addc_u32 s68, s68, s5
	v_pk_mul_f32 v[128:129], v[128:129], v[142:143] op_sel_hi:[1,0]
	v_pk_mul_f32 v[126:127], v[126:127], v[142:143] op_sel_hi:[1,0]
	v_pk_mul_f32 v[124:125], v[124:125], v[142:143] op_sel_hi:[1,0]
	v_max_f32_e32 v122, 0, v122
	v_max_f32_e32 v123, 0, v123
	s_add_u32 s59, s66, s59
	v_max_f32_e32 v126, 0, v126
	v_max_f32_e32 v127, 0, v127
	v_pk_mul_f32 v[144:145], v[122:123], v[122:123]
	v_max_f32_e32 v122, 0, v128
	v_max_f32_e32 v124, 0, v124
	v_max_f32_e32 v123, 0, v129
	v_max_f32_e32 v125, 0, v125
	s_addc_u32 s66, s68, 0
	v_pk_mul_f32 v[126:127], v[126:127], v[126:127]
	v_pk_mul_f32 v[128:129], v[122:123], v[122:123]
	v_pk_mul_f32 v[146:147], v[124:125], v[124:125]
	s_add_u32 s70, s59, s57
	v_pk_mul_f32 v[114:115], v[114:115], v[142:143] op_sel_hi:[1,0]
	s_addc_u32 s71, s66, 0
	v_cvt_pk_bf16_f32 v122, v126, v127
	v_cvt_pk_bf16_f32 v123, v128, v129
	v_cvt_pk_bf16_f32 v124, v144, v145
	v_cvt_pk_bf16_f32 v125, v146, v147
	v_pk_mul_f32 v[120:121], v[120:121], v[142:143] op_sel_hi:[1,0]
	v_pk_mul_f32 v[118:119], v[118:119], v[142:143] op_sel_hi:[1,0]
	v_pk_mul_f32 v[116:117], v[116:117], v[142:143] op_sel_hi:[1,0]
	v_max_f32_e32 v114, 0, v114
	v_max_f32_e32 v115, 0, v115
	global_store_dwordx4 v141, v[122:125], s[70:71] sc1
	v_max_f32_e32 v118, 0, v118
	v_max_f32_e32 v119, 0, v119
	v_pk_mul_f32 v[122:123], v[114:115], v[114:115]
	v_max_f32_e32 v114, 0, v120
	v_max_f32_e32 v116, 0, v116
	v_max_f32_e32 v115, 0, v121
	v_max_f32_e32 v117, 0, v117
	v_pk_mul_f32 v[118:119], v[118:119], v[118:119]
	v_pk_mul_f32 v[120:121], v[114:115], v[114:115]
	v_pk_mul_f32 v[124:125], v[116:117], v[116:117]
	v_cvt_pk_bf16_f32 v114, v118, v119
	v_cvt_pk_bf16_f32 v115, v120, v121
	v_cvt_pk_bf16_f32 v116, v122, v123
	v_cvt_pk_bf16_f32 v117, v124, v125
	global_store_dwordx4 v141, v[114:117], s[70:71] offset:1024 sc1
	s_ashr_i32 s70, s47, 8
	s_ashr_i32 s71, s70, 31
	s_lshl_b32 s47, s47, 7
	s_lshl_b64 s[70:71], s[70:71], 21
	s_and_b32 s57, s47, 0x4000
	s_and_b32 s47, s47, 0x2800
	s_add_u32 s59, s52, s70
	s_addc_u32 s66, s53, s71
	v_mov_b32_e32 v114, v143
	s_add_u32 s59, s59, s4
	v_pk_mul_f32 v[106:107], v[106:107], v[114:115] op_sel_hi:[1,0]
	s_addc_u32 s66, s66, s5
	v_pk_mul_f32 v[112:113], v[112:113], v[114:115] op_sel_hi:[1,0]
	v_pk_mul_f32 v[110:111], v[110:111], v[114:115] op_sel_hi:[1,0]
	v_pk_mul_f32 v[108:109], v[108:109], v[114:115] op_sel_hi:[1,0]
	v_max_f32_e32 v106, 0, v106
	v_max_f32_e32 v107, 0, v107
	s_add_u32 s57, s59, s57
	v_max_f32_e32 v110, 0, v110
	v_max_f32_e32 v111, 0, v111
	v_pk_mul_f32 v[116:117], v[106:107], v[106:107]
	v_max_f32_e32 v106, 0, v112
	v_max_f32_e32 v108, 0, v108
	v_max_f32_e32 v107, 0, v113
	v_max_f32_e32 v109, 0, v109
	s_addc_u32 s59, s66, 0
	v_pk_mul_f32 v[110:111], v[110:111], v[110:111]
	v_pk_mul_f32 v[112:113], v[106:107], v[106:107]
	v_pk_mul_f32 v[118:119], v[108:109], v[108:109]
	s_add_u32 s70, s57, s47
	v_pk_mul_f32 v[98:99], v[98:99], v[114:115] op_sel_hi:[1,0]
	s_addc_u32 s71, s59, 0
	v_cvt_pk_bf16_f32 v106, v110, v111
	v_cvt_pk_bf16_f32 v107, v112, v113
	v_cvt_pk_bf16_f32 v108, v116, v117
	v_cvt_pk_bf16_f32 v109, v118, v119
	v_pk_mul_f32 v[104:105], v[104:105], v[114:115] op_sel_hi:[1,0]
	v_pk_mul_f32 v[102:103], v[102:103], v[114:115] op_sel_hi:[1,0]
	v_pk_mul_f32 v[100:101], v[100:101], v[114:115] op_sel_hi:[1,0]
	v_max_f32_e32 v98, 0, v98
	v_max_f32_e32 v99, 0, v99
	global_store_dwordx4 v141, v[106:109], s[70:71] sc1
	v_max_f32_e32 v102, 0, v102
	v_max_f32_e32 v103, 0, v103
	v_pk_mul_f32 v[106:107], v[98:99], v[98:99]
	v_max_f32_e32 v98, 0, v104
	v_max_f32_e32 v100, 0, v100
	v_max_f32_e32 v99, 0, v105
	v_max_f32_e32 v101, 0, v101
	v_pk_mul_f32 v[102:103], v[102:103], v[102:103]
	v_pk_mul_f32 v[104:105], v[98:99], v[98:99]
	v_pk_mul_f32 v[108:109], v[100:101], v[100:101]
	v_cvt_pk_bf16_f32 v98, v102, v103
	v_cvt_pk_bf16_f32 v99, v104, v105
	v_cvt_pk_bf16_f32 v100, v106, v107
	v_cvt_pk_bf16_f32 v101, v108, v109
	global_store_dwordx4 v141, v[98:101], s[70:71] offset:1024 sc1
	s_ashr_i32 s70, s46, 8
	ds_read2_b32 v[134:135], v148 offset0:32 offset1:48
	s_ashr_i32 s71, s70, 31
	s_lshl_b32 s46, s46, 7
	s_lshl_b64 s[70:71], s[70:71], 21
	s_and_b32 s47, s46, 0x4000
	s_and_b32 s46, s46, 0x3000
	s_add_u32 s57, s52, s70
	s_addc_u32 s59, s53, s71
	s_add_u32 s57, s57, s4
	s_waitcnt lgkmcnt(0)
; __device__ __forceinline__ unsigned lane_tb(int fr, int fq) { return (unsigned)((fr * 64 + fq * 16) ^ ((fr >> 3) << 5)); }
; __device__ __forceinline__ void st_bf8(bf16* p, const f32x4 a, const f32x4 b) { *(GAS v4u*)p = (v4u){pk2(a.x, a.y), pk2(a.z, a.w), pk2(b.x, b.y), pk2(b.z, b.w)}; }
;     template <int NR> __device__ __forceinline__ void rows(const int (&rowb)[NR], int fr, const float (&rstd)[NR], const f32x4 (&a)[NR][2][2], int pn, int wc, int fq) const {
; #pragma unroll
;         for (int i = 0; i < NR; ++i) {
;             const float rr = rstd[i];
; #pragma unroll
;             for (int bj = 0; bj < 2; ++bj) {
;                 f32x4 u = a[i][bj][0] * rr, v = a[i][bj][1] * rr;
; #pragma unroll
;                 for (int j = 0; j < 4; ++j) { const float p = fmaxf(u[j], 0.f), q = fmaxf(v[j], 0.f); u[j] = p * p; v[j] = q * q; }
;                 st_bf8((bf16*)((char*)H + tile_ub(rowb[i], (pn << 8) + 64 * wc + 32 * bj, FF) + lane_tb(fr, fq)), u, v);
;             }
;         }
;     }
	v_pk_mul_f32 v[90:91], v[90:91], v[134:135] op_sel_hi:[1,0]
	s_addc_u32 s59, s59, s5
	v_pk_mul_f32 v[96:97], v[96:97], v[134:135] op_sel_hi:[1,0]
	v_pk_mul_f32 v[94:95], v[94:95], v[134:135] op_sel_hi:[1,0]
	v_pk_mul_f32 v[92:93], v[92:93], v[134:135] op_sel_hi:[1,0]
	v_max_f32_e32 v90, 0, v90
	v_max_f32_e32 v91, 0, v91
	s_add_u32 s47, s57, s47
	v_max_f32_e32 v94, 0, v94
	v_max_f32_e32 v95, 0, v95
	v_pk_mul_f32 v[98:99], v[90:91], v[90:91]
	v_max_f32_e32 v90, 0, v96
	v_max_f32_e32 v92, 0, v92
	v_max_f32_e32 v91, 0, v97
	v_max_f32_e32 v93, 0, v93
	s_addc_u32 s57, s59, 0
	v_pk_mul_f32 v[94:95], v[94:95], v[94:95]
	v_pk_mul_f32 v[96:97], v[90:91], v[90:91]
	v_pk_mul_f32 v[100:101], v[92:93], v[92:93]
	s_add_u32 s46, s47, s46
	v_pk_mul_f32 v[82:83], v[82:83], v[134:135] op_sel_hi:[1,0]
	s_addc_u32 s47, s57, 0
	v_cvt_pk_bf16_f32 v90, v94, v95
	v_cvt_pk_bf16_f32 v91, v96, v97
	v_cvt_pk_bf16_f32 v92, v98, v99
	v_cvt_pk_bf16_f32 v93, v100, v101
	v_pk_mul_f32 v[88:89], v[88:89], v[134:135] op_sel_hi:[1,0]
	v_pk_mul_f32 v[86:87], v[86:87], v[134:135] op_sel_hi:[1,0]
	v_pk_mul_f32 v[84:85], v[84:85], v[134:135] op_sel_hi:[1,0]
	v_max_f32_e32 v82, 0, v82
	v_max_f32_e32 v83, 0, v83
	global_store_dwordx4 v141, v[90:93], s[46:47] sc1
	v_max_f32_e32 v86, 0, v86
	v_max_f32_e32 v87, 0, v87
	v_pk_mul_f32 v[90:91], v[82:83], v[82:83]
	v_max_f32_e32 v82, 0, v88
	v_max_f32_e32 v84, 0, v84
	v_max_f32_e32 v83, 0, v89
	v_max_f32_e32 v85, 0, v85
	v_pk_mul_f32 v[86:87], v[86:87], v[86:87]
	v_pk_mul_f32 v[88:89], v[82:83], v[82:83]
	v_pk_mul_f32 v[92:93], v[84:85], v[84:85]
	v_cvt_pk_bf16_f32 v82, v86, v87
	v_cvt_pk_bf16_f32 v83, v88, v89
	v_cvt_pk_bf16_f32 v84, v90, v91
	v_cvt_pk_bf16_f32 v85, v92, v93
	global_store_dwordx4 v141, v[82:85], s[46:47] offset:1024 sc1
	s_ashr_i32 s46, s35, 8
	s_ashr_i32 s47, s46, 31
	s_lshl_b32 s35, s35, 7
	s_lshl_b64 s[46:47], s[46:47], 21
	s_and_b32 s57, s35, 0x4000
	s_and_b32 s35, s35, 0x3800
	s_add_u32 s46, s52, s46
	s_addc_u32 s47, s53, s47
	v_mov_b32_e32 v82, v135
	s_add_u32 s46, s46, s4
	v_pk_mul_f32 v[74:75], v[74:75], v[82:83] op_sel_hi:[1,0]
	s_addc_u32 s47, s47, s5
	v_pk_mul_f32 v[80:81], v[80:81], v[82:83] op_sel_hi:[1,0]
	v_pk_mul_f32 v[78:79], v[78:79], v[82:83] op_sel_hi:[1,0]
	v_pk_mul_f32 v[76:77], v[76:77], v[82:83] op_sel_hi:[1,0]
	v_max_f32_e32 v74, 0, v74
	v_max_f32_e32 v75, 0, v75
	s_add_u32 s46, s46, s57
	v_max_f32_e32 v78, 0, v78
	v_max_f32_e32 v79, 0, v79
	v_pk_mul_f32 v[84:85], v[74:75], v[74:75]
	v_max_f32_e32 v74, 0, v80
	v_max_f32_e32 v76, 0, v76
	v_max_f32_e32 v75, 0, v81
	v_max_f32_e32 v77, 0, v77
	s_addc_u32 s47, s47, 0
	v_pk_mul_f32 v[78:79], v[78:79], v[78:79]
	v_pk_mul_f32 v[80:81], v[74:75], v[74:75]
	v_pk_mul_f32 v[86:87], v[76:77], v[76:77]
	s_add_u32 s46, s46, s35
	v_pk_mul_f32 v[66:67], v[66:67], v[82:83] op_sel_hi:[1,0]
	s_addc_u32 s47, s47, 0
	v_cvt_pk_bf16_f32 v74, v78, v79
	v_cvt_pk_bf16_f32 v75, v80, v81
	v_cvt_pk_bf16_f32 v76, v84, v85
	v_cvt_pk_bf16_f32 v77, v86, v87
	v_pk_mul_f32 v[72:73], v[72:73], v[82:83] op_sel_hi:[1,0]
	v_pk_mul_f32 v[70:71], v[70:71], v[82:83] op_sel_hi:[1,0]
	v_pk_mul_f32 v[68:69], v[68:69], v[82:83] op_sel_hi:[1,0]
	v_max_f32_e32 v66, 0, v66
	v_max_f32_e32 v67, 0, v67
	global_store_dwordx4 v141, v[74:77], s[46:47] sc1
	v_max_f32_e32 v70, 0, v70
	v_max_f32_e32 v71, 0, v71
	v_pk_mul_f32 v[74:75], v[66:67], v[66:67]
	v_max_f32_e32 v66, 0, v72
	v_max_f32_e32 v68, 0, v68
	v_max_f32_e32 v67, 0, v73
	v_max_f32_e32 v69, 0, v69
	v_pk_mul_f32 v[70:71], v[70:71], v[70:71]
	v_pk_mul_f32 v[72:73], v[66:67], v[66:67]
	v_pk_mul_f32 v[76:77], v[68:69], v[68:69]
	v_cvt_pk_bf16_f32 v66, v70, v71
	v_cvt_pk_bf16_f32 v67, v72, v73
	v_cvt_pk_bf16_f32 v68, v74, v75
	v_cvt_pk_bf16_f32 v69, v76, v77
	global_store_dwordx4 v141, v[66:69], s[46:47] offset:1024 sc1
	s_add_i32 s35, s34, 0xb0
	s_add_i32 s46, s34, 0xa0
	s_add_i32 s47, s34, 0x90
	s_addk_i32 s34, 0x80
	s_ashr_i32 s70, s34, 8
	s_ashr_i32 s71, s70, 31
	s_lshl_b32 s34, s34, 7
	ds_read2_b32 v[68:69], v148 offset0:128 offset1:144
	ds_read2_b32 v[66:67], v148 offset0:160 offset1:176
	s_lshl_b64 s[70:71], s[70:71], 21
	s_and_b32 s57, s34, 0x4000
	s_and_b32 s34, s34, 0x2000
	s_add_u32 s59, s52, s70
	s_addc_u32 s66, s53, s71
	s_add_u32 s59, s59, s4
	s_waitcnt lgkmcnt(0)
; __device__ __forceinline__ unsigned lane_tb(int fr, int fq) { return (unsigned)((fr * 64 + fq * 16) ^ ((fr >> 3) << 5)); }
; __device__ __forceinline__ void st_bf8(bf16* p, const f32x4 a, const f32x4 b) { *(GAS v4u*)p = (v4u){pk2(a.x, a.y), pk2(a.z, a.w), pk2(b.x, b.y), pk2(b.z, b.w)}; }
;     template <int NR> __device__ __forceinline__ void rows(const int (&rowb)[NR], int fr, const float (&rstd)[NR], const f32x4 (&a)[NR][2][2], int pn, int wc, int fq) const {
; #pragma unroll
;         for (int i = 0; i < NR; ++i) {
;             const float rr = rstd[i];
; #pragma unroll
;             for (int bj = 0; bj < 2; ++bj) {
;                 f32x4 u = a[i][bj][0] * rr, v = a[i][bj][1] * rr;
; #pragma unroll
;                 for (int j = 0; j < 4; ++j) { const float p = fmaxf(u[j], 0.f), q = fmaxf(v[j], 0.f); u[j] = p * p; v[j] = q * q; }
;                 st_bf8((bf16*)((char*)H + tile_ub(rowb[i], (pn << 8) + 64 * wc + 32 * bj, FF) + lane_tb(fr, fq)), u, v);
;             }
;         }
;     }
	v_pk_mul_f32 v[58:59], v[58:59], v[68:69] op_sel_hi:[1,0]
	s_addc_u32 s66, s66, s5
	v_pk_mul_f32 v[64:65], v[64:65], v[68:69] op_sel_hi:[1,0]
	v_pk_mul_f32 v[62:63], v[62:63], v[68:69] op_sel_hi:[1,0]
	v_pk_mul_f32 v[60:61], v[60:61], v[68:69] op_sel_hi:[1,0]
	v_max_f32_e32 v58, 0, v58
	v_max_f32_e32 v59, 0, v59
	s_add_u32 s57, s59, s57
	v_max_f32_e32 v62, 0, v62
	v_max_f32_e32 v63, 0, v63
	v_pk_mul_f32 v[70:71], v[58:59], v[58:59]
	v_max_f32_e32 v58, 0, v64
	v_max_f32_e32 v60, 0, v60
	v_max_f32_e32 v59, 0, v65
	v_max_f32_e32 v61, 0, v61
	s_addc_u32 s59, s66, 0
	v_pk_mul_f32 v[62:63], v[62:63], v[62:63]
	v_pk_mul_f32 v[64:65], v[58:59], v[58:59]
	v_pk_mul_f32 v[72:73], v[60:61], v[60:61]
	s_add_u32 s70, s57, s34
	v_pk_mul_f32 v[50:51], v[50:51], v[68:69] op_sel_hi:[1,0]
	s_addc_u32 s71, s59, 0
	v_cvt_pk_bf16_f32 v58, v62, v63
	v_cvt_pk_bf16_f32 v59, v64, v65
	v_cvt_pk_bf16_f32 v60, v70, v71
	v_cvt_pk_bf16_f32 v61, v72, v73
	v_pk_mul_f32 v[56:57], v[56:57], v[68:69] op_sel_hi:[1,0]
	v_pk_mul_f32 v[54:55], v[54:55], v[68:69] op_sel_hi:[1,0]
	v_pk_mul_f32 v[52:53], v[52:53], v[68:69] op_sel_hi:[1,0]
	v_max_f32_e32 v50, 0, v50
	v_max_f32_e32 v51, 0, v51
	global_store_dwordx4 v141, v[58:61], s[70:71] sc1
	v_max_f32_e32 v54, 0, v54
	v_max_f32_e32 v55, 0, v55
	v_pk_mul_f32 v[58:59], v[50:51], v[50:51]
	v_max_f32_e32 v50, 0, v56
	v_max_f32_e32 v52, 0, v52
	v_max_f32_e32 v51, 0, v57
	v_max_f32_e32 v53, 0, v53
	v_pk_mul_f32 v[54:55], v[54:55], v[54:55]
	v_pk_mul_f32 v[56:57], v[50:51], v[50:51]
	v_pk_mul_f32 v[60:61], v[52:53], v[52:53]
	v_cvt_pk_bf16_f32 v50, v54, v55
	v_cvt_pk_bf16_f32 v51, v56, v57
	v_cvt_pk_bf16_f32 v52, v58, v59
	v_cvt_pk_bf16_f32 v53, v60, v61
	global_store_dwordx4 v141, v[50:53], s[70:71] offset:1024 sc1
	s_ashr_i32 s70, s47, 8
	s_ashr_i32 s71, s70, 31
	s_lshl_b32 s34, s47, 7
	s_lshl_b64 s[70:71], s[70:71], 21
	s_and_b32 s47, s34, 0x4000
	s_and_b32 s34, s34, 0x2800
	s_add_u32 s57, s52, s70
	s_addc_u32 s59, s53, s71
	v_mov_b32_e32 v50, v69
	s_add_u32 s57, s57, s4
	v_pk_mul_f32 v[42:43], v[42:43], v[50:51] op_sel_hi:[1,0]
	s_addc_u32 s59, s59, s5
	v_pk_mul_f32 v[48:49], v[48:49], v[50:51] op_sel_hi:[1,0]
	v_pk_mul_f32 v[46:47], v[46:47], v[50:51] op_sel_hi:[1,0]
	v_pk_mul_f32 v[44:45], v[44:45], v[50:51] op_sel_hi:[1,0]
	v_max_f32_e32 v42, 0, v42
	v_max_f32_e32 v43, 0, v43
	s_add_u32 s47, s57, s47
	v_max_f32_e32 v46, 0, v46
	v_max_f32_e32 v47, 0, v47
	v_pk_mul_f32 v[52:53], v[42:43], v[42:43]
	v_max_f32_e32 v42, 0, v48
	v_max_f32_e32 v44, 0, v44
	v_max_f32_e32 v43, 0, v49
	v_max_f32_e32 v45, 0, v45
	s_addc_u32 s57, s59, 0
	v_pk_mul_f32 v[46:47], v[46:47], v[46:47]
	v_pk_mul_f32 v[48:49], v[42:43], v[42:43]
	v_pk_mul_f32 v[54:55], v[44:45], v[44:45]
	s_add_u32 s70, s47, s34
	v_pk_mul_f32 v[34:35], v[34:35], v[50:51] op_sel_hi:[1,0]
	s_addc_u32 s71, s57, 0
	v_cvt_pk_bf16_f32 v42, v46, v47
	v_cvt_pk_bf16_f32 v43, v48, v49
	v_cvt_pk_bf16_f32 v44, v52, v53
	v_cvt_pk_bf16_f32 v45, v54, v55
	v_pk_mul_f32 v[40:41], v[40:41], v[50:51] op_sel_hi:[1,0]
	v_pk_mul_f32 v[38:39], v[38:39], v[50:51] op_sel_hi:[1,0]
	v_pk_mul_f32 v[36:37], v[36:37], v[50:51] op_sel_hi:[1,0]
	v_max_f32_e32 v34, 0, v34
	v_max_f32_e32 v35, 0, v35
	global_store_dwordx4 v141, v[42:45], s[70:71] sc1
	v_max_f32_e32 v38, 0, v38
	v_max_f32_e32 v39, 0, v39
	v_pk_mul_f32 v[42:43], v[34:35], v[34:35]
	v_max_f32_e32 v34, 0, v40
	v_max_f32_e32 v36, 0, v36
	v_max_f32_e32 v35, 0, v41
	v_max_f32_e32 v37, 0, v37
	v_pk_mul_f32 v[38:39], v[38:39], v[38:39]
	v_pk_mul_f32 v[40:41], v[34:35], v[34:35]
	v_pk_mul_f32 v[44:45], v[36:37], v[36:37]
	v_cvt_pk_bf16_f32 v34, v38, v39
	v_cvt_pk_bf16_f32 v35, v40, v41
	v_cvt_pk_bf16_f32 v36, v42, v43
	v_cvt_pk_bf16_f32 v37, v44, v45
	global_store_dwordx4 v141, v[34:37], s[70:71] offset:1024 sc1
	s_ashr_i32 s70, s46, 8
	s_ashr_i32 s71, s70, 31
	s_lshl_b32 s34, s46, 7
	s_lshl_b64 s[70:71], s[70:71], 21
	s_and_b32 s46, s34, 0x4000
	s_and_b32 s34, s34, 0x3000
; __device__ __forceinline__ unsigned lane_tb(int fr, int fq) { return (unsigned)((fr * 64 + fq * 16) ^ ((fr >> 3) << 5)); }
; __device__ __forceinline__ void st_bf8(bf16* p, const f32x4 a, const f32x4 b) { *(GAS v4u*)p = (v4u){pk2(a.x, a.y), pk2(a.z, a.w), pk2(b.x, b.y), pk2(b.z, b.w)}; }
;     template <int NR> __device__ __forceinline__ void rows(const int (&rowb)[NR], int fr, const float (&rstd)[NR], const f32x4 (&a)[NR][2][2], int pn, int wc, int fq) const {
; #pragma unroll
;         for (int i = 0; i < NR; ++i) {
;             const float rr = rstd[i];
; #pragma unroll
;             for (int bj = 0; bj < 2; ++bj) {
;                 f32x4 u = a[i][bj][0] * rr, v = a[i][bj][1] * rr;
; #pragma unroll
;                 for (int j = 0; j < 4; ++j) { const float p = fmaxf(u[j], 0.f), q = fmaxf(v[j], 0.f); u[j] = p * p; v[j] = q * q; }
;                 st_bf8((bf16*)((char*)H + tile_ub(rowb[i], (pn << 8) + 64 * wc + 32 * bj, FF) + lane_tb(fr, fq)), u, v);
;             }
;         }
;     }
	s_add_u32 s47, s52, s70
	s_addc_u32 s57, s53, s71
	s_add_u32 s47, s47, s4
	v_pk_mul_f32 v[26:27], v[26:27], v[66:67] op_sel_hi:[1,0]
	s_addc_u32 s57, s57, s5
	v_pk_mul_f32 v[32:33], v[32:33], v[66:67] op_sel_hi:[1,0]
	v_pk_mul_f32 v[30:31], v[30:31], v[66:67] op_sel_hi:[1,0]
	v_pk_mul_f32 v[28:29], v[28:29], v[66:67] op_sel_hi:[1,0]
	v_max_f32_e32 v26, 0, v26
	v_max_f32_e32 v27, 0, v27
	s_add_u32 s46, s47, s46
	v_max_f32_e32 v30, 0, v30
	v_max_f32_e32 v31, 0, v31
	v_pk_mul_f32 v[34:35], v[26:27], v[26:27]
	v_max_f32_e32 v26, 0, v32
	v_max_f32_e32 v28, 0, v28
	v_max_f32_e32 v27, 0, v33
	v_max_f32_e32 v29, 0, v29
	s_addc_u32 s47, s57, 0
	v_pk_mul_f32 v[30:31], v[30:31], v[30:31]
	v_pk_mul_f32 v[32:33], v[26:27], v[26:27]
	v_pk_mul_f32 v[36:37], v[28:29], v[28:29]
	s_add_u32 s46, s46, s34
	v_pk_mul_f32 v[18:19], v[18:19], v[66:67] op_sel_hi:[1,0]
	s_addc_u32 s47, s47, 0
	v_cvt_pk_bf16_f32 v26, v30, v31
	v_cvt_pk_bf16_f32 v27, v32, v33
	v_cvt_pk_bf16_f32 v28, v34, v35
	v_cvt_pk_bf16_f32 v29, v36, v37
	v_pk_mul_f32 v[24:25], v[24:25], v[66:67] op_sel_hi:[1,0]
	v_pk_mul_f32 v[22:23], v[22:23], v[66:67] op_sel_hi:[1,0]
	v_pk_mul_f32 v[20:21], v[20:21], v[66:67] op_sel_hi:[1,0]
	v_max_f32_e32 v18, 0, v18
	v_max_f32_e32 v19, 0, v19
	global_store_dwordx4 v141, v[26:29], s[46:47] sc1
	v_max_f32_e32 v22, 0, v22
	v_max_f32_e32 v23, 0, v23
	v_pk_mul_f32 v[26:27], v[18:19], v[18:19]
	v_max_f32_e32 v18, 0, v24
	v_max_f32_e32 v20, 0, v20
	v_max_f32_e32 v19, 0, v25
	v_max_f32_e32 v21, 0, v21
	v_pk_mul_f32 v[22:23], v[22:23], v[22:23]
	v_pk_mul_f32 v[24:25], v[18:19], v[18:19]
	v_pk_mul_f32 v[28:29], v[20:21], v[20:21]
	v_cvt_pk_bf16_f32 v18, v22, v23
	v_cvt_pk_bf16_f32 v19, v24, v25
	v_cvt_pk_bf16_f32 v20, v26, v27
	v_cvt_pk_bf16_f32 v21, v28, v29
	global_store_dwordx4 v141, v[18:21], s[46:47] offset:1024 sc1
	s_ashr_i32 s46, s35, 8
	s_ashr_i32 s47, s46, 31
	s_lshl_b32 s34, s35, 7
	s_lshl_b64 s[46:47], s[46:47], 21
	s_and_b32 s35, s34, 0x4000
	s_and_b32 s34, s34, 0x3800
	s_add_u32 s46, s52, s46
	s_addc_u32 s47, s53, s47
	v_mov_b32_e32 v18, v67
	s_add_u32 s4, s46, s4
	v_pk_mul_f32 v[10:11], v[10:11], v[18:19] op_sel_hi:[1,0]
	s_addc_u32 s5, s47, s5
	v_pk_mul_f32 v[16:17], v[16:17], v[18:19] op_sel_hi:[1,0]
	v_pk_mul_f32 v[14:15], v[14:15], v[18:19] op_sel_hi:[1,0]
	v_pk_mul_f32 v[12:13], v[12:13], v[18:19] op_sel_hi:[1,0]
	v_max_f32_e32 v10, 0, v10
	v_max_f32_e32 v11, 0, v11
	s_add_u32 s4, s4, s35
	v_max_f32_e32 v14, 0, v14
	v_max_f32_e32 v15, 0, v15
	v_pk_mul_f32 v[20:21], v[10:11], v[10:11]
	v_max_f32_e32 v10, 0, v16
	v_max_f32_e32 v12, 0, v12
	v_max_f32_e32 v11, 0, v17
	v_max_f32_e32 v13, 0, v13
	s_addc_u32 s5, s5, 0
	v_pk_mul_f32 v[14:15], v[14:15], v[14:15]
	v_pk_mul_f32 v[16:17], v[10:11], v[10:11]
	v_pk_mul_f32 v[22:23], v[12:13], v[12:13]
	s_add_u32 s4, s4, s34
	v_pk_mul_f32 v[2:3], v[2:3], v[18:19] op_sel_hi:[1,0]
	s_addc_u32 s5, s5, 0
	v_cvt_pk_bf16_f32 v10, v14, v15
	v_cvt_pk_bf16_f32 v11, v16, v17
	v_cvt_pk_bf16_f32 v12, v20, v21
	v_cvt_pk_bf16_f32 v13, v22, v23
	v_pk_mul_f32 v[8:9], v[8:9], v[18:19] op_sel_hi:[1,0]
	v_pk_mul_f32 v[6:7], v[6:7], v[18:19] op_sel_hi:[1,0]
	v_pk_mul_f32 v[4:5], v[4:5], v[18:19] op_sel_hi:[1,0]
	v_max_f32_e32 v2, 0, v2
	v_max_f32_e32 v3, 0, v3
	global_store_dwordx4 v141, v[10:13], s[4:5] sc1
	v_max_f32_e32 v6, 0, v6
	v_max_f32_e32 v7, 0, v7
	v_pk_mul_f32 v[10:11], v[2:3], v[2:3]
	v_max_f32_e32 v2, 0, v8
	v_max_f32_e32 v4, 0, v4
	v_max_f32_e32 v3, 0, v9
	v_max_f32_e32 v5, 0, v5
	v_pk_mul_f32 v[6:7], v[6:7], v[6:7]
	v_pk_mul_f32 v[8:9], v[2:3], v[2:3]
	v_pk_mul_f32 v[12:13], v[4:5], v[4:5]
	v_cvt_pk_bf16_f32 v2, v6, v7
	v_cvt_pk_bf16_f32 v3, v8, v9
	v_cvt_pk_bf16_f32 v4, v10, v11
	v_cvt_pk_bf16_f32 v5, v12, v13
	global_store_dwordx4 v141, v[2:5], s[4:5] offset:1024 sc1
	s_andn2_b64 vcc, exec, s[60:61]
	s_mov_b64 s[4:5], -1
	s_cbranch_vccnz .LBB0_1115
	s_andn2_b64 vcc, exec, s[38:39]
	s_cbranch_vccnz .LBB0_1114
	s_barrier
	s_branch .LBB0_1114

; __device__ __forceinline__ void st_bf8(bf16* p, const f32x4 a, const f32x4 b) { *(GAS v4u*)p = (v4u){pk2(a.x, a.y), pk2(a.z, a.w), pk2(b.x, b.y), pk2(b.z, b.w)}; }
; __device__ __forceinline__ float sq4(const f32x4 a) { return (a.x * a.x + a.y * a.y) + (a.z * a.z + a.w * a.w); }
;     template <int NR> __device__ __forceinline__ void rows(const int (&rowb)[NR], int fr, const float (&rstd)[NR], const f32x4 (&a)[NR][2][2], int pn, int wc, int fq) const {
;     ...
;         const int dsh = 2 * g, W = 128 << dsh;
;         bf16* dbase = (bf16*)(qkv_base + (size_t)(which * 3 + g) * QKV_STRIDE) + h * 64 + 8 * fq;
;         float* kvp = out + (g == 0 ? O_KV128P : g == 1 ? O_KV512P : O_KV2048P) + (size_t)(which - 1) * 1024 + h * 64 + 8 * fq;
;         float* kvs = out + (g == 0 ? O_KV128S : g == 1 ? O_KV512S : O_KV2048S) + (size_t)(which - 1) * 1024 + h * 64 + 8 * fq;
; #pragma unroll
;         for (int i = 0; i < NR; ++i) {
;             const float rr = rstd[i];
;             f32x4 v[2][2] = {{a[i][0][0] * rr, a[i][0][1] * rr}, {a[i][1][0] * rr, a[i][1][1] * rr}};
;             if (which < 2) {
;                 float ss = sq4(v[0][0]) + sq4(v[0][1]) + sq4(v[1][0]) + sq4(v[1][1]);
;                 ss += __shfl_xor(ss, 16); ss += __shfl_xor(ss, 32);
;                 float sc = rsqrtf(ss * (1.f / 64.f) + EPS); if (which == 0) sc *= QSCALE;
; #pragma unroll
;                 for (int bj = 0; bj < 2; ++bj)
; #pragma unroll
;                     for (int n = 0; n < 2; ++n) v[bj][n] = v[bj][n] * wv[bj][n] * sc;
;             }
;             const int rw = rowb[i] + fr; int arow = rw, b, t = 0; const bool prompt = rw < MP;
;             if (prompt) { b = rw >> 12; t = rw & 4095; arow = (b << 12) + ((t & ((1 << dsh) - 1)) << (12 - dsh)) + (t >> dsh); } else { b = (rw - MP) >> 3; }
;             bf16* dst = dbase + (size_t)arow * DM;
;             st_bf8(dst, v[0][0], v[0][1]); st_bf8(dst + 32, v[1][0], v[1][1]);
;             if (which >= 1) {
;                 float* o = nullptr;
;                 if (prompt) { if (t >= SEQ - W) o = kvp + (size_t)(b * W + (t - (SEQ - W))) * 2048; }
;                 else o = kvs + (size_t)(rw - MP) * 2048;
;                 if (o) { nt_store4(o, v[0][0]); nt_store4(o + 4, v[0][1]); nt_store4(o + 32, v[1][0]); nt_store4(o + 36, v[1][1]); }
.LBB0_1144:
	s_mul_hi_i32 s5, s4, 0x2aaaaaab
	s_lshr_b32 s12, s5, 31
	s_ashr_i32 s5, s5, 1
	s_add_i32 s12, s5, s12
	s_ashr_i32 s5, s16, 4
	s_mul_hi_i32 s13, s5, 0x55555556
	s_lshr_b32 s14, s13, 31
	s_add_i32 s13, s13, s14
	s_mul_i32 s13, s13, 3
	s_add_i32 s23, s18, s17
	s_sub_i32 s17, s5, s13
	s_mul_i32 s5, s12, 3
	s_add_i32 s5, s5, s17
	s_lshl_b32 s34, s17, 1
	s_mul_hi_i32 s13, s5, 0x2100000
	s_mul_i32 s5, s5, 0x2100000
	s_add_u32 s14, s24, s5
	s_addc_u32 s13, s25, s13
	s_lshl_b32 s5, s16, 6
	s_and_b32 s5, s5, 0x3c0
	s_mul_i32 s15, s5, 0x8200
	s_add_u32 s14, s14, s15
	s_addc_u32 s15, s13, 0
	s_waitcnt vmcnt(1)
	v_lshlrev_b32_e32 v2, 1, v146
	v_mov_b32_e32 v3, v149
	s_waitcnt vmcnt(0)
	v_lshl_add_u64 v[6:7], s[14:15], 0, v[2:3]
	v_or_b32_e32 v2, s23, v147
	v_bitop3_b32 v4, s23, v165, v147 bitop3:0xc8
	s_sub_i32 s14, 12, s34
	s_and_b32 s13, s23, 0xfffff000
	v_lshlrev_b32_e32 v3, s14, v2
	v_lshrrev_b32_e32 v5, s34, v4
	v_and_b32_e32 v3, 0xfff, v3
	v_or_b32_e32 v5, s13, v5
	v_add_u32_e32 v3, v5, v3
	v_cmp_gt_i32_e32 vcc, s1, v2
	v_mov_b32_e32 v9, v149
	s_cmp_lt_i32 s4, 12
	v_cndmask_b32_e32 v8, v2, v3, vcc
	v_lshlrev_b64 v[8:9], 7, v[8:9]
	v_lshl_add_u64 v[10:11], v[6:7], 0, v[8:9]
	v_cvt_pk_bf16_f32 v6, v14, v15
	v_cvt_pk_bf16_f32 v7, v16, v17
	v_cvt_pk_bf16_f32 v8, v18, v19
	v_cvt_pk_bf16_f32 v9, v20, v21
	global_store_dwordx4 v[10:11], v[6:9], off sc1
	s_nop 1
	v_cvt_pk_bf16_f32 v6, v22, v23
	v_cvt_pk_bf16_f32 v7, v24, v25
	v_cvt_pk_bf16_f32 v8, v26, v27
	v_cvt_pk_bf16_f32 v9, v28, v29
	global_store_dwordx4 v[10:11], v[6:9], off offset:64 sc1
	s_cbranch_scc1 .LBB0_1134
	s_add_i32 s12, s12, -1
	s_ashr_i32 s13, s12, 31
	s_cmp_eq_u32 s17, 1
	s_cselect_b64 s[14:15], -1, 0
	s_and_b64 s[36:37], s[14:15], exec
	s_cselect_b32 s4, s21, 0x2ac0000
	s_cmp_eq_u32 s17, 0
	s_cselect_b64 s[16:17], -1, 0
	s_and_b64 s[36:37], s[16:17], exec
	s_cselect_b32 s4, 0x15c0000, s4
	s_lshl_b32 s4, s4, 2
	s_add_u32 s4, s28, s4
	s_addc_u32 s35, s29, 0
	s_lshl_b64 s[36:37], s[12:13], 12
	s_add_u32 s4, s4, s36
	s_addc_u32 s36, s35, s37
	s_lshl_b32 s35, s5, 2
	s_add_u32 s4, s4, s35
	s_addc_u32 s5, s36, 0
	v_add_u32_e32 v2, 0xffffc000, v2
	v_mov_b32_e32 v3, v149
	v_lshl_add_u64 v[6:7], s[4:5], 0, v[148:149]
	v_lshlrev_b64 v[2:3], 13, v[2:3]
	v_lshl_add_u64 v[2:3], v[6:7], 0, v[2:3]
	s_and_saveexec_b64 s[4:5], vcc
	s_cbranch_execz .LBB0_1147
	s_lshl_b64 s[12:13], s[12:13], 10
	s_lshl_b32 s36, 0xffffff80, s34
	s_and_b64 s[14:15], s[14:15], exec
	s_cselect_b32 s37, s22, 0x1ac0000
	s_and_b64 s[14:15], s[16:17], exec
	s_cselect_b32 s14, 0x14c0000, s37
	s_lshl_b32 s14, s14, 2
	s_add_u32 s14, s28, s14
	s_addc_u32 s15, s29, 0
	s_lshl_b64 s[12:13], s[12:13], 2
	s_add_u32 s12, s14, s12
	s_addc_u32 s13, s15, s13
	s_add_u32 s12, s12, s35
	s_addc_u32 s13, s13, 0
	v_lshl_add_u64 v[2:3], s[12:13], 0, v[148:149]
	s_lshr_b32 s12, s23, 12
	s_add_i32 s34, s34, 7
	s_lshl_b32 s12, s12, s34
	v_subrev_u32_e32 v5, s36, v4
	v_add_u32_e32 v5, s12, v5
	v_add_u32_e32 v6, 0xfffff000, v5
	v_ashrrev_i32_e32 v7, 31, v6
	s_add_i32 s13, s36, 0x1000
	v_lshlrev_b64 v[6:7], 13, v[6:7]
	v_lshl_add_u64 v[2:3], v[2:3], 0, v[6:7]
	v_cmp_le_i32_e32 vcc, s13, v4
	s_nop 1
	v_cndmask_b32_e32 v3, 0, v3, vcc
	v_cndmask_b32_e32 v2, 0, v2, vcc

; __device__ __forceinline__ unsigned xb_add(unsigned* p, unsigned v) { return __hip_atomic_fetch_add(p, v, __ATOMIC_RELAXED, __HIP_MEMORY_SCOPE_AGENT); }
; __device__ __forceinline__ void xcd_barrier(const XcdBarrier& b) {
;     ...
;         if (old + 1u == (gen + 1u) * nloc) {
;             __builtin_amdgcn_fence(__ATOMIC_RELEASE, "agent");
;             asm volatile("s_waitcnt vmcnt(0)" ::: "memory");
;             const unsigned og = xb_add(&bar[XB_TOP], 1u);
.LBB0_1182:
	s_andn2_saveexec_b64 s[0:1], s[10:11]
	s_cbranch_execz .LBB0_1202
	s_mov_b64 s[10:11], exec
	s_nop 0
	s_nop 0
	s_waitcnt lgkmcnt(0)
	s_waitcnt vmcnt(0)
	v_mbcnt_lo_u32_b32 v3, s10, 0
	v_mbcnt_hi_u32_b32 v3, s11, v3
	v_cmp_eq_u32_e32 vcc, 0, v3
	s_and_saveexec_b64 s[12:13], vcc
	s_cbranch_execz .LBB0_1185
	s_bcnt1_i32_b64 s0, s[10:11]
	v_mov_b32_e32 v4, 0x7000
	v_mov_b32_e32 v5, s0
	global_atomic_add v4, v4, v5, s[30:31] offset:1024 sc0

; #define GAS __attribute__((address_space(1)))
; #define WG_BAR() asm volatile("s_waitcnt lgkmcnt(0)\n\ts_barrier" ::: "memory")
; template <class RowEpi, int MTL>
; __device__ __forceinline__ void small_gemm_t(Frame& F, const bf16* A  , const bf16* Bt, int N, int K, const RowEpi& R, int i_lo, int i_hi) {
;     ...
;         const int ar0 = rb * 16 * MTL + fr, ak0 = w * kw + 8 * fq;
;         const int bp0 = pn * 256 + 32 * wc + fr, bk0 = w * kw + 8 * fq;
; #pragma unroll 4
;         for (int k = 0; k < kw; k += 32) {
;             bf16x8 a[MTL], b[2][2];
; #pragma unroll
;             for (int m = 0; m < MTL; ++m) a[m] = *(const GAS bf16x8*)(A + wt_off(ar0 + 16 * m, ak0 + k, K));
; #pragma unroll
;             for (int bj = 0; bj < 2; ++bj)
; #pragma unroll
;                 for (int n = 0; n < 2; ++n) b[bj][n] = *(const GAS bf16x8*)(Bt + wt_off(bp0 + 128 * bj + 16 * n, bk0 + k, K));
; #pragma unroll
;             for (int m = 0; m < MTL; ++m)
; #pragma unroll
;                 for (int bj = 0; bj < 2; ++bj)
; #pragma unroll
;                     for (int n = 0; n < 2; ++n) acc[m][bj][n] = __builtin_amdgcn_mfma_f32_16x16x32_bf16(b[bj][n], a[m], acc[m][bj][n], 0, 0, 0);
;         }
; #pragma unroll
;         for (int m = 0; m < MTL; ++m)
; #pragma unroll
;             for (int bj = 0; bj < 2; ++bj)
; #pragma unroll
;                 for (int n = 0; n < 2; ++n) part[(w * (4 * MTL) + m * 4 + bj * 2 + n) * 64 + lane] = acc[m][bj][n];
;         WG_BAR();
.LBB0_1812:
	s_cmpk_gt_i32 s19, 0xff
	s_mov_b64 s[16:17], -1
	s_cbranch_scc1 .LBB0_1811
	s_ashr_i32 s12, s19, 31
	s_lshr_b32 s12, s12, 28
	s_add_i32 s16, s19, s12
	s_ashr_i32 s12, s16, 4
	s_and_b32 s16, s16, -16
	s_sub_i32 s16, s19, s16
	s_lshl_b32 s21, s16, 11
	s_lshl_b32 s22, s16, 1
	s_and_b32 s17, s16, -16
	s_and_b32 s21, s21, 0x4000
	s_and_b32 s26, s22, 14
	s_add_u32 s22, s48, s21
	s_addc_u32 s23, s49, 0
	s_bfe_i32 s24, s12, 0x180002
	s_ashr_i32 s25, s24, 31
	s_lshl_b32 s21, s12, 2
	s_and_b32 s21, s21, 12
	s_lshl_b64 s[24:25], s[24:25], 19
	s_add_u32 s24, s33, s24
	s_waitcnt lgkmcnt(0)
	v_add_u32_e32 v18, s17, v12
	s_addc_u32 s25, s45, s25
	v_ashrrev_i32_e32 v19, 31, v18
	v_lshlrev_b64 v[22:23], 15, v[18:19]
	s_lshl_b32 s27, s26, 10
	v_lshl_add_u64 v[38:39], s[24:25], 0, v[6:7]
	v_lshl_or_b32 v54, s21, 10, v2
	v_bitop3_b32 v4, v14, s27, v11 bitop3:0xde
	v_mov_b32_e32 v55, v5
	v_lshl_add_u64 v[42:43], s[22:23], 0, v[22:23]
	v_lshl_add_u64 v[56:57], v[38:39], 0, s[14:15]
	v_or_b32_e32 v58, 0x800, v54
	v_mov_b32_e32 v59, v5
	v_lshl_add_u64 v[26:27], v[38:39], 0, v[54:55]
	v_lshl_add_u64 v[22:23], v[42:43], 0, v[4:5]
	v_lshl_add_u64 v[30:31], v[56:57], 0, v[54:55]
	v_lshl_add_u64 v[34:35], v[56:57], 0, v[58:59]
	global_load_dwordx4 v[18:21], v[26:27], off
	s_nop 0
	global_load_dwordx4 v[22:25], v[22:23], off
	s_nop 0
	global_load_dwordx4 v[26:29], v[26:27], off offset:2048
	v_or_b32_e64 v17, 1, s26
	global_load_dwordx4 v[30:33], v[30:31], off
	v_lshlrev_b32_e32 v17, 10, v17
	global_load_dwordx4 v[34:37], v[34:35], off
	v_bitop3_b32 v60, v14, v17, v11 bitop3:0xde
	v_or_b32_e64 v17, 1, s21
	v_mov_b32_e32 v63, v5
	v_lshl_or_b32 v62, v17, 10, v2
	v_lshl_add_u64 v[44:45], v[38:39], 0, v[62:63]
	global_load_dwordx4 v[38:41], v[44:45], off
	v_mov_b32_e32 v61, v5
	v_mov_b32_e32 v65, v5
	v_or_b32_e32 v64, 0x800, v62
	v_lshl_add_u64 v[46:47], v[42:43], 0, v[60:61]
	v_lshl_add_u64 v[50:51], v[56:57], 0, v[62:63]
	v_lshl_add_u64 v[56:57], v[56:57], 0, v[64:65]
	global_load_dwordx4 v[46:49], v[46:47], off
	v_lshl_add_u64 v[66:67], s[24:25], 0, v[8:9]
	global_load_dwordx4 v[42:45], v[44:45], off offset:2048
	v_lshl_add_u64 v[68:69], v[66:67], 0, v[54:55]
	global_load_dwordx4 v[50:53], v[50:51], off
	s_and_b64 vcc, exec, s[6:7]
	s_waitcnt vmcnt(6)
	v_mfma_f32_16x16x32_bf16 v[26:29], v[26:29], v[22:25], 0
	v_mfma_f32_16x16x32_bf16 v[18:21], v[18:21], v[22:25], 0
	s_waitcnt vmcnt(5)
	v_mfma_f32_16x16x32_bf16 v[30:33], v[30:33], v[22:25], 0
	s_waitcnt vmcnt(4)
	v_mfma_f32_16x16x32_bf16 v[22:25], v[34:37], v[22:25], 0
	global_load_dwordx4 v[34:37], v[56:57], off
	s_waitcnt vmcnt(3)
	v_mfma_f32_16x16x32_bf16 v[18:21], v[38:41], v[46:49], v[18:21]
	v_add_u32_e32 v38, s17, v13
	v_ashrrev_i32_e32 v39, 31, v38
	v_lshlrev_b64 v[38:39], 15, v[38:39]
	v_lshl_add_u64 v[56:57], s[22:23], 0, v[38:39]
	global_load_dwordx4 v[38:41], v[68:69], off
	s_waitcnt vmcnt(3)
	v_mfma_f32_16x16x32_bf16 v[26:29], v[42:45], v[46:49], v[26:29]
	v_lshl_add_u64 v[42:43], v[56:57], 0, v[4:5]
	global_load_dwordx4 v[42:45], v[42:43], off
	s_waitcnt vmcnt(3)
	v_mfma_f32_16x16x32_bf16 v[30:33], v[50:53], v[46:49], v[30:33]
	v_lshl_add_u64 v[50:51], v[66:67], 0, s[14:15]
	v_lshl_add_u64 v[52:53], v[66:67], 0, v[62:63]
	s_waitcnt vmcnt(2)
	v_mfma_f32_16x16x32_bf16 v[22:25], v[34:37], v[46:49], v[22:25]
	global_load_dwordx4 v[34:37], v[68:69], off offset:2048
	v_lshl_add_u64 v[46:47], v[50:51], 0, v[54:55]
	s_waitcnt vmcnt(1)
	v_mfma_f32_16x16x32_bf16 v[18:21], v[38:41], v[42:45], v[18:21]
	global_load_dwordx4 v[38:41], v[46:47], off
	v_lshl_add_u64 v[46:47], v[50:51], 0, v[58:59]
	s_waitcnt vmcnt(1)
	v_mfma_f32_16x16x32_bf16 v[26:29], v[34:37], v[42:45], v[26:29]
	global_load_dwordx4 v[34:37], v[46:47], off
	s_waitcnt vmcnt(1)
	v_mfma_f32_16x16x32_bf16 v[30:33], v[38:41], v[42:45], v[30:33]
	global_load_dwordx4 v[38:41], v[52:53], off
	v_lshl_add_u64 v[46:47], v[56:57], 0, v[60:61]
	global_load_dwordx4 v[46:49], v[46:47], off
	s_waitcnt vmcnt(2)
	v_mfma_f32_16x16x32_bf16 v[22:25], v[34:37], v[42:45], v[22:25]
	global_load_dwordx4 v[34:37], v[52:53], off offset:2048
	v_lshl_add_u64 v[42:43], v[50:51], 0, v[62:63]
	s_waitcnt vmcnt(1)
	v_mfma_f32_16x16x32_bf16 v[18:21], v[38:41], v[46:49], v[18:21]
	global_load_dwordx4 v[38:41], v[42:43], off
	v_lshl_add_u64 v[42:43], v[50:51], 0, v[64:65]
	s_waitcnt vmcnt(1)
	v_mfma_f32_16x16x32_bf16 v[26:29], v[34:37], v[46:49], v[26:29]
	global_load_dwordx4 v[34:37], v[42:43], off
	s_waitcnt vmcnt(1)
	v_mfma_f32_16x16x32_bf16 v[30:33], v[38:41], v[46:49], v[30:33]
	s_waitcnt vmcnt(0)
	v_mfma_f32_16x16x32_bf16 v[22:25], v[34:37], v[46:49], v[22:25]
	ds_write_b128 v15, v[18:21]
	s_nop 1
	ds_write_b128 v15, v[26:29] offset:1024
	s_nop 1
	ds_write_b128 v15, v[30:33] offset:2048
	s_nop 0
	ds_write_b128 v15, v[22:25] offset:3072
	s_waitcnt lgkmcnt(0)
	s_barrier
	s_cbranch_vccnz .LBB0_1810
; template <class RowEpi, int MTL>
; __device__ __forceinline__ void small_gemm_t(Frame& F, const bf16* A  , const bf16* Bt, int N, int K, const RowEpi& R, int i_lo, int i_hi) {
;     ...
;         if (w < MTL) {
;             f32x4 s[2][2];
; #pragma unroll
;             for (int bj = 0; bj < 2; ++bj)
; #pragma unroll
;                 for (int n = 0; n < 2; ++n) { f32x4 t = (f32x4){0.f, 0.f, 0.f, 0.f};
; #pragma unroll
;                     for (int ww = 0; ww < 8; ++ww) t += part[(ww * (4 * MTL) + w * 4 + bj * 2 + n) * 64 + lane];
;                     s[bj][n] = t; }
	s_lshl_b32 s16, s16, 4
	s_lshl_b32 s17, s12, 6
	s_add_i32 s21, s18, s16
	s_lshr_b32 s12, s21, 8
	s_ashr_i32 s16, s17, 6
	ds_read_b128 v[18:21], v15
	s_ashr_i32 s17, s16, 31
	s_lshl_b64 s[22:23], s[12:13], 19
	s_lshl_b32 s12, s21, 7
	s_lshl_b64 s[16:17], s[16:17], 15
	s_and_b32 s24, s12, 0x4000
	ds_read_b128 v[22:25], v15 offset:4096
	ds_read_b128 v[26:29], v15 offset:1024
	s_add_u32 s22, s50, s22
	s_addc_u32 s23, s51, s23
	s_add_u32 s16, s22, s16
	s_waitcnt lgkmcnt(2)
	v_pk_add_f32 v[34:35], v[20:21], 0 op_sel_hi:[1,0]
	v_pk_add_f32 v[36:37], v[18:19], 0 op_sel_hi:[1,0]
	ds_read_b128 v[18:21], v15 offset:8192
	ds_read_b128 v[30:33], v15 offset:5120
	s_addc_u32 s17, s23, s17
	s_waitcnt lgkmcnt(3)
	v_pk_add_f32 v[38:39], v[34:35], v[24:25]
	v_pk_add_f32 v[40:41], v[36:37], v[22:23]
	ds_read_b128 v[22:25], v15 offset:12288
	ds_read_b128 v[34:37], v15 offset:9216
	s_add_u32 s16, s16, s24
	s_addc_u32 s17, s17, 0
	v_lshl_add_u64 v[42:43], s[16:17], 0, v[2:3]
	s_and_b32 s12, s12, 0x3800
	s_waitcnt lgkmcnt(3)
	v_pk_add_f32 v[38:39], v[38:39], v[20:21]
	v_pk_add_f32 v[40:41], v[40:41], v[18:19]
	v_lshl_add_u64 v[54:55], v[42:43], 0, s[12:13]
	ds_read_b128 v[18:21], v15 offset:13312
	s_waitcnt lgkmcnt(2)
	v_pk_add_f32 v[50:51], v[38:39], v[24:25]
	v_pk_add_f32 v[52:53], v[40:41], v[22:23]
	ds_read_b128 v[22:25], v15 offset:16384
	ds_read_b128 v[38:41], v15 offset:20480
	global_load_dwordx4 v[42:45], v[54:55], off
	ds_read_b128 v[46:49], v15 offset:17408
	v_pk_add_f32 v[28:29], v[28:29], 0 op_sel_hi:[1,0]
	s_waitcnt lgkmcnt(2)
	v_pk_add_f32 v[50:51], v[50:51], v[24:25]
	v_pk_add_f32 v[56:57], v[52:53], v[22:23]
	s_waitcnt lgkmcnt(1)
	v_pk_add_f32 v[62:63], v[50:51], v[40:41]
	v_pk_add_f32 v[64:65], v[56:57], v[38:39]
	global_load_dwordx4 v[38:41], v[54:55], off offset:1024
	ds_read_b128 v[22:25], v15 offset:21504
	ds_read_b128 v[50:53], v15 offset:24576
	v_pk_add_f32 v[26:27], v[26:27], 0 op_sel_hi:[1,0]
	ds_read_b128 v[54:57], v15 offset:28672
	ds_read_b128 v[58:61], v15 offset:25600
	v_pk_add_f32 v[28:29], v[28:29], v[32:33]
	v_pk_add_f32 v[26:27], v[26:27], v[30:31]
	v_pk_add_f32 v[28:29], v[28:29], v[36:37]
	v_pk_add_f32 v[26:27], v[26:27], v[34:35]
	v_pk_add_f32 v[20:21], v[28:29], v[20:21]
	v_pk_add_f32 v[18:19], v[26:27], v[18:19]
	s_waitcnt lgkmcnt(4)
	v_pk_add_f32 v[20:21], v[20:21], v[48:49]
	v_pk_add_f32 v[18:19], v[18:19], v[46:47]
	s_waitcnt lgkmcnt(2)
	v_pk_add_f32 v[62:63], v[62:63], v[52:53]
	v_pk_add_f32 v[64:65], v[64:65], v[50:51]
	ds_read_b128 v[50:53], v15 offset:29696
	v_pk_add_f32 v[20:21], v[20:21], v[24:25]
	v_pk_add_f32 v[18:19], v[18:19], v[22:23]
	s_waitcnt lgkmcnt(1)
	v_pk_add_f32 v[22:23], v[20:21], v[60:61]
	v_pk_add_f32 v[24:25], v[18:19], v[58:59]
	ds_read_b128 v[18:21], v15 offset:2048
	s_waitcnt lgkmcnt(1)
	v_pk_add_f32 v[66:67], v[22:23], v[52:53]
	v_pk_add_f32 v[68:69], v[24:25], v[50:51]
	ds_read_b128 v[22:25], v15 offset:6144
	ds_read_b128 v[26:29], v15 offset:3072
	v_pk_add_f32 v[62:63], v[62:63], v[56:57]
	s_waitcnt lgkmcnt(2)
	v_pk_add_f32 v[34:35], v[20:21], 0 op_sel_hi:[1,0]
	v_pk_add_f32 v[36:37], v[18:19], 0 op_sel_hi:[1,0]
	ds_read_b128 v[18:21], v15 offset:10240
	ds_read_b128 v[30:33], v15 offset:7168
	s_waitcnt lgkmcnt(3)
	v_pk_add_f32 v[46:47], v[34:35], v[24:25]
	v_pk_add_f32 v[48:49], v[36:37], v[22:23]
	ds_read_b128 v[22:25], v15 offset:14336
	ds_read_b128 v[34:37], v15 offset:11264
	s_waitcnt lgkmcnt(3)
	v_pk_add_f32 v[50:51], v[46:47], v[20:21]
	v_pk_add_f32 v[52:53], v[48:49], v[18:19]
	ds_read_b128 v[18:21], v15 offset:18432
	ds_read_b128 v[46:49], v15 offset:15360
	v_pk_add_f32 v[64:65], v[64:65], v[54:55]
	s_waitcnt lgkmcnt(3)
	v_pk_add_f32 v[54:55], v[50:51], v[24:25]
	v_pk_add_f32 v[56:57], v[52:53], v[22:23]
	ds_read_b128 v[22:25], v15 offset:22528
	ds_read_b128 v[50:53], v15 offset:19456
	s_waitcnt lgkmcnt(3)
; #define GAS __attribute__((address_space(1)))
;     template <int NR> __device__ __forceinline__ void rows(const int (&rowb)[NR], int fr, const float (&rstd)[NR], const f32x4 (&a)[NR][2][2], int pn, int wc, int fq) const {
;     ...
;             v4u w[NR][2];
; #pragma unroll
;             for (int i = 0; i < NR; ++i)
; #pragma unroll
;                 for (int bj = 0; bj < 2; ++bj) w[i][bj] = *(const GAS v4u*)((const char*)XN + tile_ub(rowb[i], c0b + 32 * bj, DM) + ltb);
; #pragma unroll
;             for (int i = 0; i < NR; ++i)
; #pragma unroll
;                 for (int bj = 0; bj < 2; ++bj) { bs[i][bj][0] = (f32x4){bflo(w[i][bj].x), bfhi(w[i][bj].x), bflo(w[i][bj].y), bfhi(w[i][bj].y)}; bs[i][bj][1] = (f32x4){bflo(w[i][bj].z), bfhi(w[i][bj].z), bflo(w[i][bj].w), bfhi(w[i][bj].w)}; }
;         }
; #pragma unroll
;         for (int i = 0; i < NR; ++i) {
;             const float rr = rstd[i];
;             float ss = 0.f;
; #pragma unroll
;             for (int bj = 0; bj < 2; ++bj) {
;                 const size_t off = (size_t)(rowb[i] + fr) * DM + c0 + 32 * bj;
;                 const f32x4 u = bs[i][bj][0] + a[i][bj][0] * rr, v = bs[i][bj][1] + a[i][bj][1] * rr;
;                 if (Yout) { nt_store4(Yout + off, u); nt_store4(Yout + off + 4, v); }
;                 if (wr_xn) st_bf8((bf16*)((char*)XN + tile_ub(rowb[i], c0b + 32 * bj, DM) + ltb), u, v);
;                 ss += sq4(u) + sq4(v);
;             }
;             if (rs_out) row_atomic(rs_out, rowb[i] + fr, ss, fq);
; template <class RowEpi, int MTL>
; __device__ __forceinline__ void small_gemm_t(Frame& F, const bf16* A  , const bf16* Bt, int N, int K, const RowEpi& R, int i_lo, int i_hi) {
;     ...
;         if (w < MTL) {
;             f32x4 s[2][2];
; #pragma unroll
;             for (int bj = 0; bj < 2; ++bj)
; #pragma unroll
;                 for (int n = 0; n < 2; ++n) { f32x4 t = (f32x4){0.f, 0.f, 0.f, 0.f};
; #pragma unroll
;                     for (int ww = 0; ww < 8; ++ww) t += part[(ww * (4 * MTL) + w * 4 + bj * 2 + n) * 64 + lane];
;                     s[bj][n] = t; }
;             const int row1[1] = {MP + rb * 16 * MTL + 16 * w}; const f32x4 a1[1][2][2] = {{{s[0][0], s[0][1]}, {s[1][0], s[1][1]}}};
;             const float rr1[1] = {rsp ? rsqrtf(rsv * (1.f / DM) + EPS) : 1.f};
;             R.template rows<1>(row1, fr, rr1, a1, pn, wc, fq);
;         }
	v_pk_add_f32 v[58:59], v[54:55], v[20:21]
	v_pk_add_f32 v[60:61], v[56:57], v[18:19]
	ds_read_b128 v[18:21], v15 offset:26624
	ds_read_b128 v[54:57], v15 offset:23552
	v_pk_add_f32 v[28:29], v[28:29], 0 op_sel_hi:[1,0]
	v_pk_add_f32 v[26:27], v[26:27], 0 op_sel_hi:[1,0]
	s_waitcnt lgkmcnt(3)
	v_pk_add_f32 v[70:71], v[58:59], v[24:25]
	v_pk_add_f32 v[72:73], v[60:61], v[22:23]
	ds_read_b128 v[22:25], v15 offset:30720
	ds_read_b128 v[58:61], v15 offset:27648
	v_pk_add_f32 v[28:29], v[28:29], v[32:33]
	v_pk_add_f32 v[26:27], v[26:27], v[30:31]
	s_waitcnt lgkmcnt(3)
	v_pk_add_f32 v[70:71], v[70:71], v[20:21]
	v_pk_add_f32 v[72:73], v[72:73], v[18:19]
	ds_read_b128 v[18:21], v15 offset:31744
	v_pk_add_f32 v[28:29], v[28:29], v[36:37]
	v_pk_add_f32 v[26:27], v[26:27], v[34:35]
	v_pk_add_f32 v[28:29], v[28:29], v[48:49]
	v_pk_add_f32 v[26:27], v[26:27], v[46:47]
	v_pk_add_f32 v[28:29], v[28:29], v[52:53]
	v_pk_add_f32 v[26:27], v[26:27], v[50:51]
	s_waitcnt lgkmcnt(3)
	v_pk_add_f32 v[28:29], v[28:29], v[56:57]
	v_pk_add_f32 v[26:27], v[26:27], v[54:55]
	s_waitcnt lgkmcnt(1)
	v_pk_add_f32 v[28:29], v[28:29], v[60:61]
	v_pk_add_f32 v[26:27], v[26:27], v[58:59]
	s_waitcnt lgkmcnt(0)
	v_pk_add_f32 v[20:21], v[28:29], v[20:21]
	v_pk_add_f32 v[26:27], v[26:27], v[18:19]
	v_pk_add_f32 v[24:25], v[70:71], v[24:25]
	v_pk_add_f32 v[22:23], v[72:73], v[22:23]
	s_add_u32 s16, s16, s12
	s_addc_u32 s17, s17, 0
	s_waitcnt vmcnt(1)
	v_lshlrev_b32_e32 v18, 16, v42
	v_and_b32_e32 v19, 0xffff0000, v42
	v_lshlrev_b32_e32 v28, 16, v43
	v_and_b32_e32 v29, 0xffff0000, v43
	v_pk_add_f32 v[28:29], v[62:63], v[28:29]
	v_pk_add_f32 v[42:43], v[64:65], v[18:19]
	v_lshlrev_b32_e32 v30, 16, v44
	v_and_b32_e32 v31, 0xffff0000, v44
	v_lshlrev_b32_e32 v32, 16, v45
	v_and_b32_e32 v33, 0xffff0000, v45
	v_mul_f32_e32 v4, v43, v43
	v_mul_f32_e32 v17, v29, v29
	v_pk_add_f32 v[32:33], v[66:67], v[32:33]
	v_pk_add_f32 v[30:31], v[68:69], v[30:31]
	v_fmac_f32_e32 v4, v42, v42
	v_fmac_f32_e32 v17, v28, v28
	v_cvt_pk_bf16_f32 v19, v28, v29
	v_add_f32_e32 v4, v4, v17
	v_mul_f32_e32 v17, v31, v31
	v_mul_f32_e32 v28, v33, v33
	s_waitcnt vmcnt(0)
	v_lshlrev_b32_e32 v34, 16, v38
	v_and_b32_e32 v35, 0xffff0000, v38
	v_lshlrev_b32_e32 v36, 16, v39
	v_and_b32_e32 v37, 0xffff0000, v39
	v_fmac_f32_e32 v17, v30, v30
	v_fmac_f32_e32 v28, v32, v32
	v_lshlrev_b32_e32 v38, 16, v40
	v_and_b32_e32 v39, 0xffff0000, v40
	v_lshlrev_b32_e32 v40, 16, v41
	v_and_b32_e32 v41, 0xffff0000, v41
	v_add_f32_e32 v17, v17, v28
	v_pk_add_f32 v[24:25], v[24:25], v[36:37]
	v_pk_add_f32 v[22:23], v[22:23], v[34:35]
	v_add_f32_e32 v4, v4, v17
	v_pk_add_f32 v[28:29], v[20:21], v[40:41]
	v_mul_f32_e32 v17, v23, v23
	v_mul_f32_e32 v20, v25, v25
	v_pk_add_f32 v[26:27], v[26:27], v[38:39]
	v_fmac_f32_e32 v17, v22, v22
	v_fmac_f32_e32 v20, v24, v24
	v_add_f32_e32 v17, v17, v20
	v_mul_f32_e32 v20, v27, v27
	v_mul_f32_e32 v21, v29, v29
	v_fmac_f32_e32 v20, v26, v26
	v_fmac_f32_e32 v21, v28, v28
	v_add_f32_e32 v20, v20, v21
	v_add_f32_e32 v17, v17, v20
	v_and_b32_e32 v20, 64, v16
	v_add_f32_e32 v4, v4, v17
	v_xor_b32_e32 v17, 16, v16
	v_add_u32_e32 v34, 64, v20
	v_cmp_lt_i32_e32 vcc, v17, v34
	v_lshl_add_u64 v[44:45], s[16:17], 0, v[2:3]
	v_cvt_pk_bf16_f32 v18, v42, v43
	v_cndmask_b32_e32 v17, v16, v17, vcc
	v_lshlrev_b32_e32 v17, 2, v17
	ds_bpermute_b32 v17, v17, v4
	v_cvt_pk_bf16_f32 v20, v30, v31
	v_cvt_pk_bf16_f32 v21, v32, v33
	global_store_dwordx4 v[44:45], v[18:21], off sc1
	s_waitcnt lgkmcnt(0)
	v_add_f32_e32 v17, v4, v17
	v_xor_b32_e32 v4, 32, v16
	v_cmp_lt_i32_e32 vcc, v4, v34
	v_cvt_pk_bf16_f32 v20, v22, v23
	v_cvt_pk_bf16_f32 v21, v24, v25
	v_cndmask_b32_e32 v4, v16, v4, vcc
	v_lshlrev_b32_e32 v4, 2, v4
	ds_bpermute_b32 v18, v4, v17
	v_cvt_pk_bf16_f32 v22, v26, v27
	v_cvt_pk_bf16_f32 v23, v28, v29
	global_store_dwordx4 v[44:45], v[20:23], off offset:1024 sc1
	s_and_saveexec_b64 s[16:17], s[0:1]
	s_cbranch_execz .LBB0_1809
	v_or_b32_e32 v4, s21, v160
	v_lshl_add_u64 v[20:21], v[4:5], 2, s[10:11]
	s_waitcnt lgkmcnt(0)
	v_add_f32_e32 v4, v17, v18
	global_atomic_add_f32 v[20:21], v4, off
	s_branch .LBB0_1809

; #define GAS __attribute__((address_space(1)))
; __device__ __forceinline__ float bflo(unsigned w) { return __uint_as_float(w << 16); }
; __device__ __forceinline__ float bfhi(unsigned w) { return __uint_as_float(w & 0xffff0000u); }
; __device__ __forceinline__ unsigned lane_tb(int fr, int fq) { return (unsigned)((fr * 64 + fq * 16) ^ ((fr >> 3) << 5)); }
;     template <int NR> __device__ __forceinline__ void rows(const int (&rowb)[NR], int fr, const float (&rstd)[NR], const f32x4 (&a)[NR][2][2], int pn, int wc, int fq) const {
;         const int c0b = (pn << 8) + 64 * wc, c0 = c0b + 8 * fq; const unsigned ltb = lane_tb(fr, fq);
;         f32x4 bs[NR][2][2];
;         if (xp) {
; #pragma unroll
;             for (int i = 0; i < NR; ++i) { const int rw_ = rowb[i] + fr; const float* base = (rw_ < MP ? xp + (size_t)rw_ * DM : xs + (size_t)(rw_ - MP) * DM) + c0;
; #pragma unroll
;                 for (int bj = 0; bj < 2; ++bj) { bs[i][bj][0] = *(const GAS f32x4*)(base + 32 * bj); bs[i][bj][1] = *(const GAS f32x4*)(base + 32 * bj + 4); } }
;         } else {
;             v4u w[NR][2];
; #pragma unroll
;             for (int i = 0; i < NR; ++i)
; #pragma unroll
;                 for (int bj = 0; bj < 2; ++bj) w[i][bj] = *(const GAS v4u*)((const char*)XN + tile_ub(rowb[i], c0b + 32 * bj, DM) + ltb);
; #pragma unroll
;             for (int i = 0; i < NR; ++i)
; #pragma unroll
;                 for (int bj = 0; bj < 2; ++bj) { bs[i][bj][0] = (f32x4){bflo(w[i][bj].x), bfhi(w[i][bj].x), bflo(w[i][bj].y), bfhi(w[i][bj].y)}; bs[i][bj][1] = (f32x4){bflo(w[i][bj].z), bfhi(w[i][bj].z), bflo(w[i][bj].w), bfhi(w[i][bj].w)}; }
;         }
; #pragma unroll
;         for (int i = 0; i < NR; ++i) {
;             const float rr = rstd[i];
;             float ss = 0.f;
; #pragma unroll
;             for (int bj = 0; bj < 2; ++bj) {
;                 const size_t off = (size_t)(rowb[i] + fr) * DM + c0 + 32 * bj;
;                 const f32x4 u = bs[i][bj][0] + a[i][bj][0] * rr, v = bs[i][bj][1] + a[i][bj][1] * rr;
;                 if (Yout) { nt_store4(Yout + off, u); nt_store4(Yout + off + 4, v); }
;                 if (wr_xn) st_bf8((bf16*)((char*)XN + tile_ub(rowb[i], c0b + 32 * bj, DM) + ltb), u, v);
;                 ss += sq4(u) + sq4(v);
;             }
;             if (rs_out) row_atomic(rs_out, rowb[i] + fr, ss, fq);
;         }
.LBB0_1861:
	s_lshl_b32 s0, s0, 8
	s_or_b32 s0, s0, s85
	s_ashr_i32 s0, s0, 6
	s_lshl_b32 s43, s60, 8
	s_ashr_i32 s1, s0, 31
	s_lshl_b64 s[60:61], s[0:1], 15
	s_add_i32 s41, s43, s84
	s_add_i32 s91, s43, s86
	s_add_i32 s90, s43, s87
	s_add_i32 s43, s43, s88
	s_add_u32 s92, s50, s60
	s_addc_u32 s93, s51, s61
	s_ashr_i32 s0, s41, 8
	s_ashr_i32 s1, s0, 31
	s_lshl_b32 s12, s41, 7
	v_mov_b32_e32 v130, v0
	s_lshl_b64 s[0:1], s[0:1], 19
	s_and_b32 s8, s12, 0x4000
	s_add_u32 s4, s92, s0
	v_and_b32_e32 v166, 15, v130
	v_bfe_u32 v167, v130, 4, 2
	v_lshlrev_b32_e32 v130, 2, v130
	s_addc_u32 s5, s93, s1
	v_lshlrev_b32_e32 v131, 6, v166
	v_lshlrev_b32_e32 v132, 4, v167
	v_and_b32_e32 v130, 32, v130
	s_add_u32 s4, s4, s8
	v_bitop3_b32 v156, v132, v130, v131 bitop3:0x36
	s_addc_u32 s5, s5, 0
	v_lshl_add_u64 v[130:131], s[4:5], 0, v[156:157]
	s_and_b32 s66, s12, 0x2000
	s_mov_b32 s67, s13
	v_lshl_add_u64 v[130:131], v[130:131], 0, s[66:67]
	global_load_dwordx4 v[168:171], v[130:131], off
	global_load_dwordx4 v[172:175], v[130:131], off offset:1024
	s_ashr_i32 s34, s91, 8
	s_lshl_b32 s4, s91, 7
	s_ashr_i32 s35, s34, 31
	s_and_b32 s95, s4, 0x4000
	s_lshl_b64 s[64:65], s[34:35], 19
	s_add_u32 s9, s92, s64
	s_addc_u32 s12, s93, s65
	s_add_u32 s34, s9, s95
	s_addc_u32 s35, s12, 0
	s_ashr_i32 s62, s90, 8
	s_and_b32 s12, s4, 0x2800
	s_lshl_b32 s4, s90, 7
	s_ashr_i32 s63, s62, 31
	s_and_b32 s94, s4, 0x4000
	s_lshl_b64 s[62:63], s[62:63], 19
	s_add_u32 s9, s92, s62
	v_lshl_add_u64 v[130:131], s[34:35], 0, v[156:157]
	s_addc_u32 s35, s93, s63
	s_add_u32 s34, s9, s94
	s_addc_u32 s35, s35, 0
	s_ashr_i32 s96, s43, 8
	v_lshl_add_u64 v[130:131], v[130:131], 0, s[12:13]
	s_and_b32 s46, s4, 0x3000
	s_lshl_b32 s4, s43, 7
	s_ashr_i32 s97, s96, 31
	global_load_dwordx4 v[150:153], v[130:131], off
	global_load_dwordx4 v[146:149], v[130:131], off offset:1024
	v_lshl_add_u64 v[130:131], s[34:35], 0, v[156:157]
	s_and_b32 s67, s4, 0x4000
	s_lshl_b64 s[34:35], s[96:97], 19
	s_mov_b32 s47, s13
	s_add_u32 s9, s92, s34
	v_lshl_add_u64 v[130:131], v[130:131], 0, s[46:47]
	s_addc_u32 s47, s93, s35
	s_add_u32 s96, s9, s67
	s_addc_u32 s97, s47, 0
	s_mov_b32 s5, s13
	global_load_dwordx4 v[142:145], v[130:131], off
	global_load_dwordx4 v[138:141], v[130:131], off offset:1024
	s_and_b32 s4, s4, 0x3800
	v_lshl_add_u64 v[130:131], s[96:97], 0, v[156:157]
	v_lshl_add_u64 v[130:131], v[130:131], 0, s[4:5]
	global_load_dwordx4 v[134:137], v[130:131], off
	s_nop 0
	global_load_dwordx4 v[130:133], v[130:131], off offset:1024
	s_add_u32 s0, s50, s0
	v_cmp_eq_u32_e32 vcc, 0, v167
	s_addc_u32 s1, s51, s1
	s_add_u32 s0, s0, s60
	s_addc_u32 s1, s1, s61
	s_add_u32 s0, s0, s8
	s_addc_u32 s1, s1, 0
	s_add_u32 s96, s0, s66
	s_addc_u32 s97, s1, 0
	s_waitcnt vmcnt(0)
	v_lshlrev_b32_e32 v176, 16, v168
	v_and_b32_e32 v177, 0xffff0000, v168
	v_lshlrev_b32_e32 v168, 16, v169
	v_and_b32_e32 v169, 0xffff0000, v169
	v_lshlrev_b32_e32 v178, 16, v170
	v_and_b32_e32 v179, 0xffff0000, v170
	v_lshlrev_b32_e32 v170, 16, v171
	v_and_b32_e32 v171, 0xffff0000, v171
	v_pk_add_f32 v[126:127], v[126:127], v[176:177]
	v_pk_add_f32 v[128:129], v[128:129], v[168:169]
	v_pk_add_f32 v[168:169], v[124:125], v[170:171]
	v_pk_add_f32 v[124:125], v[122:123], v[178:179]
	v_cvt_pk_bf16_f32 v122, v126, v127
	v_mul_f32_e32 v127, v127, v127
	v_fmac_f32_e32 v127, v126, v126
	v_mul_f32_e32 v126, v129, v129
	v_fmac_f32_e32 v126, v128, v128
	v_lshlrev_b32_e32 v180, 16, v172
	v_and_b32_e32 v181, 0xffff0000, v172
	v_lshlrev_b32_e32 v172, 16, v173
	v_and_b32_e32 v173, 0xffff0000, v173
	v_cvt_pk_bf16_f32 v123, v128, v129
	v_add_f32_e32 v126, v127, v126
	v_mul_f32_e32 v127, v125, v125
	v_mul_f32_e32 v128, v169, v169
	v_lshlrev_b32_e32 v182, 16, v174
	v_and_b32_e32 v183, 0xffff0000, v174
	v_fmac_f32_e32 v127, v124, v124
	v_fmac_f32_e32 v128, v168, v168
	v_pk_add_f32 v[120:121], v[120:121], v[172:173]
	v_pk_add_f32 v[118:119], v[118:119], v[180:181]
	v_lshlrev_b32_e32 v174, 16, v175
	v_and_b32_e32 v175, 0xffff0000, v175
	v_add_f32_e32 v127, v127, v128
	v_pk_add_f32 v[128:129], v[114:115], v[182:183]
	v_mul_f32_e32 v114, v119, v119
	v_mul_f32_e32 v115, v121, v121
	v_add_f32_e32 v167, v127, v126
	v_pk_add_f32 v[126:127], v[116:117], v[174:175]
	v_fmac_f32_e32 v114, v118, v118
	v_fmac_f32_e32 v115, v120, v120
	v_add_f32_e32 v114, v114, v115
	v_mul_f32_e32 v115, v129, v129
	v_mul_f32_e32 v116, v127, v127
	v_fmac_f32_e32 v115, v128, v128
	v_fmac_f32_e32 v116, v126, v126
	v_add_f32_e32 v115, v115, v116
	v_add_f32_e32 v114, v115, v114
	v_and_b32_e32 v116, 64, v164
	v_add_f32_e32 v115, v167, v114
	v_xor_b32_e32 v114, 16, v164
	v_add_u32_e32 v117, 64, v116
	v_cmp_lt_i32_e64 s[0:1], v114, v117
	v_cvt_pk_bf16_f32 v124, v124, v125
	v_cvt_pk_bf16_f32 v125, v168, v169
	v_cndmask_b32_e64 v114, v164, v114, s[0:1]
	v_lshlrev_b32_e32 v114, 2, v114
	ds_bpermute_b32 v116, v114, v115
	v_cvt_pk_bf16_f32 v118, v118, v119
	v_cvt_pk_bf16_f32 v119, v120, v121
	v_cvt_pk_bf16_f32 v120, v128, v129
	v_cvt_pk_bf16_f32 v121, v126, v127
	s_waitcnt lgkmcnt(0)
	v_add_f32_e32 v116, v115, v116
	v_xor_b32_e32 v115, 32, v164
	v_cmp_lt_i32_e64 s[0:1], v115, v117
	global_store_dwordx4 v156, v[122:125], s[96:97] sc1
	global_store_dwordx4 v156, v[118:121], s[96:97] offset:1024 sc1
	v_cndmask_b32_e64 v115, v164, v115, s[0:1]
	v_lshlrev_b32_e32 v115, 2, v115
	ds_bpermute_b32 v117, v115, v116
	s_and_saveexec_b64 s[0:1], vcc
	s_cbranch_execz .LBB0_1863
	s_waitcnt lgkmcnt(0)
	v_add_f32_e32 v118, v116, v117
	v_or_b32_e32 v116, s41, v166
	v_ashrrev_i32_e32 v117, 31, v116
	v_lshl_add_u64 v[116:117], v[116:117], 2, s[10:11]
	global_atomic_add_f32 v[116:117], v118, off
; #define GAS __attribute__((address_space(1)))
; __device__ __forceinline__ float bflo(unsigned w) { return __uint_as_float(w << 16); }
; __device__ __forceinline__ float bfhi(unsigned w) { return __uint_as_float(w & 0xffff0000u); }
; __device__ __forceinline__ void st_bf8(bf16* p, const f32x4 a, const f32x4 b) { *(GAS v4u*)p = (v4u){pk2(a.x, a.y), pk2(a.z, a.w), pk2(b.x, b.y), pk2(b.z, b.w)}; }
; __device__ __forceinline__ float sq4(const f32x4 a) { return (a.x * a.x + a.y * a.y) + (a.z * a.z + a.w * a.w); }
; __device__ __forceinline__ void row_atomic(float* rs, int row, float s, int fq) { s += __shfl_xor(s, 16); s += __shfl_xor(s, 32); if (fq == 0) atomicAdd(rs + row, s); }
; __device__ __forceinline__ void nt_store4(float* p, f32x4 v) { __builtin_nontemporal_store(v, (f32x4*)p); }
;     template <int NR> __device__ __forceinline__ void rows(const int (&rowb)[NR], int fr, const float (&rstd)[NR], const f32x4 (&a)[NR][2][2], int pn, int wc, int fq) const {
;     ...
;             v4u w[NR][2];
; #pragma unroll
;             for (int i = 0; i < NR; ++i)
; #pragma unroll
;                 for (int bj = 0; bj < 2; ++bj) w[i][bj] = *(const GAS v4u*)((const char*)XN + tile_ub(rowb[i], c0b + 32 * bj, DM) + ltb);
; #pragma unroll
;             for (int i = 0; i < NR; ++i)
; #pragma unroll
;                 for (int bj = 0; bj < 2; ++bj) { bs[i][bj][0] = (f32x4){bflo(w[i][bj].x), bfhi(w[i][bj].x), bflo(w[i][bj].y), bfhi(w[i][bj].y)}; bs[i][bj][1] = (f32x4){bflo(w[i][bj].z), bfhi(w[i][bj].z), bflo(w[i][bj].w), bfhi(w[i][bj].w)}; }
;         }
; #pragma unroll
;         for (int i = 0; i < NR; ++i) {
;             const float rr = rstd[i];
;             float ss = 0.f;
; #pragma unroll
;             for (int bj = 0; bj < 2; ++bj) {
;                 const size_t off = (size_t)(rowb[i] + fr) * DM + c0 + 32 * bj;
;                 const f32x4 u = bs[i][bj][0] + a[i][bj][0] * rr, v = bs[i][bj][1] + a[i][bj][1] * rr;
;                 if (Yout) { nt_store4(Yout + off, u); nt_store4(Yout + off + 4, v); }
;                 if (wr_xn) st_bf8((bf16*)((char*)XN + tile_ub(rowb[i], c0b + 32 * bj, DM) + ltb), u, v);
;                 ss += sq4(u) + sq4(v);
;             }
;             if (rs_out) row_atomic(rs_out, rowb[i] + fr, ss, fq);
.LBB0_1863:
	s_or_b64 exec, exec, s[0:1]
	v_lshlrev_b32_e32 v116, 16, v150
	s_waitcnt lgkmcnt(0)
	v_and_b32_e32 v117, 0xffff0000, v150
	v_lshlrev_b32_e32 v118, 16, v151
	v_and_b32_e32 v119, 0xffff0000, v151
	v_lshlrev_b32_e32 v120, 16, v152
	v_and_b32_e32 v121, 0xffff0000, v152
	v_lshlrev_b32_e32 v122, 16, v153
	v_and_b32_e32 v123, 0xffff0000, v153
	v_pk_add_f32 v[110:111], v[110:111], v[116:117]
	v_pk_add_f32 v[112:113], v[112:113], v[118:119]
	v_pk_add_f32 v[116:117], v[108:109], v[122:123]
	v_pk_add_f32 v[108:109], v[106:107], v[120:121]
	v_cvt_pk_bf16_f32 v106, v110, v111
	v_mul_f32_e32 v111, v111, v111
	v_fmac_f32_e32 v111, v110, v110
	v_mul_f32_e32 v110, v113, v113
	v_fmac_f32_e32 v110, v112, v112
	v_lshlrev_b32_e32 v124, 16, v146
	v_and_b32_e32 v125, 0xffff0000, v146
	v_lshlrev_b32_e32 v126, 16, v147
	v_and_b32_e32 v127, 0xffff0000, v147
	v_cvt_pk_bf16_f32 v107, v112, v113
	v_add_f32_e32 v110, v111, v110
	v_mul_f32_e32 v111, v109, v109
	v_mul_f32_e32 v112, v117, v117
	v_lshlrev_b32_e32 v128, 16, v148
	v_and_b32_e32 v129, 0xffff0000, v148
	v_fmac_f32_e32 v111, v108, v108
	v_fmac_f32_e32 v112, v116, v116
	v_pk_add_f32 v[104:105], v[104:105], v[126:127]
	v_pk_add_f32 v[102:103], v[102:103], v[124:125]
	v_lshlrev_b32_e32 v146, 16, v149
	v_and_b32_e32 v147, 0xffff0000, v149
	v_add_f32_e32 v111, v111, v112
	v_pk_add_f32 v[112:113], v[98:99], v[128:129]
	v_mul_f32_e32 v98, v103, v103
	v_mul_f32_e32 v99, v105, v105
	v_add_f32_e32 v120, v111, v110
	v_pk_add_f32 v[110:111], v[100:101], v[146:147]
	v_fmac_f32_e32 v98, v102, v102
	v_fmac_f32_e32 v99, v104, v104
	v_add_f32_e32 v98, v98, v99
	v_mul_f32_e32 v99, v113, v113
	v_mul_f32_e32 v100, v111, v111
	v_fmac_f32_e32 v99, v112, v112
	v_fmac_f32_e32 v100, v110, v110
	v_add_f32_e32 v99, v99, v100
	v_add_f32_e32 v98, v99, v98
	v_add_f32_e32 v98, v120, v98
	ds_bpermute_b32 v99, v114, v98
	s_add_u32 s0, s50, s64
	s_addc_u32 s1, s51, s65
	s_add_u32 s0, s0, s60
	s_addc_u32 s1, s1, s61
	s_waitcnt lgkmcnt(0)
	v_add_f32_e32 v98, v98, v99
	s_add_u32 s0, s0, s95
	ds_bpermute_b32 v99, v115, v98
	s_addc_u32 s1, s1, 0
	s_add_u32 s0, s0, s12
	s_addc_u32 s1, s1, 0
	v_lshl_add_u64 v[118:119], s[0:1], 0, v[156:157]
	v_cvt_pk_bf16_f32 v108, v108, v109
	v_cvt_pk_bf16_f32 v109, v116, v117
	v_cvt_pk_bf16_f32 v100, v102, v103
	v_cvt_pk_bf16_f32 v101, v104, v105
	v_cvt_pk_bf16_f32 v102, v112, v113
	v_cvt_pk_bf16_f32 v103, v110, v111
	global_store_dwordx4 v[118:119], v[106:109], off sc1
	global_store_dwordx4 v[118:119], v[100:103], off offset:1024 sc1
	s_and_saveexec_b64 s[0:1], vcc
	s_cbranch_execz .LBB0_1865
	s_waitcnt lgkmcnt(0)
	v_add_f32_e32 v100, v98, v99
	v_or_b32_e32 v98, s91, v166
	v_ashrrev_i32_e32 v99, 31, v98
	v_lshl_add_u64 v[98:99], v[98:99], 2, s[10:11]
	global_atomic_add_f32 v[98:99], v100, off
.LBB0_1865:
	s_or_b64 exec, exec, s[0:1]
	v_lshlrev_b32_e32 v98, 16, v142
	s_waitcnt lgkmcnt(0)
	v_and_b32_e32 v99, 0xffff0000, v142
	v_lshlrev_b32_e32 v100, 16, v143
	v_and_b32_e32 v101, 0xffff0000, v143
	v_lshlrev_b32_e32 v102, 16, v144
	v_and_b32_e32 v103, 0xffff0000, v144
	v_lshlrev_b32_e32 v104, 16, v145
	v_and_b32_e32 v105, 0xffff0000, v145
	v_pk_add_f32 v[94:95], v[94:95], v[98:99]
	v_pk_add_f32 v[96:97], v[96:97], v[100:101]
	v_pk_add_f32 v[98:99], v[92:93], v[104:105]
	v_pk_add_f32 v[92:93], v[90:91], v[102:103]
	v_cvt_pk_bf16_f32 v90, v94, v95
	v_mul_f32_e32 v95, v95, v95
	v_fmac_f32_e32 v95, v94, v94
	v_mul_f32_e32 v94, v97, v97
	v_fmac_f32_e32 v94, v96, v96
	v_lshlrev_b32_e32 v106, 16, v138
	v_and_b32_e32 v107, 0xffff0000, v138
	v_lshlrev_b32_e32 v108, 16, v139
	v_and_b32_e32 v109, 0xffff0000, v139
	v_cvt_pk_bf16_f32 v91, v96, v97
	v_add_f32_e32 v94, v95, v94
	v_mul_f32_e32 v95, v93, v93
	v_mul_f32_e32 v96, v99, v99
	v_lshlrev_b32_e32 v110, 16, v140
	v_and_b32_e32 v111, 0xffff0000, v140
	v_fmac_f32_e32 v95, v92, v92
	v_fmac_f32_e32 v96, v98, v98
	v_pk_add_f32 v[88:89], v[88:89], v[108:109]
	v_pk_add_f32 v[86:87], v[86:87], v[106:107]
	v_lshlrev_b32_e32 v112, 16, v141
	v_and_b32_e32 v113, 0xffff0000, v141
	v_add_f32_e32 v95, v95, v96
	v_pk_add_f32 v[96:97], v[82:83], v[110:111]
	v_mul_f32_e32 v82, v87, v87
	v_mul_f32_e32 v83, v89, v89
	v_add_f32_e32 v102, v94, v95
	v_pk_add_f32 v[94:95], v[84:85], v[112:113]
	v_fmac_f32_e32 v82, v86, v86
	v_fmac_f32_e32 v83, v88, v88
	v_add_f32_e32 v82, v82, v83
	v_mul_f32_e32 v83, v97, v97
	v_mul_f32_e32 v84, v95, v95
	v_fmac_f32_e32 v83, v96, v96
	v_fmac_f32_e32 v84, v94, v94
	v_add_f32_e32 v83, v83, v84
	v_add_f32_e32 v82, v82, v83
	v_add_f32_e32 v82, v102, v82
	ds_bpermute_b32 v83, v114, v82
	s_add_u32 s0, s50, s62
	s_addc_u32 s1, s51, s63
	s_add_u32 s0, s0, s60
	s_addc_u32 s1, s1, s61
	s_waitcnt lgkmcnt(0)
	v_add_f32_e32 v82, v82, v83
	s_add_u32 s0, s0, s94
	ds_bpermute_b32 v83, v115, v82
	s_addc_u32 s1, s1, 0
	s_add_u32 s0, s0, s46
	s_addc_u32 s1, s1, 0
	v_lshl_add_u64 v[100:101], s[0:1], 0, v[156:157]
	v_cvt_pk_bf16_f32 v92, v92, v93
	v_cvt_pk_bf16_f32 v93, v98, v99
	v_cvt_pk_bf16_f32 v84, v86, v87
	v_cvt_pk_bf16_f32 v85, v88, v89
	v_cvt_pk_bf16_f32 v86, v96, v97
	v_cvt_pk_bf16_f32 v87, v94, v95
	global_store_dwordx4 v[100:101], v[90:93], off sc1
	global_store_dwordx4 v[100:101], v[84:87], off offset:1024 sc1
	s_and_saveexec_b64 s[0:1], vcc
	s_cbranch_execz .LBB0_1867
	s_waitcnt lgkmcnt(0)
	v_add_f32_e32 v84, v82, v83
	v_or_b32_e32 v82, s90, v166
	v_ashrrev_i32_e32 v83, 31, v82
	v_lshl_add_u64 v[82:83], v[82:83], 2, s[10:11]
	global_atomic_add_f32 v[82:83], v84, off
; #define GAS __attribute__((address_space(1)))
; __device__ __forceinline__ float bflo(unsigned w) { return __uint_as_float(w << 16); }
; __device__ __forceinline__ float bfhi(unsigned w) { return __uint_as_float(w & 0xffff0000u); }
; __device__ __forceinline__ void st_bf8(bf16* p, const f32x4 a, const f32x4 b) { *(GAS v4u*)p = (v4u){pk2(a.x, a.y), pk2(a.z, a.w), pk2(b.x, b.y), pk2(b.z, b.w)}; }
; __device__ __forceinline__ float sq4(const f32x4 a) { return (a.x * a.x + a.y * a.y) + (a.z * a.z + a.w * a.w); }
; __device__ __forceinline__ void row_atomic(float* rs, int row, float s, int fq) { s += __shfl_xor(s, 16); s += __shfl_xor(s, 32); if (fq == 0) atomicAdd(rs + row, s); }
; __device__ __forceinline__ void nt_store4(float* p, f32x4 v) { __builtin_nontemporal_store(v, (f32x4*)p); }
;     template <int NR> __device__ __forceinline__ void rows(const int (&rowb)[NR], int fr, const float (&rstd)[NR], const f32x4 (&a)[NR][2][2], int pn, int wc, int fq) const {
;     ...
;             v4u w[NR][2];
; #pragma unroll
;             for (int i = 0; i < NR; ++i)
; #pragma unroll
;                 for (int bj = 0; bj < 2; ++bj) w[i][bj] = *(const GAS v4u*)((const char*)XN + tile_ub(rowb[i], c0b + 32 * bj, DM) + ltb);
; #pragma unroll
;             for (int i = 0; i < NR; ++i)
; #pragma unroll
;                 for (int bj = 0; bj < 2; ++bj) { bs[i][bj][0] = (f32x4){bflo(w[i][bj].x), bfhi(w[i][bj].x), bflo(w[i][bj].y), bfhi(w[i][bj].y)}; bs[i][bj][1] = (f32x4){bflo(w[i][bj].z), bfhi(w[i][bj].z), bflo(w[i][bj].w), bfhi(w[i][bj].w)}; }
;         }
; #pragma unroll
;         for (int i = 0; i < NR; ++i) {
;             const float rr = rstd[i];
;             float ss = 0.f;
; #pragma unroll
;             for (int bj = 0; bj < 2; ++bj) {
;                 const size_t off = (size_t)(rowb[i] + fr) * DM + c0 + 32 * bj;
;                 const f32x4 u = bs[i][bj][0] + a[i][bj][0] * rr, v = bs[i][bj][1] + a[i][bj][1] * rr;
;                 if (Yout) { nt_store4(Yout + off, u); nt_store4(Yout + off + 4, v); }
;                 if (wr_xn) st_bf8((bf16*)((char*)XN + tile_ub(rowb[i], c0b + 32 * bj, DM) + ltb), u, v);
;                 ss += sq4(u) + sq4(v);
;             }
;             if (rs_out) row_atomic(rs_out, rowb[i] + fr, ss, fq);
.LBB0_1867:
	s_or_b64 exec, exec, s[0:1]
	v_lshlrev_b32_e32 v82, 16, v134
	s_waitcnt lgkmcnt(0)
	v_and_b32_e32 v83, 0xffff0000, v134
	v_lshlrev_b32_e32 v84, 16, v135
	v_and_b32_e32 v85, 0xffff0000, v135
	v_lshlrev_b32_e32 v86, 16, v136
	v_and_b32_e32 v87, 0xffff0000, v136
	v_lshlrev_b32_e32 v88, 16, v137
	v_and_b32_e32 v89, 0xffff0000, v137
	v_pk_add_f32 v[78:79], v[78:79], v[82:83]
	v_pk_add_f32 v[80:81], v[80:81], v[84:85]
	v_pk_add_f32 v[82:83], v[76:77], v[88:89]
	v_pk_add_f32 v[76:77], v[74:75], v[86:87]
	v_cvt_pk_bf16_f32 v74, v78, v79
	v_mul_f32_e32 v79, v79, v79
	v_fmac_f32_e32 v79, v78, v78
	v_mul_f32_e32 v78, v81, v81
	v_fmac_f32_e32 v78, v80, v80
	v_lshlrev_b32_e32 v90, 16, v130
	v_and_b32_e32 v91, 0xffff0000, v130
	v_lshlrev_b32_e32 v92, 16, v131
	v_and_b32_e32 v93, 0xffff0000, v131
	v_cvt_pk_bf16_f32 v75, v80, v81
	v_add_f32_e32 v78, v79, v78
	v_mul_f32_e32 v79, v77, v77
	v_mul_f32_e32 v80, v83, v83
	v_lshlrev_b32_e32 v94, 16, v132
	v_and_b32_e32 v95, 0xffff0000, v132
	v_fmac_f32_e32 v79, v76, v76
	v_fmac_f32_e32 v80, v82, v82
	v_pk_add_f32 v[72:73], v[72:73], v[92:93]
	v_pk_add_f32 v[70:71], v[70:71], v[90:91]
	v_lshlrev_b32_e32 v96, 16, v133
	v_and_b32_e32 v97, 0xffff0000, v133
	v_add_f32_e32 v79, v79, v80
	v_pk_add_f32 v[80:81], v[66:67], v[94:95]
	v_mul_f32_e32 v66, v71, v71
	v_mul_f32_e32 v67, v73, v73
	v_add_f32_e32 v86, v78, v79
	v_pk_add_f32 v[78:79], v[68:69], v[96:97]
	v_fmac_f32_e32 v66, v70, v70
	v_fmac_f32_e32 v67, v72, v72
	v_add_f32_e32 v66, v66, v67
	v_mul_f32_e32 v67, v81, v81
	v_mul_f32_e32 v68, v79, v79
	v_fmac_f32_e32 v67, v80, v80
	v_fmac_f32_e32 v68, v78, v78
	v_add_f32_e32 v67, v67, v68
	v_add_f32_e32 v66, v66, v67
	v_add_f32_e32 v66, v86, v66
	ds_bpermute_b32 v67, v114, v66
	s_add_u32 s0, s50, s34
	s_addc_u32 s1, s51, s35
	s_add_u32 s0, s0, s60
	s_addc_u32 s1, s1, s61
	s_waitcnt lgkmcnt(0)
	v_add_f32_e32 v66, v66, v67
	s_add_u32 s0, s0, s67
	ds_bpermute_b32 v67, v115, v66
	s_addc_u32 s1, s1, 0
	s_add_u32 s0, s0, s4
	s_addc_u32 s1, s1, 0
	v_lshl_add_u64 v[84:85], s[0:1], 0, v[156:157]
	v_cvt_pk_bf16_f32 v76, v76, v77
	v_cvt_pk_bf16_f32 v77, v82, v83
	v_cvt_pk_bf16_f32 v68, v70, v71
	v_cvt_pk_bf16_f32 v69, v72, v73
	v_cvt_pk_bf16_f32 v70, v80, v81
	v_cvt_pk_bf16_f32 v71, v78, v79
	global_store_dwordx4 v[84:85], v[74:77], off sc1
	global_store_dwordx4 v[84:85], v[68:71], off offset:1024 sc1
	s_and_saveexec_b64 s[0:1], vcc
	s_cbranch_execz .LBB0_1869
	s_waitcnt lgkmcnt(0)
	v_add_f32_e32 v68, v66, v67
	v_or_b32_e32 v66, s43, v166
	v_ashrrev_i32_e32 v67, 31, v66
	v_lshl_add_u64 v[66:67], v[66:67], 2, s[10:11]
	global_atomic_add_f32 v[66:67], v68, off
.LBB0_1869:
	s_or_b64 exec, exec, s[0:1]
	s_add_i32 s95, s41, 0x80
	s_ashr_i32 s0, s95, 8
	s_ashr_i32 s1, s0, 31
	s_lshl_b32 s8, s95, 7
	s_add_i32 s91, s41, 0x90
	s_add_i32 s43, s41, 0xa0
	s_addk_i32 s41, 0xb0
	s_lshl_b64 s[4:5], s[0:1], 19
	s_and_b32 s96, s8, 0x4000
	s_add_u32 s0, s92, s4
	s_addc_u32 s1, s93, s5
	s_add_u32 s0, s0, s96
	s_addc_u32 s1, s1, 0
	s_waitcnt lgkmcnt(0)
	v_lshl_add_u64 v[66:67], s[0:1], 0, v[156:157]
	s_and_b32 s34, s8, 0x2000
	s_mov_b32 s35, s13
	v_lshl_add_u64 v[66:67], v[66:67], 0, s[34:35]
	global_load_dwordx4 v[94:97], v[66:67], off
	global_load_dwordx4 v[90:93], v[66:67], off offset:1024
	s_ashr_i32 s0, s91, 8
	s_ashr_i32 s1, s0, 31
	s_lshl_b32 s8, s91, 7
	s_lshl_b64 s[46:47], s[0:1], 19
	s_and_b32 s94, s8, 0x4000
	s_add_u32 s0, s92, s46
	s_addc_u32 s1, s93, s47
	s_add_u32 s0, s0, s94
	s_addc_u32 s1, s1, 0
	v_lshl_add_u64 v[66:67], s[0:1], 0, v[156:157]
	s_ashr_i32 s0, s43, 8
	s_and_b32 s12, s8, 0x2800
	s_ashr_i32 s1, s0, 31
	s_lshl_b32 s8, s43, 7
	s_lshl_b64 s[64:65], s[0:1], 19
	s_and_b32 s90, s8, 0x4000
	s_add_u32 s0, s92, s64
	s_addc_u32 s1, s93, s65
	s_add_u32 s0, s0, s90
	v_lshl_add_u64 v[66:67], v[66:67], 0, s[12:13]
	s_addc_u32 s1, s1, 0
	global_load_dwordx4 v[78:81], v[66:67], off
	global_load_dwordx4 v[70:73], v[66:67], off offset:1024
	v_lshl_add_u64 v[66:67], s[0:1], 0, v[156:157]
	s_ashr_i32 s0, s41, 8
	s_and_b32 s66, s8, 0x3000
	s_ashr_i32 s1, s0, 31
	s_lshl_b32 s8, s41, 7
	s_lshl_b64 s[0:1], s[0:1], 19
	s_and_b32 s35, s8, 0x4000
	s_add_u32 s9, s92, s0
	s_addc_u32 s63, s93, s1
	s_add_u32 s62, s9, s35
	s_addc_u32 s63, s63, 0
	s_mov_b32 s67, s13
	v_lshl_add_u64 v[82:83], s[62:63], 0, v[156:157]
	s_and_b32 s62, s8, 0x3800
	s_mov_b32 s63, s13
	v_lshl_add_u64 v[66:67], v[66:67], 0, s[66:67]
	v_lshl_add_u64 v[82:83], v[82:83], 0, s[62:63]
	global_load_dwordx4 v[74:77], v[66:67], off
	s_nop 0
	global_load_dwordx4 v[66:69], v[66:67], off offset:1024
	s_nop 0
	global_load_dwordx4 v[86:89], v[82:83], off
	s_nop 0
	global_load_dwordx4 v[82:85], v[82:83], off offset:1024
	s_add_u32 s4, s50, s4
	s_addc_u32 s5, s51, s5
	s_add_u32 s4, s4, s60
	s_addc_u32 s5, s5, s61
	s_add_u32 s4, s4, s96
	s_addc_u32 s5, s5, 0
	s_add_u32 s4, s4, s34
	s_addc_u32 s5, s5, 0
	s_waitcnt vmcnt(7)
	v_lshlrev_b32_e32 v98, 16, v94
	v_and_b32_e32 v99, 0xffff0000, v94
	v_lshlrev_b32_e32 v94, 16, v95
	v_and_b32_e32 v95, 0xffff0000, v95
	v_lshlrev_b32_e32 v100, 16, v96
	v_and_b32_e32 v101, 0xffff0000, v96
	v_lshlrev_b32_e32 v96, 16, v97
	v_and_b32_e32 v97, 0xffff0000, v97
	v_pk_add_f32 v[64:65], v[64:65], v[94:95]
	v_pk_add_f32 v[62:63], v[62:63], v[98:99]
	v_pk_add_f32 v[94:95], v[60:61], v[96:97]
	v_pk_add_f32 v[96:97], v[58:59], v[100:101]
	v_lshl_add_u64 v[98:99], s[4:5], 0, v[156:157]
	v_cvt_pk_bf16_f32 v58, v62, v63
	v_cvt_pk_bf16_f32 v59, v64, v65
	v_cvt_pk_bf16_f32 v60, v96, v97
	v_cvt_pk_bf16_f32 v61, v94, v95
	global_store_dwordx4 v[98:99], v[58:61], off sc1
	s_waitcnt vmcnt(7)
; #define GAS __attribute__((address_space(1)))
; __device__ __forceinline__ float bflo(unsigned w) { return __uint_as_float(w << 16); }
; __device__ __forceinline__ float bfhi(unsigned w) { return __uint_as_float(w & 0xffff0000u); }
; __device__ __forceinline__ void st_bf8(bf16* p, const f32x4 a, const f32x4 b) { *(GAS v4u*)p = (v4u){pk2(a.x, a.y), pk2(a.z, a.w), pk2(b.x, b.y), pk2(b.z, b.w)}; }
; __device__ __forceinline__ float sq4(const f32x4 a) { return (a.x * a.x + a.y * a.y) + (a.z * a.z + a.w * a.w); }
; __device__ __forceinline__ void row_atomic(float* rs, int row, float s, int fq) { s += __shfl_xor(s, 16); s += __shfl_xor(s, 32); if (fq == 0) atomicAdd(rs + row, s); }
; __device__ __forceinline__ void nt_store4(float* p, f32x4 v) { __builtin_nontemporal_store(v, (f32x4*)p); }
;     template <int NR> __device__ __forceinline__ void rows(const int (&rowb)[NR], int fr, const float (&rstd)[NR], const f32x4 (&a)[NR][2][2], int pn, int wc, int fq) const {
;     ...
;             v4u w[NR][2];
; #pragma unroll
;             for (int i = 0; i < NR; ++i)
; #pragma unroll
;                 for (int bj = 0; bj < 2; ++bj) w[i][bj] = *(const GAS v4u*)((const char*)XN + tile_ub(rowb[i], c0b + 32 * bj, DM) + ltb);
; #pragma unroll
;             for (int i = 0; i < NR; ++i)
; #pragma unroll
;                 for (int bj = 0; bj < 2; ++bj) { bs[i][bj][0] = (f32x4){bflo(w[i][bj].x), bfhi(w[i][bj].x), bflo(w[i][bj].y), bfhi(w[i][bj].y)}; bs[i][bj][1] = (f32x4){bflo(w[i][bj].z), bfhi(w[i][bj].z), bflo(w[i][bj].w), bfhi(w[i][bj].w)}; }
;         }
; #pragma unroll
;         for (int i = 0; i < NR; ++i) {
;             const float rr = rstd[i];
;             float ss = 0.f;
; #pragma unroll
;             for (int bj = 0; bj < 2; ++bj) {
;                 const size_t off = (size_t)(rowb[i] + fr) * DM + c0 + 32 * bj;
;                 const f32x4 u = bs[i][bj][0] + a[i][bj][0] * rr, v = bs[i][bj][1] + a[i][bj][1] * rr;
;                 if (Yout) { nt_store4(Yout + off, u); nt_store4(Yout + off + 4, v); }
;                 if (wr_xn) st_bf8((bf16*)((char*)XN + tile_ub(rowb[i], c0b + 32 * bj, DM) + ltb), u, v);
;                 ss += sq4(u) + sq4(v);
;             }
;             if (rs_out) row_atomic(rs_out, rowb[i] + fr, ss, fq);
	v_lshlrev_b32_e32 v102, 16, v90
	v_and_b32_e32 v103, 0xffff0000, v90
	v_mul_f32_e32 v58, v63, v63
	v_mul_f32_e32 v59, v65, v65
	v_fmac_f32_e32 v58, v62, v62
	v_fmac_f32_e32 v59, v64, v64
	v_add_f32_e32 v58, v58, v59
	v_mul_f32_e32 v59, v97, v97
	v_mul_f32_e32 v60, v95, v95
	v_fmac_f32_e32 v59, v96, v96
	v_fmac_f32_e32 v60, v94, v94
	v_lshlrev_b32_e32 v90, 16, v91
	v_and_b32_e32 v91, 0xffff0000, v91
	v_lshlrev_b32_e32 v104, 16, v92
	v_and_b32_e32 v105, 0xffff0000, v92
	v_lshlrev_b32_e32 v92, 16, v93
	v_and_b32_e32 v93, 0xffff0000, v93
	v_add_f32_e32 v59, v59, v60
	v_add_f32_e32 v62, v59, v58
	v_pk_add_f32 v[56:57], v[56:57], v[90:91]
	v_pk_add_f32 v[54:55], v[54:55], v[102:103]
	v_pk_add_f32 v[58:59], v[52:53], v[92:93]
	v_pk_add_f32 v[60:61], v[50:51], v[104:105]
	v_cvt_pk_bf16_f32 v50, v54, v55
	v_cvt_pk_bf16_f32 v51, v56, v57
	v_cvt_pk_bf16_f32 v52, v60, v61
	v_cvt_pk_bf16_f32 v53, v58, v59
	global_store_dwordx4 v[98:99], v[50:53], off offset:1024 sc1
	s_nop 1
	v_mul_f32_e32 v50, v55, v55
	v_mul_f32_e32 v51, v57, v57
	v_fmac_f32_e32 v50, v54, v54
	v_fmac_f32_e32 v51, v56, v56
	v_add_f32_e32 v50, v50, v51
	v_mul_f32_e32 v51, v61, v61
	v_mul_f32_e32 v52, v59, v59
	v_fmac_f32_e32 v51, v60, v60
	v_fmac_f32_e32 v52, v58, v58
	v_add_f32_e32 v51, v51, v52
	v_add_f32_e32 v50, v51, v50
	v_add_f32_e32 v50, v62, v50
	ds_bpermute_b32 v51, v114, v50
	s_waitcnt lgkmcnt(0)
	v_add_f32_e32 v50, v50, v51
	ds_bpermute_b32 v51, v115, v50
	s_and_saveexec_b64 s[4:5], vcc
	s_cbranch_execz .LBB0_1871
	s_waitcnt lgkmcnt(0)
	v_add_f32_e32 v52, v50, v51
	v_or_b32_e32 v50, s95, v166
	v_ashrrev_i32_e32 v51, 31, v50
	v_lshl_add_u64 v[50:51], v[50:51], 2, s[10:11]
	global_atomic_add_f32 v[50:51], v52, off
.LBB0_1871:
	s_or_b64 exec, exec, s[4:5]
	s_waitcnt vmcnt(7)
	v_lshlrev_b32_e32 v50, 16, v78
	s_waitcnt lgkmcnt(0)
	v_and_b32_e32 v51, 0xffff0000, v78
	v_lshlrev_b32_e32 v52, 16, v79
	v_and_b32_e32 v53, 0xffff0000, v79
	v_lshlrev_b32_e32 v54, 16, v80
	v_and_b32_e32 v55, 0xffff0000, v80
	v_lshlrev_b32_e32 v56, 16, v81
	v_and_b32_e32 v57, 0xffff0000, v81
	v_pk_add_f32 v[46:47], v[46:47], v[50:51]
	v_pk_add_f32 v[48:49], v[48:49], v[52:53]
	v_pk_add_f32 v[50:51], v[44:45], v[56:57]
	v_pk_add_f32 v[44:45], v[42:43], v[54:55]
	v_cvt_pk_bf16_f32 v42, v46, v47
	v_mul_f32_e32 v47, v47, v47
	v_fmac_f32_e32 v47, v46, v46
	v_mul_f32_e32 v46, v49, v49
	v_fmac_f32_e32 v46, v48, v48
	s_waitcnt vmcnt(6)
	v_lshlrev_b32_e32 v58, 16, v70
	v_and_b32_e32 v59, 0xffff0000, v70
	v_lshlrev_b32_e32 v60, 16, v71
	v_and_b32_e32 v61, 0xffff0000, v71
	v_cvt_pk_bf16_f32 v43, v48, v49
	v_add_f32_e32 v46, v47, v46
	v_mul_f32_e32 v47, v45, v45
	v_mul_f32_e32 v48, v51, v51
	v_lshlrev_b32_e32 v62, 16, v72
	v_and_b32_e32 v63, 0xffff0000, v72
	v_fmac_f32_e32 v47, v44, v44
	v_fmac_f32_e32 v48, v50, v50
	v_pk_add_f32 v[40:41], v[40:41], v[60:61]
	v_pk_add_f32 v[38:39], v[38:39], v[58:59]
	v_lshlrev_b32_e32 v64, 16, v73
	v_and_b32_e32 v65, 0xffff0000, v73
	v_add_f32_e32 v47, v47, v48
	v_pk_add_f32 v[48:49], v[34:35], v[62:63]
	v_mul_f32_e32 v34, v39, v39
	v_mul_f32_e32 v35, v41, v41
	v_add_f32_e32 v54, v47, v46
	v_pk_add_f32 v[46:47], v[36:37], v[64:65]
	v_fmac_f32_e32 v34, v38, v38
	v_fmac_f32_e32 v35, v40, v40
	v_add_f32_e32 v34, v34, v35
	v_mul_f32_e32 v35, v49, v49
	v_mul_f32_e32 v36, v47, v47
	v_fmac_f32_e32 v35, v48, v48
	v_fmac_f32_e32 v36, v46, v46
	v_add_f32_e32 v35, v35, v36
	v_add_f32_e32 v34, v35, v34
	v_add_f32_e32 v34, v54, v34
	ds_bpermute_b32 v35, v114, v34
	s_add_u32 s4, s50, s46
	s_addc_u32 s5, s51, s47
	s_add_u32 s4, s4, s60
	s_addc_u32 s5, s5, s61
	s_waitcnt lgkmcnt(0)
	v_add_f32_e32 v34, v34, v35
	s_add_u32 s4, s4, s94
	ds_bpermute_b32 v35, v115, v34
	s_addc_u32 s5, s5, 0
	s_add_u32 s4, s4, s12
	s_addc_u32 s5, s5, 0
	v_lshl_add_u64 v[52:53], s[4:5], 0, v[156:157]
	v_cvt_pk_bf16_f32 v44, v44, v45
	v_cvt_pk_bf16_f32 v45, v50, v51
	v_cvt_pk_bf16_f32 v36, v38, v39
	v_cvt_pk_bf16_f32 v37, v40, v41
	v_cvt_pk_bf16_f32 v38, v48, v49
	v_cvt_pk_bf16_f32 v39, v46, v47
	global_store_dwordx4 v[52:53], v[42:45], off sc1
	global_store_dwordx4 v[52:53], v[36:39], off offset:1024 sc1
	s_and_saveexec_b64 s[4:5], vcc
	s_cbranch_execz .LBB0_1873
	s_waitcnt lgkmcnt(0)
	v_add_f32_e32 v36, v34, v35
	v_or_b32_e32 v34, s91, v166
	v_ashrrev_i32_e32 v35, 31, v34
	v_lshl_add_u64 v[34:35], v[34:35], 2, s[10:11]
	global_atomic_add_f32 v[34:35], v36, off
; #define GAS __attribute__((address_space(1)))
; __device__ __forceinline__ float bflo(unsigned w) { return __uint_as_float(w << 16); }
; __device__ __forceinline__ float bfhi(unsigned w) { return __uint_as_float(w & 0xffff0000u); }
; __device__ __forceinline__ void st_bf8(bf16* p, const f32x4 a, const f32x4 b) { *(GAS v4u*)p = (v4u){pk2(a.x, a.y), pk2(a.z, a.w), pk2(b.x, b.y), pk2(b.z, b.w)}; }
; __device__ __forceinline__ float sq4(const f32x4 a) { return (a.x * a.x + a.y * a.y) + (a.z * a.z + a.w * a.w); }
; __device__ __forceinline__ void row_atomic(float* rs, int row, float s, int fq) { s += __shfl_xor(s, 16); s += __shfl_xor(s, 32); if (fq == 0) atomicAdd(rs + row, s); }
; __device__ __forceinline__ void nt_store4(float* p, f32x4 v) { __builtin_nontemporal_store(v, (f32x4*)p); }
;     template <int NR> __device__ __forceinline__ void rows(const int (&rowb)[NR], int fr, const float (&rstd)[NR], const f32x4 (&a)[NR][2][2], int pn, int wc, int fq) const {
;     ...
;             v4u w[NR][2];
; #pragma unroll
;             for (int i = 0; i < NR; ++i)
; #pragma unroll
;                 for (int bj = 0; bj < 2; ++bj) w[i][bj] = *(const GAS v4u*)((const char*)XN + tile_ub(rowb[i], c0b + 32 * bj, DM) + ltb);
; #pragma unroll
;             for (int i = 0; i < NR; ++i)
; #pragma unroll
;                 for (int bj = 0; bj < 2; ++bj) { bs[i][bj][0] = (f32x4){bflo(w[i][bj].x), bfhi(w[i][bj].x), bflo(w[i][bj].y), bfhi(w[i][bj].y)}; bs[i][bj][1] = (f32x4){bflo(w[i][bj].z), bfhi(w[i][bj].z), bflo(w[i][bj].w), bfhi(w[i][bj].w)}; }
;         }
; #pragma unroll
;         for (int i = 0; i < NR; ++i) {
;             const float rr = rstd[i];
;             float ss = 0.f;
; #pragma unroll
;             for (int bj = 0; bj < 2; ++bj) {
;                 const size_t off = (size_t)(rowb[i] + fr) * DM + c0 + 32 * bj;
;                 const f32x4 u = bs[i][bj][0] + a[i][bj][0] * rr, v = bs[i][bj][1] + a[i][bj][1] * rr;
;                 if (Yout) { nt_store4(Yout + off, u); nt_store4(Yout + off + 4, v); }
;                 if (wr_xn) st_bf8((bf16*)((char*)XN + tile_ub(rowb[i], c0b + 32 * bj, DM) + ltb), u, v);
;                 ss += sq4(u) + sq4(v);
;             }
;             if (rs_out) row_atomic(rs_out, rowb[i] + fr, ss, fq);
.LBB0_1873:
	s_or_b64 exec, exec, s[4:5]
	s_waitcnt vmcnt(7)
	v_lshlrev_b32_e32 v34, 16, v74
	s_waitcnt lgkmcnt(0)
	v_and_b32_e32 v35, 0xffff0000, v74
	v_lshlrev_b32_e32 v36, 16, v75
	v_and_b32_e32 v37, 0xffff0000, v75
	v_lshlrev_b32_e32 v38, 16, v76
	v_and_b32_e32 v39, 0xffff0000, v76
	v_lshlrev_b32_e32 v40, 16, v77
	v_and_b32_e32 v41, 0xffff0000, v77
	v_pk_add_f32 v[30:31], v[30:31], v[34:35]
	v_pk_add_f32 v[32:33], v[32:33], v[36:37]
	v_pk_add_f32 v[34:35], v[28:29], v[40:41]
	v_pk_add_f32 v[28:29], v[26:27], v[38:39]
	v_cvt_pk_bf16_f32 v26, v30, v31
	v_mul_f32_e32 v31, v31, v31
	v_fmac_f32_e32 v31, v30, v30
	v_mul_f32_e32 v30, v33, v33
	v_fmac_f32_e32 v30, v32, v32
	s_waitcnt vmcnt(6)
	v_lshlrev_b32_e32 v42, 16, v66
	v_and_b32_e32 v43, 0xffff0000, v66
	v_lshlrev_b32_e32 v44, 16, v67
	v_and_b32_e32 v45, 0xffff0000, v67
	v_cvt_pk_bf16_f32 v27, v32, v33
	v_add_f32_e32 v30, v31, v30
	v_mul_f32_e32 v31, v29, v29
	v_mul_f32_e32 v32, v35, v35
	v_lshlrev_b32_e32 v46, 16, v68
	v_and_b32_e32 v47, 0xffff0000, v68
	v_fmac_f32_e32 v31, v28, v28
	v_fmac_f32_e32 v32, v34, v34
	v_pk_add_f32 v[24:25], v[24:25], v[44:45]
	v_pk_add_f32 v[22:23], v[22:23], v[42:43]
	v_lshlrev_b32_e32 v48, 16, v69
	v_and_b32_e32 v49, 0xffff0000, v69
	v_add_f32_e32 v31, v31, v32
	v_pk_add_f32 v[32:33], v[18:19], v[46:47]
	v_mul_f32_e32 v18, v23, v23
	v_mul_f32_e32 v19, v25, v25
	v_add_f32_e32 v38, v30, v31
	v_pk_add_f32 v[30:31], v[20:21], v[48:49]
	v_fmac_f32_e32 v18, v22, v22
	v_fmac_f32_e32 v19, v24, v24
	v_add_f32_e32 v18, v18, v19
	v_mul_f32_e32 v19, v33, v33
	v_mul_f32_e32 v20, v31, v31
	v_fmac_f32_e32 v19, v32, v32
	v_fmac_f32_e32 v20, v30, v30
	v_add_f32_e32 v19, v19, v20
	v_add_f32_e32 v18, v18, v19
	v_add_f32_e32 v18, v38, v18
	ds_bpermute_b32 v19, v114, v18
	s_add_u32 s4, s50, s64
	s_addc_u32 s5, s51, s65
	s_add_u32 s4, s4, s60
	s_addc_u32 s5, s5, s61
	s_waitcnt lgkmcnt(0)
	v_add_f32_e32 v18, v18, v19
	s_add_u32 s4, s4, s90
	ds_bpermute_b32 v19, v115, v18
	s_addc_u32 s5, s5, 0
	s_add_u32 s4, s4, s66
	s_addc_u32 s5, s5, 0
	v_lshl_add_u64 v[36:37], s[4:5], 0, v[156:157]
	v_cvt_pk_bf16_f32 v28, v28, v29
	v_cvt_pk_bf16_f32 v29, v34, v35
	v_cvt_pk_bf16_f32 v20, v22, v23
	v_cvt_pk_bf16_f32 v21, v24, v25
	v_cvt_pk_bf16_f32 v22, v32, v33
	v_cvt_pk_bf16_f32 v23, v30, v31
	global_store_dwordx4 v[36:37], v[26:29], off sc1
	global_store_dwordx4 v[36:37], v[20:23], off offset:1024 sc1
	s_and_saveexec_b64 s[4:5], vcc
	s_cbranch_execz .LBB0_1875
	s_waitcnt lgkmcnt(0)
	v_add_f32_e32 v20, v18, v19
	v_or_b32_e32 v18, s43, v166
	v_ashrrev_i32_e32 v19, 31, v18
	v_lshl_add_u64 v[18:19], v[18:19], 2, s[10:11]
	global_atomic_add_f32 v[18:19], v20, off
.LBB0_1875:
	s_or_b64 exec, exec, s[4:5]
	s_waitcnt vmcnt(7)
	v_lshlrev_b32_e32 v18, 16, v86
	s_waitcnt lgkmcnt(0)
	v_and_b32_e32 v19, 0xffff0000, v86
	v_lshlrev_b32_e32 v20, 16, v87
	v_and_b32_e32 v21, 0xffff0000, v87
	v_lshlrev_b32_e32 v22, 16, v88
	v_and_b32_e32 v23, 0xffff0000, v88
	v_lshlrev_b32_e32 v24, 16, v89
	v_and_b32_e32 v25, 0xffff0000, v89
	v_pk_add_f32 v[14:15], v[14:15], v[18:19]
	v_pk_add_f32 v[16:17], v[16:17], v[20:21]
	v_pk_add_f32 v[18:19], v[12:13], v[24:25]
	v_pk_add_f32 v[12:13], v[10:11], v[22:23]
	v_cvt_pk_bf16_f32 v10, v14, v15
	v_mul_f32_e32 v15, v15, v15
	v_fmac_f32_e32 v15, v14, v14
	v_mul_f32_e32 v14, v17, v17
	v_fmac_f32_e32 v14, v16, v16
	s_waitcnt vmcnt(6)
	v_lshlrev_b32_e32 v26, 16, v82
	v_and_b32_e32 v27, 0xffff0000, v82
	v_lshlrev_b32_e32 v28, 16, v83
	v_and_b32_e32 v29, 0xffff0000, v83
	v_cvt_pk_bf16_f32 v11, v16, v17
	v_add_f32_e32 v14, v15, v14
	v_mul_f32_e32 v15, v13, v13
	v_mul_f32_e32 v16, v19, v19
	v_lshlrev_b32_e32 v30, 16, v84
	v_and_b32_e32 v31, 0xffff0000, v84
	v_fmac_f32_e32 v15, v12, v12
	v_fmac_f32_e32 v16, v18, v18
	v_pk_add_f32 v[8:9], v[8:9], v[28:29]
	v_pk_add_f32 v[6:7], v[6:7], v[26:27]
	v_lshlrev_b32_e32 v32, 16, v85
	v_and_b32_e32 v33, 0xffff0000, v85
	v_add_f32_e32 v15, v15, v16
	v_pk_add_f32 v[16:17], v[2:3], v[30:31]
	v_mul_f32_e32 v2, v7, v7
	v_mul_f32_e32 v3, v9, v9
	v_add_f32_e32 v22, v14, v15
	v_pk_add_f32 v[14:15], v[4:5], v[32:33]
	v_fmac_f32_e32 v2, v6, v6
	v_fmac_f32_e32 v3, v8, v8
	v_add_f32_e32 v2, v2, v3
	v_mul_f32_e32 v3, v17, v17
	v_mul_f32_e32 v4, v15, v15
	v_fmac_f32_e32 v3, v16, v16
	v_fmac_f32_e32 v4, v14, v14
	v_add_f32_e32 v3, v3, v4
	v_add_f32_e32 v2, v2, v3
	v_add_f32_e32 v2, v22, v2
	ds_bpermute_b32 v3, v114, v2
	s_add_u32 s0, s50, s0
	s_addc_u32 s1, s51, s1
	s_add_u32 s0, s0, s60
	s_addc_u32 s1, s1, s61
	s_waitcnt lgkmcnt(0)
	v_add_f32_e32 v2, v2, v3
	s_add_u32 s0, s0, s35
	ds_bpermute_b32 v3, v115, v2
	s_addc_u32 s1, s1, 0
	s_add_u32 s0, s0, s62
	s_addc_u32 s1, s1, 0
	v_lshl_add_u64 v[20:21], s[0:1], 0, v[156:157]
	v_cvt_pk_bf16_f32 v12, v12, v13
	v_cvt_pk_bf16_f32 v13, v18, v19
	v_cvt_pk_bf16_f32 v4, v6, v7
	v_cvt_pk_bf16_f32 v5, v8, v9
	v_cvt_pk_bf16_f32 v6, v16, v17
	v_cvt_pk_bf16_f32 v7, v14, v15
	global_store_dwordx4 v[20:21], v[10:13], off sc1
	global_store_dwordx4 v[20:21], v[4:7], off offset:1024 sc1
	s_and_saveexec_b64 s[0:1], vcc
	s_cbranch_execz .LBB0_1877
	s_waitcnt lgkmcnt(0)
	v_add_f32_e32 v4, v2, v3
	v_or_b32_e32 v2, s41, v166
	v_ashrrev_i32_e32 v3, 31, v2
	v_lshl_add_u64 v[2:3], v[2:3], 2, s[10:11]
	global_atomic_add_f32 v[2:3], v4, off

; #define GAS __attribute__((address_space(1)))
; #define WG_BAR() asm volatile("s_waitcnt lgkmcnt(0)\n\ts_barrier" ::: "memory")
; template <class RowEpi, int MTL>
; __device__ __forceinline__ void small_gemm_t(Frame& F, const bf16* A  , const bf16* Bt, int N, int K, const RowEpi& R, int i_lo, int i_hi) {
;     ...
;         const int ar0 = rb * 16 * MTL + fr, ak0 = w * kw + 8 * fq;
;         const int bp0 = pn * 256 + 32 * wc + fr, bk0 = w * kw + 8 * fq;
; #pragma unroll 4
;         for (int k = 0; k < kw; k += 32) {
;             bf16x8 a[MTL], b[2][2];
; #pragma unroll
;             for (int m = 0; m < MTL; ++m) a[m] = *(const GAS bf16x8*)(A + wt_off(ar0 + 16 * m, ak0 + k, K));
; #pragma unroll
;             for (int bj = 0; bj < 2; ++bj)
; #pragma unroll
;                 for (int n = 0; n < 2; ++n) b[bj][n] = *(const GAS bf16x8*)(Bt + wt_off(bp0 + 128 * bj + 16 * n, bk0 + k, K));
; #pragma unroll
;             for (int m = 0; m < MTL; ++m)
; #pragma unroll
;                 for (int bj = 0; bj < 2; ++bj)
; #pragma unroll
;                     for (int n = 0; n < 2; ++n) acc[m][bj][n] = __builtin_amdgcn_mfma_f32_16x16x32_bf16(b[bj][n], a[m], acc[m][bj][n], 0, 0, 0);
;         }
; #pragma unroll
;         for (int m = 0; m < MTL; ++m)
; #pragma unroll
;             for (int bj = 0; bj < 2; ++bj)
; #pragma unroll
;                 for (int n = 0; n < 2; ++n) part[(w * (4 * MTL) + m * 4 + bj * 2 + n) * 64 + lane] = acc[m][bj][n];
;         WG_BAR();
.LBB0_1886:
	s_cmpk_gt_i32 s17, 0xff
	s_mov_b64 s[14:15], -1
	s_cbranch_scc1 .LBB0_1885
	s_ashr_i32 s4, s17, 31
	s_lshr_b32 s4, s4, 28
	s_add_i32 s14, s17, s4
	s_ashr_i32 s4, s14, 4
	s_and_b32 s14, s14, -16
	s_sub_i32 s14, s17, s14
	s_lshl_b32 s18, s14, 11
	s_lshl_b32 s19, s14, 1
	s_and_b32 s15, s14, -16
	s_and_b32 s18, s18, 0x4000
	s_and_b32 s22, s19, 14
	s_add_u32 s18, s48, s18
	s_addc_u32 s19, s49, 0
	s_bfe_i32 s20, s4, 0x180002
	s_ashr_i32 s21, s20, 31
	s_lshl_b32 s23, s4, 2
	s_and_b32 s23, s23, 12
	s_lshl_b64 s[20:21], s[20:21], 19
	s_add_u32 s20, s33, s20
	v_add_u32_e32 v16, s15, v11
	s_addc_u32 s21, s45, s21
	s_waitcnt lgkmcnt(0)
	v_ashrrev_i32_e32 v17, 31, v16
	v_lshlrev_b64 v[20:21], 15, v[16:17]
	s_lshl_b32 s24, s22, 10
	v_lshl_add_u64 v[36:37], s[20:21], 0, v[6:7]
	v_lshl_or_b32 v52, s23, 10, v2
	v_bitop3_b32 v4, v13, s24, v10 bitop3:0xde
	v_mov_b32_e32 v53, v5
	v_lshl_add_u64 v[40:41], s[18:19], 0, v[20:21]
	v_lshl_add_u64 v[54:55], v[36:37], 0, s[12:13]
	v_or_b32_e32 v56, 0x800, v52
	v_mov_b32_e32 v57, v5
	v_lshl_add_u64 v[24:25], v[36:37], 0, v[52:53]
	v_lshl_add_u64 v[20:21], v[40:41], 0, v[4:5]
	v_lshl_add_u64 v[28:29], v[54:55], 0, v[52:53]
	v_lshl_add_u64 v[32:33], v[54:55], 0, v[56:57]
	global_load_dwordx4 v[16:19], v[24:25], off
	s_nop 0
	global_load_dwordx4 v[20:23], v[20:21], off
	s_nop 0
	global_load_dwordx4 v[24:27], v[24:25], off offset:2048
	v_or_b32_e64 v38, 1, s22
	global_load_dwordx4 v[28:31], v[28:29], off
	v_lshlrev_b32_e32 v38, 10, v38
	global_load_dwordx4 v[32:35], v[32:33], off
	v_bitop3_b32 v58, v13, v38, v10 bitop3:0xde
	v_or_b32_e64 v38, 1, s23
	v_mov_b32_e32 v61, v5
	v_lshl_or_b32 v60, v38, 10, v2
	v_lshl_add_u64 v[42:43], v[36:37], 0, v[60:61]
	global_load_dwordx4 v[36:39], v[42:43], off
	v_mov_b32_e32 v59, v5
	v_mov_b32_e32 v63, v5
	v_or_b32_e32 v62, 0x800, v60
	v_lshl_add_u64 v[44:45], v[40:41], 0, v[58:59]
	v_lshl_add_u64 v[48:49], v[54:55], 0, v[60:61]
	v_lshl_add_u64 v[54:55], v[54:55], 0, v[62:63]
	global_load_dwordx4 v[44:47], v[44:45], off
	v_lshl_add_u64 v[64:65], s[20:21], 0, v[8:9]
	global_load_dwordx4 v[40:43], v[42:43], off offset:2048
	v_lshl_add_u64 v[66:67], v[64:65], 0, v[52:53]
	global_load_dwordx4 v[48:51], v[48:49], off
	s_and_b64 vcc, exec, s[6:7]
	s_waitcnt vmcnt(6)
	v_mfma_f32_16x16x32_bf16 v[24:27], v[24:27], v[20:23], 0
	v_mfma_f32_16x16x32_bf16 v[16:19], v[16:19], v[20:23], 0
	s_waitcnt vmcnt(5)
	v_mfma_f32_16x16x32_bf16 v[28:31], v[28:31], v[20:23], 0
	s_waitcnt vmcnt(4)
	v_mfma_f32_16x16x32_bf16 v[20:23], v[32:35], v[20:23], 0
	global_load_dwordx4 v[32:35], v[54:55], off
	s_waitcnt vmcnt(3)
	v_mfma_f32_16x16x32_bf16 v[16:19], v[36:39], v[44:47], v[16:19]
	v_add_u32_e32 v36, s15, v12
	v_ashrrev_i32_e32 v37, 31, v36
	v_lshlrev_b64 v[36:37], 15, v[36:37]
	v_lshl_add_u64 v[54:55], s[18:19], 0, v[36:37]
	global_load_dwordx4 v[36:39], v[66:67], off
	s_waitcnt vmcnt(3)
	v_mfma_f32_16x16x32_bf16 v[24:27], v[40:43], v[44:47], v[24:27]
	v_lshl_add_u64 v[40:41], v[54:55], 0, v[4:5]
	global_load_dwordx4 v[40:43], v[40:41], off
	s_waitcnt vmcnt(3)
	v_mfma_f32_16x16x32_bf16 v[28:31], v[48:51], v[44:47], v[28:31]
	v_lshl_add_u64 v[48:49], v[64:65], 0, s[12:13]
	v_lshl_add_u64 v[50:51], v[64:65], 0, v[60:61]
	s_waitcnt vmcnt(2)
	v_mfma_f32_16x16x32_bf16 v[20:23], v[32:35], v[44:47], v[20:23]
	global_load_dwordx4 v[32:35], v[66:67], off offset:2048
	v_lshl_add_u64 v[44:45], v[48:49], 0, v[52:53]
	s_waitcnt vmcnt(1)
	v_mfma_f32_16x16x32_bf16 v[16:19], v[36:39], v[40:43], v[16:19]
	global_load_dwordx4 v[36:39], v[44:45], off
	v_lshl_add_u64 v[44:45], v[48:49], 0, v[56:57]
	s_waitcnt vmcnt(1)
	v_mfma_f32_16x16x32_bf16 v[24:27], v[32:35], v[40:43], v[24:27]
	global_load_dwordx4 v[32:35], v[44:45], off
	s_waitcnt vmcnt(1)
	v_mfma_f32_16x16x32_bf16 v[28:31], v[36:39], v[40:43], v[28:31]
	global_load_dwordx4 v[36:39], v[50:51], off
	v_lshl_add_u64 v[44:45], v[54:55], 0, v[58:59]
	global_load_dwordx4 v[44:47], v[44:45], off
	s_waitcnt vmcnt(2)
	v_mfma_f32_16x16x32_bf16 v[20:23], v[32:35], v[40:43], v[20:23]
	global_load_dwordx4 v[32:35], v[50:51], off offset:2048
	v_lshl_add_u64 v[40:41], v[48:49], 0, v[60:61]
	s_waitcnt vmcnt(1)
	v_mfma_f32_16x16x32_bf16 v[16:19], v[36:39], v[44:47], v[16:19]
	global_load_dwordx4 v[36:39], v[40:41], off
	v_lshl_add_u64 v[40:41], v[48:49], 0, v[62:63]
	s_waitcnt vmcnt(1)
	v_mfma_f32_16x16x32_bf16 v[24:27], v[32:35], v[44:47], v[24:27]
	global_load_dwordx4 v[32:35], v[40:41], off
	s_waitcnt vmcnt(1)
	v_mfma_f32_16x16x32_bf16 v[28:31], v[36:39], v[44:47], v[28:31]
	s_waitcnt vmcnt(0)
	v_mfma_f32_16x16x32_bf16 v[20:23], v[32:35], v[44:47], v[20:23]
	ds_write_b128 v14, v[16:19]
	s_nop 1
	ds_write_b128 v14, v[24:27] offset:1024
	s_nop 1
	ds_write_b128 v14, v[28:31] offset:2048
	s_nop 0
	ds_write_b128 v14, v[20:23] offset:3072
	s_waitcnt lgkmcnt(0)
	s_barrier
	s_cbranch_vccnz .LBB0_1884
; #define GAS __attribute__((address_space(1)))
;     template <int NR> __device__ __forceinline__ void rows(const int (&rowb)[NR], int fr, const float (&rstd)[NR], const f32x4 (&a)[NR][2][2], int pn, int wc, int fq) const {
;     ...
;             v4u w[NR][2];
; #pragma unroll
;             for (int i = 0; i < NR; ++i)
; #pragma unroll
;                 for (int bj = 0; bj < 2; ++bj) w[i][bj] = *(const GAS v4u*)((const char*)XN + tile_ub(rowb[i], c0b + 32 * bj, DM) + ltb);
; template <class RowEpi, int MTL>
; __device__ __forceinline__ void small_gemm_t(Frame& F, const bf16* A  , const bf16* Bt, int N, int K, const RowEpi& R, int i_lo, int i_hi) {
;     ...
;         if (w < MTL) {
;             f32x4 s[2][2];
; #pragma unroll
;             for (int bj = 0; bj < 2; ++bj)
; #pragma unroll
;                 for (int n = 0; n < 2; ++n) { f32x4 t = (f32x4){0.f, 0.f, 0.f, 0.f};
; #pragma unroll
;                     for (int ww = 0; ww < 8; ++ww) t += part[(ww * (4 * MTL) + w * 4 + bj * 2 + n) * 64 + lane];
;                     s[bj][n] = t; }
;             const int row1[1] = {MP + rb * 16 * MTL + 16 * w}; const f32x4 a1[1][2][2] = {{{s[0][0], s[0][1]}, {s[1][0], s[1][1]}}};
;             const float rr1[1] = {rsp ? rsqrtf(rsv * (1.f / DM) + EPS) : 1.f};
;             R.template rows<1>(row1, fr, rr1, a1, pn, wc, fq);
;         }
	s_lshl_b32 s14, s14, 4
	s_lshl_b32 s15, s4, 6
	s_add_i32 s18, s16, s14
	s_lshr_b32 s4, s18, 8
	s_ashr_i32 s14, s15, 6
	ds_read_b128 v[16:19], v14
	s_ashr_i32 s15, s14, 31
	s_lshl_b64 s[20:21], s[4:5], 19
	s_lshl_b32 s4, s18, 7
	s_lshl_b64 s[14:15], s[14:15], 15
	s_and_b32 s19, s4, 0x4000
	ds_read_b128 v[20:23], v14 offset:4096
	ds_read_b128 v[24:27], v14 offset:1024
	s_add_u32 s20, s50, s20
	s_addc_u32 s21, s51, s21
	s_add_u32 s14, s20, s14
	s_waitcnt lgkmcnt(2)
	v_pk_add_f32 v[32:33], v[18:19], 0 op_sel_hi:[1,0]
	v_pk_add_f32 v[34:35], v[16:17], 0 op_sel_hi:[1,0]
	ds_read_b128 v[16:19], v14 offset:8192
	ds_read_b128 v[28:31], v14 offset:5120
	s_addc_u32 s15, s21, s15
	s_waitcnt lgkmcnt(3)
	v_pk_add_f32 v[36:37], v[32:33], v[22:23]
	v_pk_add_f32 v[38:39], v[34:35], v[20:21]
	ds_read_b128 v[20:23], v14 offset:12288
	ds_read_b128 v[32:35], v14 offset:9216
	s_add_u32 s14, s14, s19
	s_addc_u32 s15, s15, 0
	v_lshl_add_u64 v[40:41], s[14:15], 0, v[2:3]
	s_and_b32 s4, s4, 0x3800
	s_waitcnt lgkmcnt(3)
	v_pk_add_f32 v[36:37], v[36:37], v[18:19]
	v_pk_add_f32 v[38:39], v[38:39], v[16:17]
	v_lshl_add_u64 v[52:53], v[40:41], 0, s[4:5]
	ds_read_b128 v[16:19], v14 offset:13312
	s_waitcnt lgkmcnt(2)
	v_pk_add_f32 v[48:49], v[36:37], v[22:23]
	v_pk_add_f32 v[50:51], v[38:39], v[20:21]
	ds_read_b128 v[20:23], v14 offset:16384
	ds_read_b128 v[36:39], v14 offset:20480
	global_load_dwordx4 v[40:43], v[52:53], off
	ds_read_b128 v[44:47], v14 offset:17408
	v_pk_add_f32 v[26:27], v[26:27], 0 op_sel_hi:[1,0]
	s_waitcnt lgkmcnt(2)
	v_pk_add_f32 v[48:49], v[48:49], v[22:23]
	v_pk_add_f32 v[54:55], v[50:51], v[20:21]
	s_waitcnt lgkmcnt(1)
	v_pk_add_f32 v[60:61], v[48:49], v[38:39]
	v_pk_add_f32 v[62:63], v[54:55], v[36:37]
	global_load_dwordx4 v[36:39], v[52:53], off offset:1024
	ds_read_b128 v[20:23], v14 offset:21504
	ds_read_b128 v[48:51], v14 offset:24576
	v_pk_add_f32 v[24:25], v[24:25], 0 op_sel_hi:[1,0]
	ds_read_b128 v[52:55], v14 offset:28672
	ds_read_b128 v[56:59], v14 offset:25600
	v_pk_add_f32 v[26:27], v[26:27], v[30:31]
	v_pk_add_f32 v[24:25], v[24:25], v[28:29]
	v_pk_add_f32 v[26:27], v[26:27], v[34:35]
	v_pk_add_f32 v[24:25], v[24:25], v[32:33]
	v_pk_add_f32 v[18:19], v[26:27], v[18:19]
	v_pk_add_f32 v[16:17], v[24:25], v[16:17]
	s_waitcnt lgkmcnt(4)
	v_pk_add_f32 v[18:19], v[18:19], v[46:47]
	v_pk_add_f32 v[16:17], v[16:17], v[44:45]
	s_waitcnt lgkmcnt(2)
	v_pk_add_f32 v[60:61], v[60:61], v[50:51]
	v_pk_add_f32 v[62:63], v[62:63], v[48:49]
	ds_read_b128 v[48:51], v14 offset:29696
	v_pk_add_f32 v[18:19], v[18:19], v[22:23]
	v_pk_add_f32 v[16:17], v[16:17], v[20:21]
	s_waitcnt lgkmcnt(1)
	v_pk_add_f32 v[20:21], v[18:19], v[58:59]
	v_pk_add_f32 v[22:23], v[16:17], v[56:57]
	ds_read_b128 v[16:19], v14 offset:2048
	s_waitcnt lgkmcnt(1)
	v_pk_add_f32 v[64:65], v[20:21], v[50:51]
	v_pk_add_f32 v[66:67], v[22:23], v[48:49]
	ds_read_b128 v[20:23], v14 offset:6144
	ds_read_b128 v[24:27], v14 offset:3072
	v_pk_add_f32 v[60:61], v[60:61], v[54:55]
	s_waitcnt lgkmcnt(2)
	v_pk_add_f32 v[32:33], v[18:19], 0 op_sel_hi:[1,0]
	v_pk_add_f32 v[34:35], v[16:17], 0 op_sel_hi:[1,0]
	ds_read_b128 v[16:19], v14 offset:10240
	ds_read_b128 v[28:31], v14 offset:7168
	s_waitcnt lgkmcnt(3)
	v_pk_add_f32 v[44:45], v[32:33], v[22:23]
	v_pk_add_f32 v[46:47], v[34:35], v[20:21]
	ds_read_b128 v[20:23], v14 offset:14336
	ds_read_b128 v[32:35], v14 offset:11264
	s_waitcnt lgkmcnt(3)
	v_pk_add_f32 v[48:49], v[44:45], v[18:19]
	v_pk_add_f32 v[50:51], v[46:47], v[16:17]
	ds_read_b128 v[16:19], v14 offset:18432
	ds_read_b128 v[44:47], v14 offset:15360
	v_pk_add_f32 v[62:63], v[62:63], v[52:53]
	s_waitcnt lgkmcnt(3)
	v_pk_add_f32 v[52:53], v[48:49], v[22:23]
	v_pk_add_f32 v[54:55], v[50:51], v[20:21]
	ds_read_b128 v[20:23], v14 offset:22528
	ds_read_b128 v[48:51], v14 offset:19456
	s_waitcnt lgkmcnt(3)
; __device__ __forceinline__ void st_bf8(bf16* p, const f32x4 a, const f32x4 b) { *(GAS v4u*)p = (v4u){pk2(a.x, a.y), pk2(a.z, a.w), pk2(b.x, b.y), pk2(b.z, b.w)}; }
; __device__ __forceinline__ float sq4(const f32x4 a) { return (a.x * a.x + a.y * a.y) + (a.z * a.z + a.w * a.w); }
; __device__ __forceinline__ void row_atomic(float* rs, int row, float s, int fq) { s += __shfl_xor(s, 16); s += __shfl_xor(s, 32); if (fq == 0) atomicAdd(rs + row, s); }
; __device__ __forceinline__ void nt_store4(float* p, f32x4 v) { __builtin_nontemporal_store(v, (f32x4*)p); }
;     template <int NR> __device__ __forceinline__ void rows(const int (&rowb)[NR], int fr, const float (&rstd)[NR], const f32x4 (&a)[NR][2][2], int pn, int wc, int fq) const {
;     ...
; #pragma unroll
;         for (int i = 0; i < NR; ++i) {
;             const float rr = rstd[i];
;             float ss = 0.f;
; #pragma unroll
;             for (int bj = 0; bj < 2; ++bj) {
;                 const size_t off = (size_t)(rowb[i] + fr) * DM + c0 + 32 * bj;
;                 const f32x4 u = bs[i][bj][0] + a[i][bj][0] * rr, v = bs[i][bj][1] + a[i][bj][1] * rr;
;                 if (Yout) { nt_store4(Yout + off, u); nt_store4(Yout + off + 4, v); }
;                 if (wr_xn) st_bf8((bf16*)((char*)XN + tile_ub(rowb[i], c0b + 32 * bj, DM) + ltb), u, v);
;                 ss += sq4(u) + sq4(v);
;             }
;             if (rs_out) row_atomic(rs_out, rowb[i] + fr, ss, fq);
; template <class RowEpi, int MTL>
; __device__ __forceinline__ void small_gemm_t(Frame& F, const bf16* A  , const bf16* Bt, int N, int K, const RowEpi& R, int i_lo, int i_hi) {
;     ...
;         if (w < MTL) {
;             f32x4 s[2][2];
; #pragma unroll
;             for (int bj = 0; bj < 2; ++bj)
; #pragma unroll
;                 for (int n = 0; n < 2; ++n) { f32x4 t = (f32x4){0.f, 0.f, 0.f, 0.f};
; #pragma unroll
;                     for (int ww = 0; ww < 8; ++ww) t += part[(ww * (4 * MTL) + w * 4 + bj * 2 + n) * 64 + lane];
;                     s[bj][n] = t; }
;             const int row1[1] = {MP + rb * 16 * MTL + 16 * w}; const f32x4 a1[1][2][2] = {{{s[0][0], s[0][1]}, {s[1][0], s[1][1]}}};
;             const float rr1[1] = {rsp ? rsqrtf(rsv * (1.f / DM) + EPS) : 1.f};
;             R.template rows<1>(row1, fr, rr1, a1, pn, wc, fq);
;         }
	v_pk_add_f32 v[56:57], v[52:53], v[18:19]
	v_pk_add_f32 v[58:59], v[54:55], v[16:17]
	ds_read_b128 v[16:19], v14 offset:26624
	ds_read_b128 v[52:55], v14 offset:23552
	v_pk_add_f32 v[26:27], v[26:27], 0 op_sel_hi:[1,0]
	v_pk_add_f32 v[24:25], v[24:25], 0 op_sel_hi:[1,0]
	s_waitcnt lgkmcnt(3)
	v_pk_add_f32 v[68:69], v[56:57], v[22:23]
	v_pk_add_f32 v[70:71], v[58:59], v[20:21]
	ds_read_b128 v[20:23], v14 offset:30720
	ds_read_b128 v[56:59], v14 offset:27648
	v_pk_add_f32 v[26:27], v[26:27], v[30:31]
	v_pk_add_f32 v[24:25], v[24:25], v[28:29]
	s_waitcnt lgkmcnt(3)
	v_pk_add_f32 v[68:69], v[68:69], v[18:19]
	v_pk_add_f32 v[70:71], v[70:71], v[16:17]
	ds_read_b128 v[16:19], v14 offset:31744
	v_pk_add_f32 v[26:27], v[26:27], v[34:35]
	v_pk_add_f32 v[24:25], v[24:25], v[32:33]
	v_pk_add_f32 v[26:27], v[26:27], v[46:47]
	v_pk_add_f32 v[24:25], v[24:25], v[44:45]
	v_pk_add_f32 v[26:27], v[26:27], v[50:51]
	v_pk_add_f32 v[24:25], v[24:25], v[48:49]
	s_waitcnt lgkmcnt(3)
	v_pk_add_f32 v[26:27], v[26:27], v[54:55]
	v_pk_add_f32 v[24:25], v[24:25], v[52:53]
	s_waitcnt lgkmcnt(1)
	v_pk_add_f32 v[26:27], v[26:27], v[58:59]
	v_pk_add_f32 v[24:25], v[24:25], v[56:57]
	s_waitcnt lgkmcnt(0)
	v_pk_add_f32 v[18:19], v[26:27], v[18:19]
	v_pk_add_f32 v[24:25], v[24:25], v[16:17]
	v_pk_add_f32 v[22:23], v[68:69], v[22:23]
	v_pk_add_f32 v[20:21], v[70:71], v[20:21]
	s_add_u32 s14, s14, s4
	s_addc_u32 s15, s15, 0
	s_waitcnt vmcnt(1)
	v_lshlrev_b32_e32 v16, 16, v40
	v_and_b32_e32 v17, 0xffff0000, v40
	v_lshlrev_b32_e32 v26, 16, v41
	v_and_b32_e32 v27, 0xffff0000, v41
	v_pk_add_f32 v[26:27], v[60:61], v[26:27]
	v_pk_add_f32 v[40:41], v[62:63], v[16:17]
	v_lshlrev_b32_e32 v28, 16, v42
	v_and_b32_e32 v29, 0xffff0000, v42
	v_lshlrev_b32_e32 v30, 16, v43
	v_and_b32_e32 v31, 0xffff0000, v43
	v_cvt_pk_bf16_f32 v17, v26, v27
	v_mul_f32_e32 v4, v41, v41
	v_mul_f32_e32 v27, v27, v27
	v_pk_add_f32 v[30:31], v[64:65], v[30:31]
	v_pk_add_f32 v[28:29], v[66:67], v[28:29]
	v_fmac_f32_e32 v4, v40, v40
	v_fmac_f32_e32 v27, v26, v26
	v_add_f32_e32 v4, v4, v27
	v_mul_f32_e32 v26, v29, v29
	v_mul_f32_e32 v27, v31, v31
	s_waitcnt vmcnt(0)
	v_lshlrev_b32_e32 v32, 16, v36
	v_and_b32_e32 v33, 0xffff0000, v36
	v_lshlrev_b32_e32 v34, 16, v37
	v_and_b32_e32 v35, 0xffff0000, v37
	v_fmac_f32_e32 v26, v28, v28
	v_fmac_f32_e32 v27, v30, v30
	v_lshlrev_b32_e32 v36, 16, v38
	v_and_b32_e32 v37, 0xffff0000, v38
	v_lshlrev_b32_e32 v38, 16, v39
	v_and_b32_e32 v39, 0xffff0000, v39
	v_add_f32_e32 v26, v26, v27
	v_pk_add_f32 v[22:23], v[22:23], v[34:35]
	v_pk_add_f32 v[20:21], v[20:21], v[32:33]
	v_add_f32_e32 v4, v4, v26
	v_pk_add_f32 v[26:27], v[18:19], v[38:39]
	v_mul_f32_e32 v18, v21, v21
	v_mul_f32_e32 v19, v23, v23
	v_pk_add_f32 v[24:25], v[24:25], v[36:37]
	v_fmac_f32_e32 v18, v20, v20
	v_fmac_f32_e32 v19, v22, v22
	v_add_f32_e32 v18, v18, v19
	v_mul_f32_e32 v19, v25, v25
	v_mul_f32_e32 v32, v27, v27
	v_fmac_f32_e32 v19, v24, v24
	v_fmac_f32_e32 v32, v26, v26
	v_add_f32_e32 v19, v19, v32
	v_add_f32_e32 v18, v18, v19
	v_and_b32_e32 v19, 64, v15
	v_add_f32_e32 v4, v4, v18
	v_xor_b32_e32 v18, 16, v15
	v_add_u32_e32 v32, 64, v19
	v_cmp_lt_i32_e32 vcc, v18, v32
	v_lshl_add_u64 v[42:43], s[14:15], 0, v[2:3]
	v_cvt_pk_bf16_f32 v16, v40, v41
	v_cndmask_b32_e32 v18, v15, v18, vcc
	v_lshlrev_b32_e32 v18, 2, v18
	ds_bpermute_b32 v33, v18, v4
	v_cvt_pk_bf16_f32 v18, v28, v29
	v_cvt_pk_bf16_f32 v19, v30, v31
	global_store_dwordx4 v[42:43], v[16:19], off sc1
	s_waitcnt lgkmcnt(0)
	s_nop 0
	v_add_f32_e32 v16, v4, v33
	v_xor_b32_e32 v4, 32, v15
	v_cmp_lt_i32_e32 vcc, v4, v32
	v_cvt_pk_bf16_f32 v18, v20, v21
	v_cvt_pk_bf16_f32 v19, v22, v23
	v_cndmask_b32_e32 v4, v15, v4, vcc
	v_lshlrev_b32_e32 v4, 2, v4
	ds_bpermute_b32 v17, v4, v16
	v_cvt_pk_bf16_f32 v20, v24, v25
	v_cvt_pk_bf16_f32 v21, v26, v27
	global_store_dwordx4 v[42:43], v[18:21], off offset:1024 sc1
	s_and_saveexec_b64 s[14:15], s[0:1]
	s_cbranch_execz .LBB0_1883
	v_or_b32_e32 v4, s18, v160
	v_lshl_add_u64 v[18:19], v[4:5], 2, s[10:11]
	s_waitcnt lgkmcnt(0)
	v_add_f32_e32 v4, v16, v17
	global_atomic_add_f32 v[18:19], v4, off
	s_branch .LBB0_1883

; __device__ __forceinline__ unsigned xb_add(unsigned* p, unsigned v) { return __hip_atomic_fetch_add(p, v, __ATOMIC_RELAXED, __HIP_MEMORY_SCOPE_AGENT); }
; __device__ __forceinline__ void xcd_barrier(const XcdBarrier& b) {
;     ...
;         const unsigned old = xb_add(&bar[XB_XSUB(b.x)], 1u);
;         const unsigned gen = old / nloc;
;         if (old + 1u == (gen + 1u) * nloc) {
;             __builtin_amdgcn_fence(__ATOMIC_RELEASE, "agent");
;             asm volatile("s_waitcnt vmcnt(0)" ::: "memory");
;             const unsigned og = xb_add(&bar[XB_TOP], 1u);
;             const unsigned tg = og / nx;
;             if (og + 1u == (tg + 1u) * nx) xb_add(&bar[XB_TOPGEN], 1u);
.LBB0_1923:
	s_andn2_saveexec_b64 s[8:9], s[8:9]
	s_cbranch_execz .LBB0_1943
	s_mov_b64 s[8:9], exec
	s_nop 0
	s_nop 0
	s_waitcnt lgkmcnt(0)
	s_waitcnt vmcnt(0)
	v_mbcnt_lo_u32_b32 v3, s8, 0
	v_mbcnt_hi_u32_b32 v3, s9, v3
	v_cmp_eq_u32_e32 vcc, 0, v3
	s_and_saveexec_b64 s[10:11], vcc
	s_cbranch_execz .LBB0_1926
	s_bcnt1_i32_b64 s3, s[8:9]
	v_mov_b32_e32 v4, 0x7000
	v_mov_b32_e32 v5, s3
	global_atomic_add v4, v4, v5, s[30:31] offset:1024 sc0

; #define GAS __attribute__((address_space(1)))
; template <class RowEpi, int MTL>
; __device__ __forceinline__ void small_gemm_t(Frame& F, const bf16* A  , const bf16* Bt, int N, int K, const RowEpi& R, int i_lo, int i_hi) {
;     ...
;         const int ar0 = rb * 16 * MTL + fr, ak0 = w * kw + 8 * fq;
;         const int bp0 = pn * 256 + 32 * wc + fr, bk0 = w * kw + 8 * fq;
; #pragma unroll 4
;         for (int k = 0; k < kw; k += 32) {
;             bf16x8 a[MTL], b[2][2];
; #pragma unroll
;             for (int m = 0; m < MTL; ++m) a[m] = *(const GAS bf16x8*)(A + wt_off(ar0 + 16 * m, ak0 + k, K));
; #pragma unroll
;             for (int bj = 0; bj < 2; ++bj)
; #pragma unroll
;                 for (int n = 0; n < 2; ++n) b[bj][n] = *(const GAS bf16x8*)(Bt + wt_off(bp0 + 128 * bj + 16 * n, bk0 + k, K));
; #pragma unroll
;             for (int m = 0; m < MTL; ++m)
; #pragma unroll
;                 for (int bj = 0; bj < 2; ++bj)
; #pragma unroll
;                     for (int n = 0; n < 2; ++n) acc[m][bj][n] = __builtin_amdgcn_mfma_f32_16x16x32_bf16(b[bj][n], a[m], acc[m][bj][n], 0, 0, 0);
;         }
.LBB0_1954:
	s_and_b32 s25, s4, -16
	s_lshl_b32 s4, s4, 13
	s_ashr_i32 s24, s5, 2
	s_and_b32 s4, s4, 0x4000
	v_readlane_b32 s5, v245, 11
	s_add_u32 s4, s5, s4
	v_readlane_b32 s5, v245, 12
	s_addc_u32 s5, s5, 0
	s_bfe_i32 s14, s24, 0x180002
	s_or_b32 s27, s10, 16
	s_or_b32 s34, s10, 32
	s_or_b32 s35, s10, 48
	v_or_b32_e32 v4, s10, v10
	s_ashr_i32 s15, s14, 31
	s_lshr_b32 s26, s10, 3
	s_lshr_b32 s27, s27, 3
	s_lshr_b32 s34, s34, 3
	s_lshr_b32 s35, s35, 3
	s_lshl_b32 s36, s24, 2
	s_and_b32 s26, s26, 8
	v_lshlrev_b32_e32 v23, 6, v4
	s_and_b32 s27, s27, 10
	s_and_b32 s34, s34, 12
	s_and_b32 s35, s35, 14
	s_and_b32 s36, s36, 12
	s_lshl_b64 s[14:15], s[14:15], 19
	v_and_b32_e32 v23, 0x3c0, v23
	v_lshlrev_b32_e32 v4, 2, v4
	s_add_u32 s14, s33, s14
	v_and_b32_e32 v134, 32, v4
	s_addc_u32 s15, s45, s15
	v_or_b32_e32 v23, v12, v23
	s_lshl_b32 s37, s26, 10
	v_add_u32_e32 v24, s25, v18
	v_bitop3_b32 v4, v23, s37, v134 bitop3:0xde
	s_lshl_b32 s37, s27, 10
	v_ashrrev_i32_e32 v25, 31, v24
	v_bitop3_b32 v116, v23, s37, v134 bitop3:0xde
	s_lshl_b32 s37, s34, 10
	v_lshlrev_b64 v[24:25], 15, v[24:25]
	v_lshl_add_u64 v[92:93], s[14:15], 0, v[6:7]
	v_lshl_or_b32 v114, s36, 10, v2
	v_bitop3_b32 v118, v23, s37, v134 bitop3:0xde
	s_lshl_b32 s37, s35, 10
	v_lshl_add_u64 v[112:113], s[4:5], 0, v[24:25]
	v_mov_b32_e32 v115, v5
	v_mov_b32_e32 v121, v5
	v_bitop3_b32 v120, v23, s37, v134 bitop3:0xde
	v_mov_b32_e32 v123, v5
	v_lshl_add_u64 v[108:109], v[92:93], 0, s[12:13]
	v_or_b32_e32 v122, 0x800, v114
	v_lshl_add_u64 v[32:33], v[92:93], 0, v[114:115]
	v_lshl_add_u64 v[28:29], v[112:113], 0, v[4:5]
	v_lshl_add_u64 v[60:61], v[112:113], 0, v[120:121]
	v_lshl_add_u64 v[72:73], v[108:109], 0, v[114:115]
	v_lshl_add_u64 v[76:77], v[108:109], 0, v[122:123]
	global_load_dwordx4 v[24:27], v[32:33], off
	s_nop 0
	global_load_dwordx4 v[28:31], v[28:29], off
	s_nop 0
	global_load_dwordx4 v[32:35], v[32:33], off offset:2048
	v_mov_b32_e32 v117, v5
	global_load_dwordx4 v[60:63], v[60:61], off
	v_mov_b32_e32 v119, v5
	global_load_dwordx4 v[72:75], v[72:73], off
	v_lshl_add_u64 v[36:37], v[112:113], 0, v[116:117]
	global_load_dwordx4 v[76:79], v[76:77], off
	v_lshl_add_u64 v[48:49], v[112:113], 0, v[118:119]
	global_load_dwordx4 v[36:39], v[36:37], off
	v_or_b32_e64 v94, 1, s36
	global_load_dwordx4 v[48:51], v[48:49], off
	v_lshl_or_b32 v126, v94, 10, v2
	v_or_b32_e64 v104, 1, s27
	v_mov_b32_e32 v127, v5
	v_or_b32_e64 v88, 1, s26
	v_lshlrev_b32_e32 v104, 10, v104
	v_or_b32_e32 v130, 0x800, v126
	v_mov_b32_e32 v131, v5
	v_lshlrev_b32_e32 v95, 10, v88
	v_lshl_add_u64 v[100:101], v[92:93], 0, v[126:127]
	v_bitop3_b32 v128, v23, v104, v134 bitop3:0xde
	v_lshl_add_u64 v[104:105], v[108:109], 0, v[126:127]
	v_lshl_add_u64 v[108:109], v[108:109], 0, v[130:131]
	v_bitop3_b32 v124, v23, v95, v134 bitop3:0xde
	global_load_dwordx4 v[92:95], v[100:101], off
	v_mov_b32_e32 v125, v5
	global_load_dwordx4 v[104:107], v[104:105], off
	v_lshl_add_u64 v[96:97], v[112:113], 0, v[124:125]
	global_load_dwordx4 v[100:103], v[100:101], off offset:2048
	v_mov_b32_e32 v129, v5
	global_load_dwordx4 v[108:111], v[108:109], off
	v_or_b32_e64 v135, 1, s35
	global_load_dwordx4 v[96:99], v[96:97], off
	s_waitcnt vmcnt(10)
	v_mfma_f32_16x16x32_bf16 v[44:47], v[32:35], v[28:31], 0
	v_lshlrev_b32_e32 v135, 10, v135
	v_mov_b32_e32 v133, v5
	s_and_b64 vcc, exec, s[0:1]
	v_mfma_f32_16x16x32_bf16 v[40:43], v[24:27], v[28:31], 0
	s_waitcnt vmcnt(6)
	v_mfma_f32_16x16x32_bf16 v[52:55], v[24:27], v[36:39], 0
	v_mfma_f32_16x16x32_bf16 v[56:59], v[32:35], v[36:39], 0
	s_waitcnt vmcnt(5)
	v_mfma_f32_16x16x32_bf16 v[64:67], v[24:27], v[48:51], 0
	v_mfma_f32_16x16x32_bf16 v[68:71], v[32:35], v[48:51], 0
	v_mfma_f32_16x16x32_bf16 v[24:27], v[24:27], v[60:63], 0
	v_mfma_f32_16x16x32_bf16 v[32:35], v[32:35], v[60:63], 0
	v_mfma_f32_16x16x32_bf16 v[80:83], v[72:75], v[28:31], 0
	v_mfma_f32_16x16x32_bf16 v[28:31], v[76:79], v[28:31], 0
	v_mfma_f32_16x16x32_bf16 v[84:87], v[72:75], v[36:39], 0
	v_mfma_f32_16x16x32_bf16 v[36:39], v[76:79], v[36:39], 0
	v_mfma_f32_16x16x32_bf16 v[88:91], v[72:75], v[48:51], 0
	v_mfma_f32_16x16x32_bf16 v[48:51], v[76:79], v[48:51], 0
	v_mfma_f32_16x16x32_bf16 v[72:75], v[72:75], v[60:63], 0
	v_mfma_f32_16x16x32_bf16 v[60:63], v[76:79], v[60:63], 0
	v_lshl_add_u64 v[76:77], v[112:113], 0, v[128:129]
	global_load_dwordx4 v[76:79], v[76:77], off
	s_waitcnt vmcnt(1)
	v_mfma_f32_16x16x32_bf16 v[40:43], v[92:95], v[96:99], v[40:43]
	v_mfma_f32_16x16x32_bf16 v[44:47], v[100:103], v[96:99], v[44:47]
	v_mfma_f32_16x16x32_bf16 v[80:83], v[104:107], v[96:99], v[80:83]
	v_mfma_f32_16x16x32_bf16 v[28:31], v[108:111], v[96:99], v[28:31]
	v_or_b32_e64 v96, 1, s34
	v_lshlrev_b32_e32 v96, 10, v96
	v_bitop3_b32 v132, v23, v96, v134 bitop3:0xde
	v_bitop3_b32 v134, v23, v135, v134 bitop3:0xde
	v_mov_b32_e32 v135, v5
	v_lshl_add_u64 v[96:97], v[112:113], 0, v[132:133]
	v_lshl_add_u64 v[112:113], v[112:113], 0, v[134:135]
	global_load_dwordx4 v[96:99], v[96:97], off
	s_waitcnt vmcnt(1)
	v_mfma_f32_16x16x32_bf16 v[52:55], v[92:95], v[76:79], v[52:55]
	v_mfma_f32_16x16x32_bf16 v[56:59], v[100:103], v[76:79], v[56:59]
	v_mfma_f32_16x16x32_bf16 v[84:87], v[104:107], v[76:79], v[84:87]
	v_mfma_f32_16x16x32_bf16 v[36:39], v[108:111], v[76:79], v[36:39]
	global_load_dwordx4 v[76:79], v[112:113], off
	v_lshl_add_u64 v[112:113], s[14:15], 0, v[8:9]
	s_waitcnt vmcnt(1)
	v_mfma_f32_16x16x32_bf16 v[64:67], v[92:95], v[96:99], v[64:67]
	s_waitcnt vmcnt(0)
; #define GAS __attribute__((address_space(1)))
; #define WG_BAR() asm volatile("s_waitcnt lgkmcnt(0)\n\ts_barrier" ::: "memory")
; template <class RowEpi, int MTL>
; __device__ __forceinline__ void small_gemm_t(Frame& F, const bf16* A  , const bf16* Bt, int N, int K, const RowEpi& R, int i_lo, int i_hi) {
;     ...
;         for (int k = 0; k < kw; k += 32) {
;             bf16x8 a[MTL], b[2][2];
; #pragma unroll
;             for (int m = 0; m < MTL; ++m) a[m] = *(const GAS bf16x8*)(A + wt_off(ar0 + 16 * m, ak0 + k, K));
; #pragma unroll
;             for (int bj = 0; bj < 2; ++bj)
; #pragma unroll
;                 for (int n = 0; n < 2; ++n) b[bj][n] = *(const GAS bf16x8*)(Bt + wt_off(bp0 + 128 * bj + 16 * n, bk0 + k, K));
; #pragma unroll
;             for (int m = 0; m < MTL; ++m)
; #pragma unroll
;                 for (int bj = 0; bj < 2; ++bj)
; #pragma unroll
;                     for (int n = 0; n < 2; ++n) acc[m][bj][n] = __builtin_amdgcn_mfma_f32_16x16x32_bf16(b[bj][n], a[m], acc[m][bj][n], 0, 0, 0);
;         }
; #pragma unroll
;         for (int m = 0; m < MTL; ++m)
; #pragma unroll
;             for (int bj = 0; bj < 2; ++bj)
; #pragma unroll
;                 for (int n = 0; n < 2; ++n) part[(w * (4 * MTL) + m * 4 + bj * 2 + n) * 64 + lane] = acc[m][bj][n];
;         WG_BAR();
	v_mfma_f32_16x16x32_bf16 v[24:27], v[92:95], v[76:79], v[24:27]
	v_add_u32_e32 v92, s25, v19
	v_ashrrev_i32_e32 v93, 31, v92
	v_mfma_f32_16x16x32_bf16 v[68:71], v[100:103], v[96:99], v[68:71]
	v_mfma_f32_16x16x32_bf16 v[88:91], v[104:107], v[96:99], v[88:91]
	v_mfma_f32_16x16x32_bf16 v[48:51], v[108:111], v[96:99], v[48:51]
	v_lshlrev_b64 v[96:97], 15, v[92:93]
	v_lshl_add_u64 v[136:137], s[4:5], 0, v[96:97]
	v_lshl_add_u64 v[96:97], v[136:137], 0, v[4:5]
	v_mfma_f32_16x16x32_bf16 v[32:35], v[100:103], v[76:79], v[32:35]
	v_lshl_add_u64 v[100:101], v[112:113], 0, v[114:115]
	global_load_dwordx4 v[92:95], v[100:101], off
	s_nop 0
	global_load_dwordx4 v[96:99], v[96:97], off
	s_nop 0
	global_load_dwordx4 v[100:103], v[100:101], off offset:2048
	v_mfma_f32_16x16x32_bf16 v[72:75], v[104:107], v[76:79], v[72:75]
	v_mfma_f32_16x16x32_bf16 v[60:63], v[108:111], v[76:79], v[60:63]
	v_lshl_add_u64 v[76:77], v[136:137], 0, v[116:117]
	v_lshl_add_u64 v[116:117], v[112:113], 0, s[12:13]
	v_lshl_add_u64 v[104:105], v[116:117], 0, v[114:115]
	v_lshl_add_u64 v[108:109], v[116:117], 0, v[122:123]
	global_load_dwordx4 v[104:107], v[104:105], off
	s_waitcnt vmcnt(2)
	v_mfma_f32_16x16x32_bf16 v[40:43], v[92:95], v[96:99], v[40:43]
	global_load_dwordx4 v[108:111], v[108:109], off
	v_lshl_add_u64 v[114:115], v[136:137], 0, v[120:121]
	global_load_dwordx4 v[76:79], v[76:77], off
	s_waitcnt vmcnt(3)
	v_mfma_f32_16x16x32_bf16 v[44:47], v[100:103], v[96:99], v[44:47]
	v_lshl_add_u64 v[112:113], v[112:113], 0, v[126:127]
	s_waitcnt vmcnt(2)
	v_mfma_f32_16x16x32_bf16 v[80:83], v[104:107], v[96:99], v[80:83]
	s_waitcnt vmcnt(1)
	v_mfma_f32_16x16x32_bf16 v[28:31], v[108:111], v[96:99], v[28:31]
	v_lshl_add_u64 v[96:97], v[136:137], 0, v[118:119]
	global_load_dwordx4 v[96:99], v[96:97], off
	s_waitcnt vmcnt(1)
	v_mfma_f32_16x16x32_bf16 v[52:55], v[92:95], v[76:79], v[52:55]
	v_mfma_f32_16x16x32_bf16 v[56:59], v[100:103], v[76:79], v[56:59]
	v_mfma_f32_16x16x32_bf16 v[84:87], v[104:107], v[76:79], v[84:87]
	v_mfma_f32_16x16x32_bf16 v[36:39], v[108:111], v[76:79], v[36:39]
	global_load_dwordx4 v[76:79], v[114:115], off
	s_waitcnt vmcnt(1)
	v_mfma_f32_16x16x32_bf16 v[88:91], v[104:107], v[96:99], v[88:91]
	s_waitcnt vmcnt(0)
	v_mfma_f32_16x16x32_bf16 v[72:75], v[104:107], v[76:79], v[72:75]
	v_lshl_add_u64 v[104:105], v[136:137], 0, v[124:125]
	v_mfma_f32_16x16x32_bf16 v[64:67], v[92:95], v[96:99], v[64:67]
	v_mfma_f32_16x16x32_bf16 v[68:71], v[100:103], v[96:99], v[68:71]
	v_mfma_f32_16x16x32_bf16 v[48:51], v[108:111], v[96:99], v[48:51]
	v_mfma_f32_16x16x32_bf16 v[24:27], v[92:95], v[76:79], v[24:27]
	global_load_dwordx4 v[92:95], v[112:113], off
	v_mfma_f32_16x16x32_bf16 v[32:35], v[100:103], v[76:79], v[32:35]
	global_load_dwordx4 v[96:99], v[104:105], off
	global_load_dwordx4 v[100:103], v[112:113], off offset:2048
	v_lshl_add_u64 v[104:105], v[116:117], 0, v[126:127]
	global_load_dwordx4 v[104:107], v[104:105], off
	v_mfma_f32_16x16x32_bf16 v[60:63], v[108:111], v[76:79], v[60:63]
	v_lshl_add_u64 v[108:109], v[116:117], 0, v[130:131]
	global_load_dwordx4 v[108:111], v[108:109], off
	v_lshl_add_u64 v[76:77], v[136:137], 0, v[128:129]
	global_load_dwordx4 v[76:79], v[76:77], off
	s_waitcnt vmcnt(4)
	v_mfma_f32_16x16x32_bf16 v[40:43], v[92:95], v[96:99], v[40:43]
	v_lshl_add_u64 v[112:113], v[136:137], 0, v[134:135]
	s_waitcnt vmcnt(3)
	v_mfma_f32_16x16x32_bf16 v[44:47], v[100:103], v[96:99], v[44:47]
	s_waitcnt vmcnt(2)
	v_mfma_f32_16x16x32_bf16 v[80:83], v[104:107], v[96:99], v[80:83]
	s_waitcnt vmcnt(1)
	v_mfma_f32_16x16x32_bf16 v[28:31], v[108:111], v[96:99], v[28:31]
	v_lshl_add_u64 v[96:97], v[136:137], 0, v[132:133]
	global_load_dwordx4 v[96:99], v[96:97], off
	s_waitcnt vmcnt(1)
	v_mfma_f32_16x16x32_bf16 v[52:55], v[92:95], v[76:79], v[52:55]
	v_mfma_f32_16x16x32_bf16 v[56:59], v[100:103], v[76:79], v[56:59]
	v_mfma_f32_16x16x32_bf16 v[84:87], v[104:107], v[76:79], v[84:87]
	v_mfma_f32_16x16x32_bf16 v[36:39], v[108:111], v[76:79], v[36:39]
	global_load_dwordx4 v[76:79], v[112:113], off
	ds_write_b128 v21, v[40:43]
	ds_write_b128 v21, v[44:47] offset:1024
	ds_write_b128 v21, v[80:83] offset:2048
	ds_write_b128 v21, v[28:31] offset:3072
	ds_write_b128 v21, v[52:55] offset:4096
	ds_write_b128 v21, v[56:59] offset:5120
	s_waitcnt vmcnt(1)
	v_mfma_f32_16x16x32_bf16 v[68:71], v[100:103], v[96:99], v[68:71]
	s_waitcnt vmcnt(0)
	v_mfma_f32_16x16x32_bf16 v[24:27], v[92:95], v[76:79], v[24:27]
	v_mfma_f32_16x16x32_bf16 v[88:91], v[104:107], v[96:99], v[88:91]
	v_mfma_f32_16x16x32_bf16 v[28:31], v[100:103], v[76:79], v[32:35]
	v_mfma_f32_16x16x32_bf16 v[64:67], v[92:95], v[96:99], v[64:67]
	ds_write_b128 v21, v[84:87] offset:6144
	ds_write_b128 v21, v[36:39] offset:7168
	s_nop 5
	ds_write_b128 v21, v[64:67] offset:8192
	v_mfma_f32_16x16x32_bf16 v[40:43], v[108:111], v[96:99], v[48:51]
	ds_write_b128 v21, v[68:71] offset:9216
	ds_write_b128 v21, v[88:91] offset:10240
	s_nop 5
	ds_write_b128 v21, v[40:43] offset:11264
	v_mfma_f32_16x16x32_bf16 v[32:35], v[104:107], v[76:79], v[72:75]
	ds_write_b128 v21, v[24:27] offset:12288
	ds_write_b128 v21, v[28:31] offset:13312
	s_nop 5
	ds_write_b128 v21, v[32:35] offset:14336
	v_mfma_f32_16x16x32_bf16 v[24:27], v[108:111], v[76:79], v[60:63]
	s_nop 7
	ds_write_b128 v21, v[24:27] offset:15360
	s_waitcnt lgkmcnt(0)
	s_barrier
	s_cbranch_vccnz .LBB0_1949
; template <class RowEpi, int MTL>
; __device__ __forceinline__ void small_gemm_t(Frame& F, const bf16* A  , const bf16* Bt, int N, int K, const RowEpi& R, int i_lo, int i_hi) {
;     ...
;         if (w < MTL) {
;             f32x4 s[2][2];
; #pragma unroll
;             for (int bj = 0; bj < 2; ++bj)
; #pragma unroll
;                 for (int n = 0; n < 2; ++n) { f32x4 t = (f32x4){0.f, 0.f, 0.f, 0.f};
; #pragma unroll
;                     for (int ww = 0; ww < 8; ++ww) t += part[(ww * (4 * MTL) + w * 4 + bj * 2 + n) * 64 + lane];
;                     s[bj][n] = t; }
	v_add_u32_e32 v4, s16, v11
	ds_read_b128 v[24:27], v4
	ds_read_b128 v[28:31], v4 offset:16384
	ds_read_b128 v[32:35], v4 offset:1024
	v_add_u32_e32 v23, s16, v13
	s_lshl_b32 s4, s24, 6
	s_add_i32 s24, s17, s10
	s_waitcnt lgkmcnt(2)
	v_pk_add_f32 v[40:41], v[26:27], 0 op_sel_hi:[1,0]
	v_pk_add_f32 v[42:43], v[24:25], 0 op_sel_hi:[1,0]
	ds_read_b128 v[24:27], v4 offset:32768
	ds_read_b128 v[36:39], v4 offset:17408
	s_waitcnt lgkmcnt(3)
	v_pk_add_f32 v[40:41], v[40:41], v[30:31]
	v_pk_add_f32 v[44:45], v[42:43], v[28:29]
	ds_read_b128 v[28:31], v4 offset:33792
	s_waitcnt lgkmcnt(2)
	v_pk_add_f32 v[48:49], v[40:41], v[26:27]
	ds_read_b128 v[40:43], v4 offset:49152
	v_pk_add_f32 v[50:51], v[44:45], v[24:25]
	ds_read_b128 v[24:27], v23
	ds_read_b128 v[44:47], v4 offset:50176
	v_add_u32_e32 v23, s16, v14
	v_cmp_gt_f32_e32 vcc, s21, v22
	s_waitcnt lgkmcnt(2)
	v_pk_add_f32 v[48:49], v[48:49], v[42:43]
	v_pk_add_f32 v[50:51], v[50:51], v[40:41]
	ds_read_b128 v[40:43], v23
	v_add_u32_e32 v23, s16, v15
	s_waitcnt lgkmcnt(2)
	v_pk_add_f32 v[52:53], v[48:49], v[26:27]
	v_pk_add_f32 v[54:55], v[50:51], v[24:25]
	ds_read_b128 v[24:27], v23
	v_add_u32_e32 v23, s16, v16
	ds_read_b128 v[48:51], v23
	s_waitcnt lgkmcnt(2)
	v_pk_add_f32 v[42:43], v[52:53], v[42:43]
	v_pk_add_f32 v[40:41], v[54:55], v[40:41]
	s_waitcnt lgkmcnt(1)
	v_pk_add_f32 v[26:27], v[42:43], v[26:27]
	v_pk_add_f32 v[24:25], v[40:41], v[24:25]
	s_waitcnt lgkmcnt(0)
	v_pk_add_f32 v[52:53], v[26:27], v[50:51]
	v_pk_add_f32 v[54:55], v[24:25], v[48:49]
	v_pk_add_f32 v[24:25], v[34:35], 0 op_sel_hi:[1,0]
	v_pk_add_f32 v[26:27], v[32:33], 0 op_sel_hi:[1,0]
	v_pk_add_f32 v[24:25], v[24:25], v[38:39]
	v_pk_add_f32 v[26:27], v[26:27], v[36:37]
	v_add_u32_e32 v23, s18, v13
	v_pk_add_f32 v[30:31], v[24:25], v[30:31]
	v_pk_add_f32 v[28:29], v[26:27], v[28:29]
	ds_read_b128 v[24:27], v23
	v_add_u32_e32 v23, s18, v14
	v_pk_add_f32 v[32:33], v[30:31], v[46:47]
	v_pk_add_f32 v[34:35], v[28:29], v[44:45]
	ds_read_b128 v[28:31], v23
	v_add_u32_e32 v23, s18, v15
	s_waitcnt lgkmcnt(1)
	v_pk_add_f32 v[32:33], v[32:33], v[26:27]
	v_pk_add_f32 v[34:35], v[34:35], v[24:25]
	ds_read_b128 v[24:27], v23
	v_add_u32_e32 v23, s18, v16
	s_waitcnt lgkmcnt(1)
	v_pk_add_f32 v[36:37], v[32:33], v[30:31]
	ds_read_b128 v[30:33], v23
	v_pk_add_f32 v[28:29], v[34:35], v[28:29]
	s_waitcnt lgkmcnt(1)
	v_pk_add_f32 v[34:35], v[36:37], v[26:27]
	v_pk_add_f32 v[28:29], v[28:29], v[24:25]
	ds_read_b128 v[24:27], v4 offset:2048
	s_waitcnt lgkmcnt(1)
	v_pk_add_f32 v[56:57], v[34:35], v[32:33]
	v_pk_add_f32 v[58:59], v[28:29], v[30:31]
	ds_read_b128 v[28:31], v4 offset:18432
	ds_read_b128 v[32:35], v4 offset:3072
	v_add_u32_e32 v23, s19, v13
	s_waitcnt lgkmcnt(2)
	v_pk_add_f32 v[40:41], v[26:27], 0 op_sel_hi:[1,0]
	v_pk_add_f32 v[42:43], v[24:25], 0 op_sel_hi:[1,0]
	ds_read_b128 v[24:27], v4 offset:34816
	ds_read_b128 v[36:39], v4 offset:19456
	s_waitcnt lgkmcnt(3)
	v_pk_add_f32 v[40:41], v[40:41], v[30:31]
	v_pk_add_f32 v[44:45], v[42:43], v[28:29]
	ds_read_b128 v[28:31], v4 offset:35840
	s_waitcnt lgkmcnt(2)
	v_pk_add_f32 v[48:49], v[40:41], v[26:27]
	ds_read_b128 v[40:43], v4 offset:51200
	v_pk_add_f32 v[50:51], v[44:45], v[24:25]
	ds_read_b128 v[24:27], v23
	ds_read_b128 v[44:47], v4 offset:52224
	v_add_u32_e32 v4, s19, v14
	s_lshr_b32 s10, s24, 8
	s_waitcnt lgkmcnt(2)
	v_pk_add_f32 v[48:49], v[48:49], v[42:43]
	v_pk_add_f32 v[50:51], v[50:51], v[40:41]
	ds_read_b128 v[40:43], v4
	v_add_u32_e32 v4, s19, v15
	s_waitcnt lgkmcnt(2)
	v_pk_add_f32 v[60:61], v[48:49], v[26:27]
	v_pk_add_f32 v[62:63], v[50:51], v[24:25]
	ds_read_b128 v[24:27], v4
	v_add_u32_e32 v4, s19, v16
	ds_read_b128 v[48:51], v4
	s_waitcnt lgkmcnt(2)
; __device__ __forceinline__ unsigned lane_tb(int fr, int fq) { return (unsigned)((fr * 64 + fq * 16) ^ ((fr >> 3) << 5)); }
; __device__ __forceinline__ void st_bf8(bf16* p, const f32x4 a, const f32x4 b) { *(GAS v4u*)p = (v4u){pk2(a.x, a.y), pk2(a.z, a.w), pk2(b.x, b.y), pk2(b.z, b.w)}; }
;     template <int NR> __device__ __forceinline__ void rows(const int (&rowb)[NR], int fr, const float (&rstd)[NR], const f32x4 (&a)[NR][2][2], int pn, int wc, int fq) const {
; #pragma unroll
;         for (int i = 0; i < NR; ++i) {
;             const float rr = rstd[i];
; #pragma unroll
;             for (int bj = 0; bj < 2; ++bj) {
;                 f32x4 u = a[i][bj][0] * rr, v = a[i][bj][1] * rr;
; #pragma unroll
;                 for (int j = 0; j < 4; ++j) { const float p = fmaxf(u[j], 0.f), q = fmaxf(v[j], 0.f); u[j] = p * p; v[j] = q * q; }
;                 st_bf8((bf16*)((char*)H + tile_ub(rowb[i], (pn << 8) + 64 * wc + 32 * bj, FF) + lane_tb(fr, fq)), u, v);
;             }
;         }
;     }
; template <class RowEpi, int MTL>
; __device__ __forceinline__ void small_gemm_t(Frame& F, const bf16* A  , const bf16* Bt, int N, int K, const RowEpi& R, int i_lo, int i_hi) {
;     ...
;                     for (int ww = 0; ww < 8; ++ww) t += part[(ww * (4 * MTL) + w * 4 + bj * 2 + n) * 64 + lane];
;                     s[bj][n] = t; }
;             const int row1[1] = {MP + rb * 16 * MTL + 16 * w}; const f32x4 a1[1][2][2] = {{{s[0][0], s[0][1]}, {s[1][0], s[1][1]}}};
;             const float rr1[1] = {rsp ? rsqrtf(rsv * (1.f / DM) + EPS) : 1.f};
;             R.template rows<1>(row1, fr, rr1, a1, pn, wc, fq);
;         }
	v_pk_add_f32 v[42:43], v[60:61], v[42:43]
	v_pk_add_f32 v[40:41], v[62:63], v[40:41]
	s_waitcnt lgkmcnt(1)
	v_pk_add_f32 v[26:27], v[42:43], v[26:27]
	v_pk_add_f32 v[24:25], v[40:41], v[24:25]
	s_waitcnt lgkmcnt(0)
	v_pk_add_f32 v[40:41], v[26:27], v[50:51]
	v_pk_add_f32 v[42:43], v[24:25], v[48:49]
	v_pk_add_f32 v[24:25], v[34:35], 0 op_sel_hi:[1,0]
	v_pk_add_f32 v[26:27], v[32:33], 0 op_sel_hi:[1,0]
	v_pk_add_f32 v[24:25], v[24:25], v[38:39]
	v_pk_add_f32 v[26:27], v[26:27], v[36:37]
	v_add_u32_e32 v4, s20, v13
	v_pk_add_f32 v[30:31], v[24:25], v[30:31]
	v_pk_add_f32 v[28:29], v[26:27], v[28:29]
	ds_read_b128 v[24:27], v4
	v_add_u32_e32 v4, s20, v14
	v_pk_add_f32 v[32:33], v[30:31], v[46:47]
	v_pk_add_f32 v[34:35], v[28:29], v[44:45]
	ds_read_b128 v[28:31], v4
	v_add_u32_e32 v4, s20, v15
	s_waitcnt lgkmcnt(1)
	v_pk_add_f32 v[32:33], v[32:33], v[26:27]
	v_pk_add_f32 v[34:35], v[34:35], v[24:25]
	ds_read_b128 v[24:27], v4
	v_add_u32_e32 v4, s20, v16
	s_waitcnt lgkmcnt(1)
	v_pk_add_f32 v[32:33], v[32:33], v[30:31]
	v_pk_add_f32 v[34:35], v[34:35], v[28:29]
	ds_read_b128 v[28:31], v4
	v_mul_f32_e32 v4, 0x4b800000, v22
	s_ashr_i32 s4, s4, 6
	v_cndmask_b32_e32 v4, v22, v4, vcc
	s_ashr_i32 s5, s4, 31
	s_lshl_b64 s[14:15], s[10:11], 21
	s_lshl_b32 s10, s24, 7
	v_rsq_f32_e32 v4, v4
	s_lshl_b64 s[4:5], s[4:5], 15
	s_and_b32 s24, s10, 0x4000
	s_and_b32 s10, s10, 0x3800
	s_add_u32 s14, s52, s14
	s_addc_u32 s15, s53, s15
	s_add_u32 s4, s14, s4
	v_mul_f32_e32 v22, 0x45800000, v4
	s_addc_u32 s5, s15, s5
	s_waitcnt lgkmcnt(1)
	v_pk_add_f32 v[26:27], v[32:33], v[26:27]
	v_pk_add_f32 v[24:25], v[34:35], v[24:25]
	v_cndmask_b32_e32 v4, v4, v22, vcc
	s_add_u32 s4, s4, s24
	s_waitcnt lgkmcnt(0)
	v_pk_add_f32 v[26:27], v[26:27], v[30:31]
	v_pk_add_f32 v[28:29], v[24:25], v[28:29]
	v_pk_mul_f32 v[22:23], v[4:5], v[52:53] op_sel_hi:[0,1]
	v_pk_mul_f32 v[24:25], v[4:5], v[54:55] op_sel_hi:[0,1]
	v_pk_mul_f32 v[30:31], v[4:5], v[56:57] op_sel_hi:[0,1]
	v_pk_mul_f32 v[32:33], v[4:5], v[58:59] op_sel_hi:[0,1]
	s_addc_u32 s5, s5, 0
	v_max_f32_e32 v24, 0, v24
	v_max_f32_e32 v32, 0, v32
	v_max_f32_e32 v25, 0, v25
	v_max_f32_e32 v33, 0, v33
	v_max_f32_e32 v22, 0, v22
	v_max_f32_e32 v30, 0, v30
	v_max_f32_e32 v23, 0, v23
	v_max_f32_e32 v31, 0, v31
	s_add_u32 s4, s4, s10
	v_pk_mul_f32 v[24:25], v[24:25], v[24:25]
	v_pk_mul_f32 v[32:33], v[32:33], v[32:33]
	v_pk_mul_f32 v[34:35], v[22:23], v[22:23]
	v_pk_mul_f32 v[30:31], v[30:31], v[30:31]
	s_addc_u32 s5, s5, 0
	v_lshl_add_u64 v[36:37], s[4:5], 0, v[2:3]
	v_cvt_pk_bf16_f32 v22, v24, v25
	v_cvt_pk_bf16_f32 v23, v34, v35
	v_cvt_pk_bf16_f32 v24, v32, v33
	v_cvt_pk_bf16_f32 v25, v30, v31
	global_store_dwordx4 v[36:37], v[22:25], off sc1
	v_pk_mul_f32 v[26:27], v[4:5], v[26:27] op_sel_hi:[0,1]
	v_pk_mul_f32 v[28:29], v[4:5], v[28:29] op_sel_hi:[0,1]
	v_pk_mul_f32 v[22:23], v[4:5], v[40:41] op_sel_hi:[0,1]
	v_pk_mul_f32 v[24:25], v[4:5], v[42:43] op_sel_hi:[0,1]
	v_max_f32_e32 v24, 0, v24
	v_max_f32_e32 v28, 0, v28
	v_max_f32_e32 v25, 0, v25
	v_max_f32_e32 v29, 0, v29
	v_max_f32_e32 v22, 0, v22
	v_max_f32_e32 v26, 0, v26
	v_max_f32_e32 v23, 0, v23
	v_max_f32_e32 v27, 0, v27
	v_pk_mul_f32 v[24:25], v[24:25], v[24:25]
	v_pk_mul_f32 v[28:29], v[28:29], v[28:29]
	v_pk_mul_f32 v[30:31], v[22:23], v[22:23]
	v_pk_mul_f32 v[26:27], v[26:27], v[26:27]
	v_cvt_pk_bf16_f32 v22, v24, v25
	v_cvt_pk_bf16_f32 v23, v30, v31
	v_cvt_pk_bf16_f32 v24, v28, v29
	v_cvt_pk_bf16_f32 v25, v26, v27
	global_store_dwordx4 v[36:37], v[22:25], off offset:1024 sc1
	s_branch .LBB0_1949

; __device__ __forceinline__ unsigned lane_tb(int fr, int fq) { return (unsigned)((fr * 64 + fq * 16) ^ ((fr >> 3) << 5)); }
; __device__ __forceinline__ void st_bf8(bf16* p, const f32x4 a, const f32x4 b) { *(GAS v4u*)p = (v4u){pk2(a.x, a.y), pk2(a.z, a.w), pk2(b.x, b.y), pk2(b.z, b.w)}; }
;     template <int NR> __device__ __forceinline__ void rows(const int (&rowb)[NR], int fr, const float (&rstd)[NR], const f32x4 (&a)[NR][2][2], int pn, int wc, int fq) const {
; #pragma unroll
;         for (int i = 0; i < NR; ++i) {
;             const float rr = rstd[i];
; #pragma unroll
;             for (int bj = 0; bj < 2; ++bj) {
;                 f32x4 u = a[i][bj][0] * rr, v = a[i][bj][1] * rr;
; #pragma unroll
;                 for (int j = 0; j < 4; ++j) { const float p = fmaxf(u[j], 0.f), q = fmaxf(v[j], 0.f); u[j] = p * p; v[j] = q * q; }
;                 st_bf8((bf16*)((char*)H + tile_ub(rowb[i], (pn << 8) + 64 * wc + 32 * bj, FF) + lane_tb(fr, fq)), u, v);
;             }
;         }
;     }
;     __device__ __forceinline__ void operator()(const f32x4 (&acc)[2][2][4][2], const pg8::Unit& u, int wr, int wc, int fr, int fq, PG8_LAS unsigned char* tabb) const {
;     ...
;             for (int m = 0; m < 4; ++m) { const int rl = ai * 128 + wr * 64 + m * 16; row[m] = u.pm * 256 + rl; rr[m] = rsp ? tab[rl + fr] : 1.f;
; #pragma unroll
;                 for (int bj = 0; bj < 2; ++bj)
; #pragma unroll
;                     for (int n = 0; n < 2; ++n) a[m][bj][n] = acc[ai][bj][m][n]; }
;             R.template rows<4>(row, fr, rr, a, u.pn, wc, fq);
.LBB0_2008:
	v_mov_b32_e32 v134, v0
	s_lshl_b32 s35, s60, 8
	v_and_b32_e32 v135, 15, v134
	s_lshl_b32 s4, s58, 8
	s_or_b32 s4, s4, s76
	v_lshlrev_b32_e32 v141, 6, v135
	v_lshlrev_b32_e32 v135, 2, v135
	s_add_i32 s34, s35, s75
	v_and_b32_e32 v134, 48, v134
	s_ashr_i32 s4, s4, 6
	v_and_b32_e32 v142, 32, v135
	v_add_u32_e32 v148, s80, v135
	s_ashr_i32 s46, s34, 8
	s_ashr_i32 s5, s4, 31
	v_bitop3_b32 v141, v141, v142, v134 bitop3:0x36
	ds_read2_b32 v[142:143], v148 offset1:16
	s_ashr_i32 s47, s46, 31
	s_lshl_b32 s58, s34, 7
	s_lshl_b64 s[4:5], s[4:5], 15
	s_add_i32 s41, s35, s77
	s_add_i32 s39, s35, s78
	s_add_i32 s35, s35, s79
	s_lshl_b64 s[46:47], s[46:47], 21
	s_and_b32 s60, s58, 0x4000
	s_and_b32 s58, s58, 0x2000
	s_add_u32 s46, s52, s46
	s_addc_u32 s47, s53, s47
	s_add_u32 s46, s46, s4
	s_waitcnt lgkmcnt(0)
	v_pk_mul_f32 v[122:123], v[122:123], v[142:143] op_sel_hi:[1,0]
	s_addc_u32 s47, s47, s5
	v_pk_mul_f32 v[128:129], v[128:129], v[142:143] op_sel_hi:[1,0]
	v_pk_mul_f32 v[126:127], v[126:127], v[142:143] op_sel_hi:[1,0]
	v_pk_mul_f32 v[124:125], v[124:125], v[142:143] op_sel_hi:[1,0]
	v_max_f32_e32 v122, 0, v122
	v_max_f32_e32 v123, 0, v123
	s_add_u32 s46, s46, s60
	v_max_f32_e32 v126, 0, v126
	v_max_f32_e32 v127, 0, v127
	v_pk_mul_f32 v[144:145], v[122:123], v[122:123]
	v_max_f32_e32 v122, 0, v128
	v_max_f32_e32 v124, 0, v124
	v_max_f32_e32 v123, 0, v129
	v_max_f32_e32 v125, 0, v125
	s_addc_u32 s47, s47, 0
	v_pk_mul_f32 v[126:127], v[126:127], v[126:127]
	v_pk_mul_f32 v[128:129], v[122:123], v[122:123]
	v_pk_mul_f32 v[146:147], v[124:125], v[124:125]
	s_add_u32 s46, s46, s58
	v_pk_mul_f32 v[114:115], v[114:115], v[142:143] op_sel_hi:[1,0]
	s_addc_u32 s47, s47, 0
	v_cvt_pk_bf16_f32 v122, v126, v127
	v_cvt_pk_bf16_f32 v123, v128, v129
	v_cvt_pk_bf16_f32 v124, v144, v145
	v_cvt_pk_bf16_f32 v125, v146, v147
	v_pk_mul_f32 v[120:121], v[120:121], v[142:143] op_sel_hi:[1,0]
	v_pk_mul_f32 v[118:119], v[118:119], v[142:143] op_sel_hi:[1,0]
	v_pk_mul_f32 v[116:117], v[116:117], v[142:143] op_sel_hi:[1,0]
	v_max_f32_e32 v114, 0, v114
	v_max_f32_e32 v115, 0, v115
	global_store_dwordx4 v141, v[122:125], s[46:47] sc1
	v_max_f32_e32 v118, 0, v118
	v_max_f32_e32 v119, 0, v119
	v_pk_mul_f32 v[122:123], v[114:115], v[114:115]
	v_max_f32_e32 v114, 0, v120
	v_max_f32_e32 v116, 0, v116
	v_max_f32_e32 v115, 0, v121
	v_max_f32_e32 v117, 0, v117
	v_pk_mul_f32 v[118:119], v[118:119], v[118:119]
	v_pk_mul_f32 v[120:121], v[114:115], v[114:115]
	v_pk_mul_f32 v[124:125], v[116:117], v[116:117]
	v_cvt_pk_bf16_f32 v114, v118, v119
	v_cvt_pk_bf16_f32 v115, v120, v121
	v_cvt_pk_bf16_f32 v116, v122, v123
	v_cvt_pk_bf16_f32 v117, v124, v125
	global_store_dwordx4 v141, v[114:117], s[46:47] offset:1024 sc1
	s_ashr_i32 s46, s41, 8
	s_ashr_i32 s47, s46, 31
	s_lshl_b32 s41, s41, 7
	s_lshl_b64 s[46:47], s[46:47], 21
	s_and_b32 s58, s41, 0x4000
	s_and_b32 s41, s41, 0x2800
	s_add_u32 s46, s52, s46
	s_addc_u32 s47, s53, s47
	v_mov_b32_e32 v114, v143
	s_add_u32 s46, s46, s4
	v_pk_mul_f32 v[106:107], v[106:107], v[114:115] op_sel_hi:[1,0]
	s_addc_u32 s47, s47, s5
	v_pk_mul_f32 v[112:113], v[112:113], v[114:115] op_sel_hi:[1,0]
	v_pk_mul_f32 v[110:111], v[110:111], v[114:115] op_sel_hi:[1,0]
	v_pk_mul_f32 v[108:109], v[108:109], v[114:115] op_sel_hi:[1,0]
	v_max_f32_e32 v106, 0, v106
	v_max_f32_e32 v107, 0, v107
	s_add_u32 s46, s46, s58
	v_max_f32_e32 v110, 0, v110
	v_max_f32_e32 v111, 0, v111
	v_pk_mul_f32 v[116:117], v[106:107], v[106:107]
	v_max_f32_e32 v106, 0, v112
	v_max_f32_e32 v108, 0, v108
	v_max_f32_e32 v107, 0, v113
	v_max_f32_e32 v109, 0, v109
	s_addc_u32 s47, s47, 0
	v_pk_mul_f32 v[110:111], v[110:111], v[110:111]
	v_pk_mul_f32 v[112:113], v[106:107], v[106:107]
	v_pk_mul_f32 v[118:119], v[108:109], v[108:109]
	s_add_u32 s46, s46, s41
	v_pk_mul_f32 v[98:99], v[98:99], v[114:115] op_sel_hi:[1,0]
	s_addc_u32 s47, s47, 0
	v_cvt_pk_bf16_f32 v106, v110, v111
	v_cvt_pk_bf16_f32 v107, v112, v113
	v_cvt_pk_bf16_f32 v108, v116, v117
	v_cvt_pk_bf16_f32 v109, v118, v119
	v_pk_mul_f32 v[104:105], v[104:105], v[114:115] op_sel_hi:[1,0]
	v_pk_mul_f32 v[102:103], v[102:103], v[114:115] op_sel_hi:[1,0]
	v_pk_mul_f32 v[100:101], v[100:101], v[114:115] op_sel_hi:[1,0]
	v_max_f32_e32 v98, 0, v98
	v_max_f32_e32 v99, 0, v99
	global_store_dwordx4 v141, v[106:109], s[46:47] sc1
	v_max_f32_e32 v102, 0, v102
	v_max_f32_e32 v103, 0, v103
	v_pk_mul_f32 v[106:107], v[98:99], v[98:99]
	v_max_f32_e32 v98, 0, v104
	v_max_f32_e32 v100, 0, v100
	v_max_f32_e32 v99, 0, v105
	v_max_f32_e32 v101, 0, v101
	v_pk_mul_f32 v[102:103], v[102:103], v[102:103]
	v_pk_mul_f32 v[104:105], v[98:99], v[98:99]
	v_pk_mul_f32 v[108:109], v[100:101], v[100:101]
	v_cvt_pk_bf16_f32 v98, v102, v103
	v_cvt_pk_bf16_f32 v99, v104, v105
	v_cvt_pk_bf16_f32 v100, v106, v107
	v_cvt_pk_bf16_f32 v101, v108, v109
	global_store_dwordx4 v141, v[98:101], s[46:47] offset:1024 sc1
	s_ashr_i32 s46, s39, 8
	ds_read2_b32 v[134:135], v148 offset0:32 offset1:48
	s_ashr_i32 s47, s46, 31
	s_lshl_b32 s39, s39, 7
	s_lshl_b64 s[46:47], s[46:47], 21
	s_and_b32 s41, s39, 0x4000
	s_and_b32 s39, s39, 0x3000
	s_add_u32 s46, s52, s46
	s_addc_u32 s47, s53, s47
	s_add_u32 s46, s46, s4
	s_waitcnt lgkmcnt(0)
; __device__ __forceinline__ unsigned lane_tb(int fr, int fq) { return (unsigned)((fr * 64 + fq * 16) ^ ((fr >> 3) << 5)); }
; __device__ __forceinline__ void st_bf8(bf16* p, const f32x4 a, const f32x4 b) { *(GAS v4u*)p = (v4u){pk2(a.x, a.y), pk2(a.z, a.w), pk2(b.x, b.y), pk2(b.z, b.w)}; }
;     template <int NR> __device__ __forceinline__ void rows(const int (&rowb)[NR], int fr, const float (&rstd)[NR], const f32x4 (&a)[NR][2][2], int pn, int wc, int fq) const {
; #pragma unroll
;         for (int i = 0; i < NR; ++i) {
;             const float rr = rstd[i];
; #pragma unroll
;             for (int bj = 0; bj < 2; ++bj) {
;                 f32x4 u = a[i][bj][0] * rr, v = a[i][bj][1] * rr;
; #pragma unroll
;                 for (int j = 0; j < 4; ++j) { const float p = fmaxf(u[j], 0.f), q = fmaxf(v[j], 0.f); u[j] = p * p; v[j] = q * q; }
;                 st_bf8((bf16*)((char*)H + tile_ub(rowb[i], (pn << 8) + 64 * wc + 32 * bj, FF) + lane_tb(fr, fq)), u, v);
;             }
;         }
;     }
;     __device__ __forceinline__ void operator()(const f32x4 (&acc)[2][2][4][2], const pg8::Unit& u, int wr, int wc, int fr, int fq, PG8_LAS unsigned char* tabb) const {
;     ...
;             for (int m = 0; m < 4; ++m) { const int rl = ai * 128 + wr * 64 + m * 16; row[m] = u.pm * 256 + rl; rr[m] = rsp ? tab[rl + fr] : 1.f;
; #pragma unroll
;                 for (int bj = 0; bj < 2; ++bj)
; #pragma unroll
;                     for (int n = 0; n < 2; ++n) a[m][bj][n] = acc[ai][bj][m][n]; }
;             R.template rows<4>(row, fr, rr, a, u.pn, wc, fq);
	v_pk_mul_f32 v[90:91], v[90:91], v[134:135] op_sel_hi:[1,0]
	s_addc_u32 s47, s47, s5
	v_pk_mul_f32 v[96:97], v[96:97], v[134:135] op_sel_hi:[1,0]
	v_pk_mul_f32 v[94:95], v[94:95], v[134:135] op_sel_hi:[1,0]
	v_pk_mul_f32 v[92:93], v[92:93], v[134:135] op_sel_hi:[1,0]
	v_max_f32_e32 v90, 0, v90
	v_max_f32_e32 v91, 0, v91
	s_add_u32 s41, s46, s41
	v_max_f32_e32 v94, 0, v94
	v_max_f32_e32 v95, 0, v95
	v_pk_mul_f32 v[98:99], v[90:91], v[90:91]
	v_max_f32_e32 v90, 0, v96
	v_max_f32_e32 v92, 0, v92
	v_max_f32_e32 v91, 0, v97
	v_max_f32_e32 v93, 0, v93
	s_addc_u32 s47, s47, 0
	v_pk_mul_f32 v[94:95], v[94:95], v[94:95]
	v_pk_mul_f32 v[96:97], v[90:91], v[90:91]
	v_pk_mul_f32 v[100:101], v[92:93], v[92:93]
	s_add_u32 s46, s41, s39
	v_pk_mul_f32 v[82:83], v[82:83], v[134:135] op_sel_hi:[1,0]
	s_addc_u32 s47, s47, 0
	v_cvt_pk_bf16_f32 v90, v94, v95
	v_cvt_pk_bf16_f32 v91, v96, v97
	v_cvt_pk_bf16_f32 v92, v98, v99
	v_cvt_pk_bf16_f32 v93, v100, v101
	v_pk_mul_f32 v[88:89], v[88:89], v[134:135] op_sel_hi:[1,0]
	v_pk_mul_f32 v[86:87], v[86:87], v[134:135] op_sel_hi:[1,0]
	v_pk_mul_f32 v[84:85], v[84:85], v[134:135] op_sel_hi:[1,0]
	v_max_f32_e32 v82, 0, v82
	v_max_f32_e32 v83, 0, v83
	global_store_dwordx4 v141, v[90:93], s[46:47] sc1
	v_max_f32_e32 v86, 0, v86
	v_max_f32_e32 v87, 0, v87
	v_pk_mul_f32 v[90:91], v[82:83], v[82:83]
	v_max_f32_e32 v82, 0, v88
	v_max_f32_e32 v84, 0, v84
	v_max_f32_e32 v83, 0, v89
	v_max_f32_e32 v85, 0, v85
	v_pk_mul_f32 v[86:87], v[86:87], v[86:87]
	v_pk_mul_f32 v[88:89], v[82:83], v[82:83]
	v_pk_mul_f32 v[92:93], v[84:85], v[84:85]
	v_cvt_pk_bf16_f32 v82, v86, v87
	v_cvt_pk_bf16_f32 v83, v88, v89
	v_cvt_pk_bf16_f32 v84, v90, v91
	v_cvt_pk_bf16_f32 v85, v92, v93
	global_store_dwordx4 v141, v[82:85], s[46:47] offset:1024 sc1
	s_ashr_i32 s46, s35, 8
	s_ashr_i32 s47, s46, 31
	s_lshl_b32 s35, s35, 7
	s_lshl_b64 s[46:47], s[46:47], 21
	s_and_b32 s39, s35, 0x4000
	s_and_b32 s35, s35, 0x3800
	s_add_u32 s41, s52, s46
	s_addc_u32 s46, s53, s47
	v_mov_b32_e32 v82, v135
	s_add_u32 s41, s41, s4
	v_pk_mul_f32 v[74:75], v[74:75], v[82:83] op_sel_hi:[1,0]
	s_addc_u32 s46, s46, s5
	v_pk_mul_f32 v[80:81], v[80:81], v[82:83] op_sel_hi:[1,0]
	v_pk_mul_f32 v[78:79], v[78:79], v[82:83] op_sel_hi:[1,0]
	v_pk_mul_f32 v[76:77], v[76:77], v[82:83] op_sel_hi:[1,0]
	v_max_f32_e32 v74, 0, v74
	v_max_f32_e32 v75, 0, v75
	s_add_u32 s39, s41, s39
	v_max_f32_e32 v78, 0, v78
	v_max_f32_e32 v79, 0, v79
	v_pk_mul_f32 v[84:85], v[74:75], v[74:75]
	v_max_f32_e32 v74, 0, v80
	v_max_f32_e32 v76, 0, v76
	v_max_f32_e32 v75, 0, v81
	v_max_f32_e32 v77, 0, v77
	s_addc_u32 s41, s46, 0
	v_pk_mul_f32 v[78:79], v[78:79], v[78:79]
	v_pk_mul_f32 v[80:81], v[74:75], v[74:75]
	v_pk_mul_f32 v[86:87], v[76:77], v[76:77]
	s_add_u32 s46, s39, s35
	v_pk_mul_f32 v[66:67], v[66:67], v[82:83] op_sel_hi:[1,0]
	s_addc_u32 s47, s41, 0
	v_cvt_pk_bf16_f32 v74, v78, v79
	v_cvt_pk_bf16_f32 v75, v80, v81
	v_cvt_pk_bf16_f32 v76, v84, v85
	v_cvt_pk_bf16_f32 v77, v86, v87
	v_pk_mul_f32 v[72:73], v[72:73], v[82:83] op_sel_hi:[1,0]
	v_pk_mul_f32 v[70:71], v[70:71], v[82:83] op_sel_hi:[1,0]
	v_pk_mul_f32 v[68:69], v[68:69], v[82:83] op_sel_hi:[1,0]
	v_max_f32_e32 v66, 0, v66
	v_max_f32_e32 v67, 0, v67
	global_store_dwordx4 v141, v[74:77], s[46:47] sc1
	v_max_f32_e32 v70, 0, v70
	v_max_f32_e32 v71, 0, v71
	v_pk_mul_f32 v[74:75], v[66:67], v[66:67]
	v_max_f32_e32 v66, 0, v72
	v_max_f32_e32 v68, 0, v68
	v_max_f32_e32 v67, 0, v73
	v_max_f32_e32 v69, 0, v69
	v_pk_mul_f32 v[70:71], v[70:71], v[70:71]
	v_pk_mul_f32 v[72:73], v[66:67], v[66:67]
	v_pk_mul_f32 v[76:77], v[68:69], v[68:69]
	v_cvt_pk_bf16_f32 v66, v70, v71
	v_cvt_pk_bf16_f32 v67, v72, v73
	v_cvt_pk_bf16_f32 v68, v74, v75
	v_cvt_pk_bf16_f32 v69, v76, v77
	s_add_i32 s35, s34, 0xb0
	s_add_i32 s39, s34, 0xa0
	s_add_i32 s41, s34, 0x90
	s_addk_i32 s34, 0x80
	global_store_dwordx4 v141, v[66:69], s[46:47] offset:1024 sc1
	s_ashr_i32 s46, s34, 8
	s_ashr_i32 s47, s46, 31
	s_lshl_b32 s34, s34, 7
	ds_read2_b32 v[68:69], v148 offset0:128 offset1:144
	ds_read2_b32 v[66:67], v148 offset0:160 offset1:176
	s_lshl_b64 s[46:47], s[46:47], 21
	s_and_b32 s58, s34, 0x4000
	s_and_b32 s34, s34, 0x2000
	s_add_u32 s46, s52, s46
	s_addc_u32 s47, s53, s47
	s_add_u32 s46, s46, s4
	s_waitcnt lgkmcnt(0)
; __device__ __forceinline__ unsigned lane_tb(int fr, int fq) { return (unsigned)((fr * 64 + fq * 16) ^ ((fr >> 3) << 5)); }
; __device__ __forceinline__ void st_bf8(bf16* p, const f32x4 a, const f32x4 b) { *(GAS v4u*)p = (v4u){pk2(a.x, a.y), pk2(a.z, a.w), pk2(b.x, b.y), pk2(b.z, b.w)}; }
;     template <int NR> __device__ __forceinline__ void rows(const int (&rowb)[NR], int fr, const float (&rstd)[NR], const f32x4 (&a)[NR][2][2], int pn, int wc, int fq) const {
; #pragma unroll
;         for (int i = 0; i < NR; ++i) {
;             const float rr = rstd[i];
; #pragma unroll
;             for (int bj = 0; bj < 2; ++bj) {
;                 f32x4 u = a[i][bj][0] * rr, v = a[i][bj][1] * rr;
; #pragma unroll
;                 for (int j = 0; j < 4; ++j) { const float p = fmaxf(u[j], 0.f), q = fmaxf(v[j], 0.f); u[j] = p * p; v[j] = q * q; }
;                 st_bf8((bf16*)((char*)H + tile_ub(rowb[i], (pn << 8) + 64 * wc + 32 * bj, FF) + lane_tb(fr, fq)), u, v);
;             }
;         }
;     }
;     __device__ __forceinline__ void operator()(const f32x4 (&acc)[2][2][4][2], const pg8::Unit& u, int wr, int wc, int fr, int fq, PG8_LAS unsigned char* tabb) const {
;     ...
;             for (int m = 0; m < 4; ++m) { const int rl = ai * 128 + wr * 64 + m * 16; row[m] = u.pm * 256 + rl; rr[m] = rsp ? tab[rl + fr] : 1.f;
; #pragma unroll
;                 for (int bj = 0; bj < 2; ++bj)
; #pragma unroll
;                     for (int n = 0; n < 2; ++n) a[m][bj][n] = acc[ai][bj][m][n]; }
;             R.template rows<4>(row, fr, rr, a, u.pn, wc, fq);
	v_pk_mul_f32 v[58:59], v[58:59], v[68:69] op_sel_hi:[1,0]
	s_addc_u32 s47, s47, s5
	v_pk_mul_f32 v[64:65], v[64:65], v[68:69] op_sel_hi:[1,0]
	v_pk_mul_f32 v[62:63], v[62:63], v[68:69] op_sel_hi:[1,0]
	v_pk_mul_f32 v[60:61], v[60:61], v[68:69] op_sel_hi:[1,0]
	v_max_f32_e32 v58, 0, v58
	v_max_f32_e32 v59, 0, v59
	s_add_u32 s46, s46, s58
	v_max_f32_e32 v62, 0, v62
	v_max_f32_e32 v63, 0, v63
	v_pk_mul_f32 v[70:71], v[58:59], v[58:59]
	v_max_f32_e32 v58, 0, v64
	v_max_f32_e32 v60, 0, v60
	v_max_f32_e32 v59, 0, v65
	v_max_f32_e32 v61, 0, v61
	s_addc_u32 s47, s47, 0
	v_pk_mul_f32 v[62:63], v[62:63], v[62:63]
	v_pk_mul_f32 v[64:65], v[58:59], v[58:59]
	v_pk_mul_f32 v[72:73], v[60:61], v[60:61]
	s_add_u32 s46, s46, s34
	v_pk_mul_f32 v[50:51], v[50:51], v[68:69] op_sel_hi:[1,0]
	s_addc_u32 s47, s47, 0
	v_cvt_pk_bf16_f32 v58, v62, v63
	v_cvt_pk_bf16_f32 v59, v64, v65
	v_cvt_pk_bf16_f32 v60, v70, v71
	v_cvt_pk_bf16_f32 v61, v72, v73
	v_pk_mul_f32 v[56:57], v[56:57], v[68:69] op_sel_hi:[1,0]
	v_pk_mul_f32 v[54:55], v[54:55], v[68:69] op_sel_hi:[1,0]
	v_pk_mul_f32 v[52:53], v[52:53], v[68:69] op_sel_hi:[1,0]
	v_max_f32_e32 v50, 0, v50
	v_max_f32_e32 v51, 0, v51
	global_store_dwordx4 v141, v[58:61], s[46:47] sc1
	v_max_f32_e32 v54, 0, v54
	v_max_f32_e32 v55, 0, v55
	v_pk_mul_f32 v[58:59], v[50:51], v[50:51]
	v_max_f32_e32 v50, 0, v56
	v_max_f32_e32 v52, 0, v52
	v_max_f32_e32 v51, 0, v57
	v_max_f32_e32 v53, 0, v53
	v_pk_mul_f32 v[54:55], v[54:55], v[54:55]
	v_pk_mul_f32 v[56:57], v[50:51], v[50:51]
	v_pk_mul_f32 v[60:61], v[52:53], v[52:53]
	v_cvt_pk_bf16_f32 v50, v54, v55
	v_cvt_pk_bf16_f32 v51, v56, v57
	v_cvt_pk_bf16_f32 v52, v58, v59
	v_cvt_pk_bf16_f32 v53, v60, v61
	global_store_dwordx4 v141, v[50:53], s[46:47] offset:1024 sc1
	s_ashr_i32 s46, s41, 8
	s_ashr_i32 s47, s46, 31
	s_lshl_b32 s34, s41, 7
	s_lshl_b64 s[46:47], s[46:47], 21
	s_and_b32 s41, s34, 0x4000
	s_and_b32 s34, s34, 0x2800
	s_add_u32 s46, s52, s46
	s_addc_u32 s47, s53, s47
	v_mov_b32_e32 v50, v69
	s_add_u32 s46, s46, s4
	v_pk_mul_f32 v[42:43], v[42:43], v[50:51] op_sel_hi:[1,0]
	s_addc_u32 s47, s47, s5
	v_pk_mul_f32 v[48:49], v[48:49], v[50:51] op_sel_hi:[1,0]
	v_pk_mul_f32 v[46:47], v[46:47], v[50:51] op_sel_hi:[1,0]
	v_pk_mul_f32 v[44:45], v[44:45], v[50:51] op_sel_hi:[1,0]
	v_max_f32_e32 v42, 0, v42
	v_max_f32_e32 v43, 0, v43
	s_add_u32 s41, s46, s41
	v_max_f32_e32 v46, 0, v46
	v_max_f32_e32 v47, 0, v47
	v_pk_mul_f32 v[52:53], v[42:43], v[42:43]
	v_max_f32_e32 v42, 0, v48
	v_max_f32_e32 v44, 0, v44
	v_max_f32_e32 v43, 0, v49
	v_max_f32_e32 v45, 0, v45
	s_addc_u32 s47, s47, 0
	v_pk_mul_f32 v[46:47], v[46:47], v[46:47]
	v_pk_mul_f32 v[48:49], v[42:43], v[42:43]
	v_pk_mul_f32 v[54:55], v[44:45], v[44:45]
	s_add_u32 s46, s41, s34
	v_pk_mul_f32 v[34:35], v[34:35], v[50:51] op_sel_hi:[1,0]
	s_addc_u32 s47, s47, 0
	v_cvt_pk_bf16_f32 v42, v46, v47
	v_cvt_pk_bf16_f32 v43, v48, v49
	v_cvt_pk_bf16_f32 v44, v52, v53
	v_cvt_pk_bf16_f32 v45, v54, v55
	v_pk_mul_f32 v[40:41], v[40:41], v[50:51] op_sel_hi:[1,0]
	v_pk_mul_f32 v[38:39], v[38:39], v[50:51] op_sel_hi:[1,0]
	v_pk_mul_f32 v[36:37], v[36:37], v[50:51] op_sel_hi:[1,0]
	v_max_f32_e32 v34, 0, v34
	v_max_f32_e32 v35, 0, v35
	global_store_dwordx4 v141, v[42:45], s[46:47] sc1
	v_max_f32_e32 v38, 0, v38
	v_max_f32_e32 v39, 0, v39
	v_pk_mul_f32 v[42:43], v[34:35], v[34:35]
	v_max_f32_e32 v34, 0, v40
	v_max_f32_e32 v36, 0, v36
	v_max_f32_e32 v35, 0, v41
	v_max_f32_e32 v37, 0, v37
	v_pk_mul_f32 v[38:39], v[38:39], v[38:39]
	v_pk_mul_f32 v[40:41], v[34:35], v[34:35]
	v_pk_mul_f32 v[44:45], v[36:37], v[36:37]
	v_cvt_pk_bf16_f32 v34, v38, v39
	v_cvt_pk_bf16_f32 v35, v40, v41
	v_cvt_pk_bf16_f32 v36, v42, v43
	v_cvt_pk_bf16_f32 v37, v44, v45
	global_store_dwordx4 v141, v[34:37], s[46:47] offset:1024 sc1
	s_ashr_i32 s46, s39, 8
	s_ashr_i32 s47, s46, 31
	s_lshl_b32 s34, s39, 7
	s_lshl_b64 s[46:47], s[46:47], 21
	s_and_b32 s39, s34, 0x4000
	s_and_b32 s34, s34, 0x3000
; __device__ __forceinline__ unsigned lane_tb(int fr, int fq) { return (unsigned)((fr * 64 + fq * 16) ^ ((fr >> 3) << 5)); }
; __device__ __forceinline__ void st_bf8(bf16* p, const f32x4 a, const f32x4 b) { *(GAS v4u*)p = (v4u){pk2(a.x, a.y), pk2(a.z, a.w), pk2(b.x, b.y), pk2(b.z, b.w)}; }
;     template <int NR> __device__ __forceinline__ void rows(const int (&rowb)[NR], int fr, const float (&rstd)[NR], const f32x4 (&a)[NR][2][2], int pn, int wc, int fq) const {
; #pragma unroll
;         for (int i = 0; i < NR; ++i) {
;             const float rr = rstd[i];
; #pragma unroll
;             for (int bj = 0; bj < 2; ++bj) {
;                 f32x4 u = a[i][bj][0] * rr, v = a[i][bj][1] * rr;
; #pragma unroll
;                 for (int j = 0; j < 4; ++j) { const float p = fmaxf(u[j], 0.f), q = fmaxf(v[j], 0.f); u[j] = p * p; v[j] = q * q; }
;                 st_bf8((bf16*)((char*)H + tile_ub(rowb[i], (pn << 8) + 64 * wc + 32 * bj, FF) + lane_tb(fr, fq)), u, v);
;             }
;         }
;     }
;     __device__ __forceinline__ void operator()(const f32x4 (&acc)[2][2][4][2], const pg8::Unit& u, int wr, int wc, int fr, int fq, PG8_LAS unsigned char* tabb) const {
;     ...
;             for (int m = 0; m < 4; ++m) { const int rl = ai * 128 + wr * 64 + m * 16; row[m] = u.pm * 256 + rl; rr[m] = rsp ? tab[rl + fr] : 1.f;
; #pragma unroll
;                 for (int bj = 0; bj < 2; ++bj)
; #pragma unroll
;                     for (int n = 0; n < 2; ++n) a[m][bj][n] = acc[ai][bj][m][n]; }
;             R.template rows<4>(row, fr, rr, a, u.pn, wc, fq);
	s_add_u32 s41, s52, s46
	s_addc_u32 s46, s53, s47
	s_add_u32 s41, s41, s4
	v_pk_mul_f32 v[26:27], v[26:27], v[66:67] op_sel_hi:[1,0]
	s_addc_u32 s46, s46, s5
	v_pk_mul_f32 v[32:33], v[32:33], v[66:67] op_sel_hi:[1,0]
	v_pk_mul_f32 v[30:31], v[30:31], v[66:67] op_sel_hi:[1,0]
	v_pk_mul_f32 v[28:29], v[28:29], v[66:67] op_sel_hi:[1,0]
	v_max_f32_e32 v26, 0, v26
	v_max_f32_e32 v27, 0, v27
	s_add_u32 s39, s41, s39
	v_max_f32_e32 v30, 0, v30
	v_max_f32_e32 v31, 0, v31
	v_pk_mul_f32 v[34:35], v[26:27], v[26:27]
	v_max_f32_e32 v26, 0, v32
	v_max_f32_e32 v28, 0, v28
	v_max_f32_e32 v27, 0, v33
	v_max_f32_e32 v29, 0, v29
	s_addc_u32 s41, s46, 0
	v_pk_mul_f32 v[30:31], v[30:31], v[30:31]
	v_pk_mul_f32 v[32:33], v[26:27], v[26:27]
	v_pk_mul_f32 v[36:37], v[28:29], v[28:29]
	s_add_u32 s46, s39, s34
	v_pk_mul_f32 v[18:19], v[18:19], v[66:67] op_sel_hi:[1,0]
	s_addc_u32 s47, s41, 0
	v_cvt_pk_bf16_f32 v26, v30, v31
	v_cvt_pk_bf16_f32 v27, v32, v33
	v_cvt_pk_bf16_f32 v28, v34, v35
	v_cvt_pk_bf16_f32 v29, v36, v37
	v_pk_mul_f32 v[24:25], v[24:25], v[66:67] op_sel_hi:[1,0]
	v_pk_mul_f32 v[22:23], v[22:23], v[66:67] op_sel_hi:[1,0]
	v_pk_mul_f32 v[20:21], v[20:21], v[66:67] op_sel_hi:[1,0]
	v_max_f32_e32 v18, 0, v18
	v_max_f32_e32 v19, 0, v19
	global_store_dwordx4 v141, v[26:29], s[46:47] sc1
	v_max_f32_e32 v22, 0, v22
	v_max_f32_e32 v23, 0, v23
	v_pk_mul_f32 v[26:27], v[18:19], v[18:19]
	v_max_f32_e32 v18, 0, v24
	v_max_f32_e32 v20, 0, v20
	v_max_f32_e32 v19, 0, v25
	v_max_f32_e32 v21, 0, v21
	v_pk_mul_f32 v[22:23], v[22:23], v[22:23]
	v_pk_mul_f32 v[24:25], v[18:19], v[18:19]
	v_pk_mul_f32 v[28:29], v[20:21], v[20:21]
	v_cvt_pk_bf16_f32 v18, v22, v23
	v_cvt_pk_bf16_f32 v19, v24, v25
	v_cvt_pk_bf16_f32 v20, v26, v27
	v_cvt_pk_bf16_f32 v21, v28, v29
	global_store_dwordx4 v141, v[18:21], s[46:47] offset:1024 sc1
	s_ashr_i32 s46, s35, 8
	s_ashr_i32 s47, s46, 31
	s_lshl_b32 s34, s35, 7
	s_lshl_b64 s[46:47], s[46:47], 21
	s_and_b32 s35, s34, 0x4000
	s_and_b32 s34, s34, 0x3800
	s_add_u32 s39, s52, s46
	s_addc_u32 s41, s53, s47
	v_mov_b32_e32 v18, v67
	s_add_u32 s4, s39, s4
	v_pk_mul_f32 v[10:11], v[10:11], v[18:19] op_sel_hi:[1,0]
	s_addc_u32 s5, s41, s5
	v_pk_mul_f32 v[16:17], v[16:17], v[18:19] op_sel_hi:[1,0]
	v_pk_mul_f32 v[14:15], v[14:15], v[18:19] op_sel_hi:[1,0]
	v_pk_mul_f32 v[12:13], v[12:13], v[18:19] op_sel_hi:[1,0]
	v_max_f32_e32 v10, 0, v10
	v_max_f32_e32 v11, 0, v11
	s_add_u32 s4, s4, s35
	v_max_f32_e32 v14, 0, v14
	v_max_f32_e32 v15, 0, v15
	v_pk_mul_f32 v[20:21], v[10:11], v[10:11]
	v_max_f32_e32 v10, 0, v16
	v_max_f32_e32 v12, 0, v12
	v_max_f32_e32 v11, 0, v17
	v_max_f32_e32 v13, 0, v13
	s_addc_u32 s5, s5, 0
	v_pk_mul_f32 v[14:15], v[14:15], v[14:15]
	v_pk_mul_f32 v[16:17], v[10:11], v[10:11]
	v_pk_mul_f32 v[22:23], v[12:13], v[12:13]
	s_add_u32 s4, s4, s34
	v_pk_mul_f32 v[2:3], v[2:3], v[18:19] op_sel_hi:[1,0]
	s_addc_u32 s5, s5, 0
	v_cvt_pk_bf16_f32 v10, v14, v15
	v_cvt_pk_bf16_f32 v11, v16, v17
	v_cvt_pk_bf16_f32 v12, v20, v21
	v_cvt_pk_bf16_f32 v13, v22, v23
	v_pk_mul_f32 v[8:9], v[8:9], v[18:19] op_sel_hi:[1,0]
	v_pk_mul_f32 v[6:7], v[6:7], v[18:19] op_sel_hi:[1,0]
	v_pk_mul_f32 v[4:5], v[4:5], v[18:19] op_sel_hi:[1,0]
	v_max_f32_e32 v2, 0, v2
	v_max_f32_e32 v3, 0, v3
	global_store_dwordx4 v141, v[10:13], s[4:5] sc1
	v_max_f32_e32 v6, 0, v6
	v_max_f32_e32 v7, 0, v7
	v_pk_mul_f32 v[10:11], v[2:3], v[2:3]
	v_max_f32_e32 v2, 0, v8
	v_max_f32_e32 v4, 0, v4
	v_max_f32_e32 v3, 0, v9
	v_max_f32_e32 v5, 0, v5
	v_pk_mul_f32 v[6:7], v[6:7], v[6:7]
	v_pk_mul_f32 v[8:9], v[2:3], v[2:3]
	v_pk_mul_f32 v[12:13], v[4:5], v[4:5]
	v_cvt_pk_bf16_f32 v2, v6, v7
	v_cvt_pk_bf16_f32 v3, v8, v9
	v_cvt_pk_bf16_f32 v4, v10, v11
	v_cvt_pk_bf16_f32 v5, v12, v13
	global_store_dwordx4 v141, v[2:5], s[4:5] offset:1024 sc1
	s_andn2_b64 vcc, exec, s[42:43]
	s_mov_b64 s[4:5], -1
	s_cbranch_vccnz .LBB0_1996
	s_andn2_b64 vcc, exec, s[26:27]
	s_cbranch_vccnz .LBB0_1995
	s_barrier
	s_branch .LBB0_1995

; #define GAS __attribute__((address_space(1)))
; template <class RowEpi, int MTL>
; __device__ __forceinline__ void small_gemm_t(Frame& F, const bf16* A  , const bf16* Bt, int N, int K, const RowEpi& R, int i_lo, int i_hi) {
;     ...
;         const int ar0 = rb * 16 * MTL + fr, ak0 = w * kw + 8 * fq;
;         const int bp0 = pn * 256 + 32 * wc + fr, bk0 = w * kw + 8 * fq;
; #pragma unroll 4
;         for (int k = 0; k < kw; k += 32) {
;             bf16x8 a[MTL], b[2][2];
; #pragma unroll
;             for (int m = 0; m < MTL; ++m) a[m] = *(const GAS bf16x8*)(A + wt_off(ar0 + 16 * m, ak0 + k, K));
; #pragma unroll
;             for (int bj = 0; bj < 2; ++bj)
; #pragma unroll
;                 for (int n = 0; n < 2; ++n) b[bj][n] = *(const GAS bf16x8*)(Bt + wt_off(bp0 + 128 * bj + 16 * n, bk0 + k, K));
; #pragma unroll
;             for (int m = 0; m < MTL; ++m)
; #pragma unroll
;                 for (int bj = 0; bj < 2; ++bj)
; #pragma unroll
;                     for (int n = 0; n < 2; ++n) acc[m][bj][n] = __builtin_amdgcn_mfma_f32_16x16x32_bf16(b[bj][n], a[m], acc[m][bj][n], 0, 0, 0);
;         }
.LBB0_2019:
	s_and_b32 s24, s4, -16
	s_lshl_b32 s4, s4, 13
	s_ashr_i32 s23, s5, 2
	s_and_b32 s4, s4, 0x4000
	v_readlane_b32 s5, v245, 11
	s_add_u32 s4, s5, s4
	v_readlane_b32 s5, v245, 12
	s_addc_u32 s5, s5, 0
	s_bfe_i32 s14, s23, 0x180002
	s_or_b32 s26, s10, 16
	s_or_b32 s27, s10, 32
	s_or_b32 s34, s10, 48
	v_or_b32_e32 v4, s10, v10
	s_ashr_i32 s15, s14, 31
	s_lshr_b32 s25, s10, 3
	s_lshr_b32 s26, s26, 3
	s_lshr_b32 s27, s27, 3
	s_lshr_b32 s34, s34, 3
	s_lshl_b32 s35, s23, 2
	s_and_b32 s25, s25, 8
	v_lshlrev_b32_e32 v22, 6, v4
	s_and_b32 s26, s26, 10
	s_and_b32 s27, s27, 12
	s_and_b32 s34, s34, 14
	s_and_b32 s35, s35, 12
	s_lshl_b64 s[14:15], s[14:15], 19
	v_and_b32_e32 v24, 0x3c0, v22
	v_lshlrev_b32_e32 v4, 2, v4
	s_add_u32 s14, s33, s14
	v_and_b32_e32 v132, 32, v4
	s_addc_u32 s15, s45, s15
	v_or_b32_e32 v133, v11, v24
	s_lshl_b32 s36, s25, 10
	v_add_u32_e32 v22, s24, v17
	v_bitop3_b32 v4, v133, s36, v132 bitop3:0xde
	s_lshl_b32 s36, s26, 10
	v_ashrrev_i32_e32 v23, 31, v22
	v_bitop3_b32 v114, v133, s36, v132 bitop3:0xde
	s_lshl_b32 s36, s27, 10
	v_lshlrev_b64 v[22:23], 15, v[22:23]
	v_lshl_add_u64 v[90:91], s[14:15], 0, v[6:7]
	v_lshl_or_b32 v112, s35, 10, v2
	v_bitop3_b32 v116, v133, s36, v132 bitop3:0xde
	s_lshl_b32 s36, s34, 10
	v_lshl_add_u64 v[110:111], s[4:5], 0, v[22:23]
	v_mov_b32_e32 v113, v5
	v_mov_b32_e32 v119, v5
	v_bitop3_b32 v118, v133, s36, v132 bitop3:0xde
	v_mov_b32_e32 v121, v5
	v_lshl_add_u64 v[106:107], v[90:91], 0, s[12:13]
	v_or_b32_e32 v120, 0x800, v112
	v_lshl_add_u64 v[30:31], v[90:91], 0, v[112:113]
	v_lshl_add_u64 v[26:27], v[110:111], 0, v[4:5]
	v_lshl_add_u64 v[58:59], v[110:111], 0, v[118:119]
	v_lshl_add_u64 v[70:71], v[106:107], 0, v[112:113]
	v_lshl_add_u64 v[74:75], v[106:107], 0, v[120:121]
	global_load_dwordx4 v[22:25], v[30:31], off
	s_nop 0
	global_load_dwordx4 v[26:29], v[26:27], off
	s_nop 0
	global_load_dwordx4 v[30:33], v[30:31], off offset:2048
	v_mov_b32_e32 v115, v5
	global_load_dwordx4 v[58:61], v[58:59], off
	v_mov_b32_e32 v117, v5
	global_load_dwordx4 v[70:73], v[70:71], off
	v_lshl_add_u64 v[34:35], v[110:111], 0, v[114:115]
	global_load_dwordx4 v[74:77], v[74:75], off
	v_lshl_add_u64 v[46:47], v[110:111], 0, v[116:117]
	global_load_dwordx4 v[34:37], v[34:35], off
	v_or_b32_e64 v92, 1, s35
	global_load_dwordx4 v[46:49], v[46:47], off
	v_lshl_or_b32 v124, v92, 10, v2
	v_or_b32_e64 v102, 1, s26
	v_mov_b32_e32 v125, v5
	v_or_b32_e64 v86, 1, s25
	v_lshlrev_b32_e32 v102, 10, v102
	v_or_b32_e32 v128, 0x800, v124
	v_mov_b32_e32 v129, v5
	v_lshlrev_b32_e32 v93, 10, v86
	v_lshl_add_u64 v[98:99], v[90:91], 0, v[124:125]
	v_bitop3_b32 v126, v133, v102, v132 bitop3:0xde
	v_lshl_add_u64 v[102:103], v[106:107], 0, v[124:125]
	v_lshl_add_u64 v[106:107], v[106:107], 0, v[128:129]
	v_bitop3_b32 v122, v133, v93, v132 bitop3:0xde
	global_load_dwordx4 v[90:93], v[98:99], off
	v_mov_b32_e32 v123, v5
	global_load_dwordx4 v[102:105], v[102:103], off
	v_lshl_add_u64 v[94:95], v[110:111], 0, v[122:123]
	global_load_dwordx4 v[98:101], v[98:99], off offset:2048
	v_mov_b32_e32 v127, v5
	global_load_dwordx4 v[106:109], v[106:107], off
	v_or_b32_e64 v134, 1, s34
	global_load_dwordx4 v[94:97], v[94:95], off
	s_waitcnt vmcnt(0)
	v_mfma_f32_16x16x32_bf16 v[42:45], v[30:33], v[26:29], 0
	v_lshlrev_b32_e32 v134, 10, v134
	v_mov_b32_e32 v131, v5
	s_and_b64 vcc, exec, s[0:1]
	v_mfma_f32_16x16x32_bf16 v[38:41], v[22:25], v[26:29], 0
	v_mfma_f32_16x16x32_bf16 v[50:53], v[22:25], v[34:37], 0
	v_mfma_f32_16x16x32_bf16 v[54:57], v[30:33], v[34:37], 0
	v_mfma_f32_16x16x32_bf16 v[62:65], v[22:25], v[46:49], 0
	v_mfma_f32_16x16x32_bf16 v[66:69], v[30:33], v[46:49], 0
	v_mfma_f32_16x16x32_bf16 v[22:25], v[22:25], v[58:61], 0
	v_mfma_f32_16x16x32_bf16 v[30:33], v[30:33], v[58:61], 0
	v_mfma_f32_16x16x32_bf16 v[78:81], v[70:73], v[26:29], 0
	v_mfma_f32_16x16x32_bf16 v[26:29], v[74:77], v[26:29], 0
	v_mfma_f32_16x16x32_bf16 v[82:85], v[70:73], v[34:37], 0
	v_mfma_f32_16x16x32_bf16 v[34:37], v[74:77], v[34:37], 0
	v_mfma_f32_16x16x32_bf16 v[86:89], v[70:73], v[46:49], 0
	v_mfma_f32_16x16x32_bf16 v[46:49], v[74:77], v[46:49], 0
	v_mfma_f32_16x16x32_bf16 v[70:73], v[70:73], v[58:61], 0
	v_mfma_f32_16x16x32_bf16 v[58:61], v[74:77], v[58:61], 0
	v_lshl_add_u64 v[74:75], v[110:111], 0, v[126:127]
	global_load_dwordx4 v[74:77], v[74:75], off
	v_mfma_f32_16x16x32_bf16 v[38:41], v[90:93], v[94:97], v[38:41]
	v_mfma_f32_16x16x32_bf16 v[42:45], v[98:101], v[94:97], v[42:45]
	v_mfma_f32_16x16x32_bf16 v[78:81], v[102:105], v[94:97], v[78:81]
	v_mfma_f32_16x16x32_bf16 v[26:29], v[106:109], v[94:97], v[26:29]
	v_or_b32_e64 v94, 1, s27
	v_lshlrev_b32_e32 v94, 10, v94
	v_bitop3_b32 v130, v133, v94, v132 bitop3:0xde
	v_bitop3_b32 v132, v133, v134, v132 bitop3:0xde
	v_mov_b32_e32 v133, v5
	v_lshl_add_u64 v[94:95], v[110:111], 0, v[130:131]
	v_lshl_add_u64 v[110:111], v[110:111], 0, v[132:133]
	global_load_dwordx4 v[94:97], v[94:95], off
	s_waitcnt vmcnt(1)
	v_mfma_f32_16x16x32_bf16 v[50:53], v[90:93], v[74:77], v[50:53]
	v_mfma_f32_16x16x32_bf16 v[54:57], v[98:101], v[74:77], v[54:57]
	v_mfma_f32_16x16x32_bf16 v[82:85], v[102:105], v[74:77], v[82:85]
	v_mfma_f32_16x16x32_bf16 v[34:37], v[106:109], v[74:77], v[34:37]
	global_load_dwordx4 v[74:77], v[110:111], off
	v_lshl_add_u64 v[110:111], s[14:15], 0, v[8:9]
	s_waitcnt vmcnt(1)
	v_mfma_f32_16x16x32_bf16 v[62:65], v[90:93], v[94:97], v[62:65]
	s_waitcnt vmcnt(0)
; #define GAS __attribute__((address_space(1)))
; #define WG_BAR() asm volatile("s_waitcnt lgkmcnt(0)\n\ts_barrier" ::: "memory")
; template <class RowEpi, int MTL>
; __device__ __forceinline__ void small_gemm_t(Frame& F, const bf16* A  , const bf16* Bt, int N, int K, const RowEpi& R, int i_lo, int i_hi) {
;     ...
;         for (int k = 0; k < kw; k += 32) {
;             bf16x8 a[MTL], b[2][2];
; #pragma unroll
;             for (int m = 0; m < MTL; ++m) a[m] = *(const GAS bf16x8*)(A + wt_off(ar0 + 16 * m, ak0 + k, K));
; #pragma unroll
;             for (int bj = 0; bj < 2; ++bj)
; #pragma unroll
;                 for (int n = 0; n < 2; ++n) b[bj][n] = *(const GAS bf16x8*)(Bt + wt_off(bp0 + 128 * bj + 16 * n, bk0 + k, K));
; #pragma unroll
;             for (int m = 0; m < MTL; ++m)
; #pragma unroll
;                 for (int bj = 0; bj < 2; ++bj)
; #pragma unroll
;                     for (int n = 0; n < 2; ++n) acc[m][bj][n] = __builtin_amdgcn_mfma_f32_16x16x32_bf16(b[bj][n], a[m], acc[m][bj][n], 0, 0, 0);
;         }
; #pragma unroll
;         for (int m = 0; m < MTL; ++m)
; #pragma unroll
;             for (int bj = 0; bj < 2; ++bj)
; #pragma unroll
;                 for (int n = 0; n < 2; ++n) part[(w * (4 * MTL) + m * 4 + bj * 2 + n) * 64 + lane] = acc[m][bj][n];
;         WG_BAR();
	v_mfma_f32_16x16x32_bf16 v[22:25], v[90:93], v[74:77], v[22:25]
	v_add_u32_e32 v90, s24, v18
	v_ashrrev_i32_e32 v91, 31, v90
	v_mfma_f32_16x16x32_bf16 v[66:69], v[98:101], v[94:97], v[66:69]
	v_mfma_f32_16x16x32_bf16 v[86:89], v[102:105], v[94:97], v[86:89]
	v_mfma_f32_16x16x32_bf16 v[46:49], v[106:109], v[94:97], v[46:49]
	v_lshlrev_b64 v[94:95], 15, v[90:91]
	v_lshl_add_u64 v[134:135], s[4:5], 0, v[94:95]
	v_lshl_add_u64 v[94:95], v[134:135], 0, v[4:5]
	v_mfma_f32_16x16x32_bf16 v[30:33], v[98:101], v[74:77], v[30:33]
	v_lshl_add_u64 v[98:99], v[110:111], 0, v[112:113]
	global_load_dwordx4 v[90:93], v[98:99], off
	s_nop 0
	global_load_dwordx4 v[94:97], v[94:95], off
	s_nop 0
	global_load_dwordx4 v[98:101], v[98:99], off offset:2048
	v_mfma_f32_16x16x32_bf16 v[70:73], v[102:105], v[74:77], v[70:73]
	v_mfma_f32_16x16x32_bf16 v[58:61], v[106:109], v[74:77], v[58:61]
	v_lshl_add_u64 v[74:75], v[134:135], 0, v[114:115]
	v_lshl_add_u64 v[114:115], v[110:111], 0, s[12:13]
	v_lshl_add_u64 v[102:103], v[114:115], 0, v[112:113]
	v_lshl_add_u64 v[106:107], v[114:115], 0, v[120:121]
	global_load_dwordx4 v[102:105], v[102:103], off
	s_waitcnt vmcnt(2)
	v_mfma_f32_16x16x32_bf16 v[38:41], v[90:93], v[94:97], v[38:41]
	global_load_dwordx4 v[106:109], v[106:107], off
	v_lshl_add_u64 v[112:113], v[134:135], 0, v[118:119]
	global_load_dwordx4 v[74:77], v[74:75], off
	s_waitcnt vmcnt(3)
	v_mfma_f32_16x16x32_bf16 v[42:45], v[98:101], v[94:97], v[42:45]
	v_lshl_add_u64 v[110:111], v[110:111], 0, v[124:125]
	s_waitcnt vmcnt(2)
	v_mfma_f32_16x16x32_bf16 v[78:81], v[102:105], v[94:97], v[78:81]
	s_waitcnt vmcnt(1)
	v_mfma_f32_16x16x32_bf16 v[26:29], v[106:109], v[94:97], v[26:29]
	v_lshl_add_u64 v[94:95], v[134:135], 0, v[116:117]
	global_load_dwordx4 v[94:97], v[94:95], off
	s_waitcnt vmcnt(1)
	v_mfma_f32_16x16x32_bf16 v[50:53], v[90:93], v[74:77], v[50:53]
	v_mfma_f32_16x16x32_bf16 v[54:57], v[98:101], v[74:77], v[54:57]
	v_mfma_f32_16x16x32_bf16 v[82:85], v[102:105], v[74:77], v[82:85]
	v_mfma_f32_16x16x32_bf16 v[34:37], v[106:109], v[74:77], v[34:37]
	global_load_dwordx4 v[74:77], v[112:113], off
	s_waitcnt vmcnt(1)
	v_mfma_f32_16x16x32_bf16 v[86:89], v[102:105], v[94:97], v[86:89]
	s_waitcnt vmcnt(0)
	v_mfma_f32_16x16x32_bf16 v[70:73], v[102:105], v[74:77], v[70:73]
	v_lshl_add_u64 v[102:103], v[134:135], 0, v[122:123]
	v_mfma_f32_16x16x32_bf16 v[62:65], v[90:93], v[94:97], v[62:65]
	v_mfma_f32_16x16x32_bf16 v[66:69], v[98:101], v[94:97], v[66:69]
	v_mfma_f32_16x16x32_bf16 v[46:49], v[106:109], v[94:97], v[46:49]
	v_mfma_f32_16x16x32_bf16 v[22:25], v[90:93], v[74:77], v[22:25]
	global_load_dwordx4 v[90:93], v[110:111], off
	v_mfma_f32_16x16x32_bf16 v[30:33], v[98:101], v[74:77], v[30:33]
	global_load_dwordx4 v[94:97], v[102:103], off
	global_load_dwordx4 v[98:101], v[110:111], off offset:2048
	v_lshl_add_u64 v[102:103], v[114:115], 0, v[124:125]
	global_load_dwordx4 v[102:105], v[102:103], off
	v_mfma_f32_16x16x32_bf16 v[58:61], v[106:109], v[74:77], v[58:61]
	v_lshl_add_u64 v[106:107], v[114:115], 0, v[128:129]
	global_load_dwordx4 v[106:109], v[106:107], off
	v_lshl_add_u64 v[74:75], v[134:135], 0, v[126:127]
	global_load_dwordx4 v[74:77], v[74:75], off
	s_waitcnt vmcnt(4)
	v_mfma_f32_16x16x32_bf16 v[38:41], v[90:93], v[94:97], v[38:41]
	v_lshl_add_u64 v[110:111], v[134:135], 0, v[132:133]
	s_waitcnt vmcnt(3)
	v_mfma_f32_16x16x32_bf16 v[42:45], v[98:101], v[94:97], v[42:45]
	s_waitcnt vmcnt(2)
	v_mfma_f32_16x16x32_bf16 v[78:81], v[102:105], v[94:97], v[78:81]
	s_waitcnt vmcnt(1)
	v_mfma_f32_16x16x32_bf16 v[26:29], v[106:109], v[94:97], v[26:29]
	v_lshl_add_u64 v[94:95], v[134:135], 0, v[130:131]
	global_load_dwordx4 v[94:97], v[94:95], off
	s_waitcnt vmcnt(1)
	v_mfma_f32_16x16x32_bf16 v[50:53], v[90:93], v[74:77], v[50:53]
	v_mfma_f32_16x16x32_bf16 v[54:57], v[98:101], v[74:77], v[54:57]
	v_mfma_f32_16x16x32_bf16 v[82:85], v[102:105], v[74:77], v[82:85]
	v_mfma_f32_16x16x32_bf16 v[34:37], v[106:109], v[74:77], v[34:37]
	global_load_dwordx4 v[74:77], v[110:111], off
	ds_write_b128 v20, v[38:41]
	ds_write_b128 v20, v[42:45] offset:1024
	ds_write_b128 v20, v[78:81] offset:2048
	ds_write_b128 v20, v[26:29] offset:3072
	ds_write_b128 v20, v[50:53] offset:4096
	ds_write_b128 v20, v[54:57] offset:5120
	s_waitcnt vmcnt(1)
	v_mfma_f32_16x16x32_bf16 v[66:69], v[98:101], v[94:97], v[66:69]
	s_waitcnt vmcnt(0)
	v_mfma_f32_16x16x32_bf16 v[22:25], v[90:93], v[74:77], v[22:25]
	v_mfma_f32_16x16x32_bf16 v[86:89], v[102:105], v[94:97], v[86:89]
	v_mfma_f32_16x16x32_bf16 v[26:29], v[98:101], v[74:77], v[30:33]
	v_mfma_f32_16x16x32_bf16 v[62:65], v[90:93], v[94:97], v[62:65]
	ds_write_b128 v20, v[82:85] offset:6144
	ds_write_b128 v20, v[34:37] offset:7168
	s_nop 5
	ds_write_b128 v20, v[62:65] offset:8192
	v_mfma_f32_16x16x32_bf16 v[38:41], v[106:109], v[94:97], v[46:49]
	ds_write_b128 v20, v[66:69] offset:9216
	ds_write_b128 v20, v[86:89] offset:10240
	s_nop 5
	ds_write_b128 v20, v[38:41] offset:11264
	v_mfma_f32_16x16x32_bf16 v[30:33], v[102:105], v[74:77], v[70:73]
	ds_write_b128 v20, v[22:25] offset:12288
	ds_write_b128 v20, v[26:29] offset:13312
	s_nop 5
	ds_write_b128 v20, v[30:33] offset:14336
	v_mfma_f32_16x16x32_bf16 v[22:25], v[106:109], v[74:77], v[58:61]
	s_nop 7
	ds_write_b128 v20, v[22:25] offset:15360
	s_waitcnt lgkmcnt(0)
	s_barrier
	s_cbranch_vccnz .LBB0_2014
; template <class RowEpi, int MTL>
; __device__ __forceinline__ void small_gemm_t(Frame& F, const bf16* A  , const bf16* Bt, int N, int K, const RowEpi& R, int i_lo, int i_hi) {
;     ...
;         if (w < MTL) {
;             f32x4 s[2][2];
; #pragma unroll
;             for (int bj = 0; bj < 2; ++bj)
; #pragma unroll
;                 for (int n = 0; n < 2; ++n) { f32x4 t = (f32x4){0.f, 0.f, 0.f, 0.f};
; #pragma unroll
;                     for (int ww = 0; ww < 8; ++ww) t += part[(ww * (4 * MTL) + w * 4 + bj * 2 + n) * 64 + lane];
;                     s[bj][n] = t; }
	v_add_u32_e32 v4, s16, v1
	ds_read_b128 v[22:25], v4
	ds_read_b128 v[26:29], v4 offset:16384
	ds_read_b128 v[30:33], v4 offset:1024
	s_lshl_b32 s4, s23, 6
	s_add_i32 s23, s17, s10
	v_cmp_gt_f32_e32 vcc, s22, v21
	s_waitcnt lgkmcnt(2)
	v_pk_add_f32 v[38:39], v[24:25], 0 op_sel_hi:[1,0]
	v_pk_add_f32 v[40:41], v[22:23], 0 op_sel_hi:[1,0]
	ds_read_b128 v[22:25], v4 offset:32768
	ds_read_b128 v[34:37], v4 offset:17408
	s_waitcnt lgkmcnt(3)
	v_pk_add_f32 v[38:39], v[38:39], v[28:29]
	v_pk_add_f32 v[42:43], v[40:41], v[26:27]
	ds_read_b128 v[26:29], v4 offset:33792
	s_waitcnt lgkmcnt(2)
	v_pk_add_f32 v[46:47], v[38:39], v[24:25]
	ds_read_b128 v[38:41], v4 offset:49152
	v_pk_add_f32 v[48:49], v[42:43], v[22:23]
	v_add_u32_e32 v22, s16, v12
	ds_read_b128 v[22:25], v22
	ds_read_b128 v[42:45], v4 offset:50176
	s_lshr_b32 s10, s23, 8
	s_waitcnt lgkmcnt(2)
	v_pk_add_f32 v[48:49], v[48:49], v[38:39]
	v_add_u32_e32 v38, s16, v13
	v_pk_add_f32 v[46:47], v[46:47], v[40:41]
	ds_read_b128 v[38:41], v38
	s_waitcnt lgkmcnt(2)
	v_pk_add_f32 v[52:53], v[48:49], v[22:23]
	v_add_u32_e32 v22, s16, v14
	v_pk_add_f32 v[50:51], v[46:47], v[24:25]
	ds_read_b128 v[22:25], v22
	v_add_u32_e32 v46, s16, v15
	ds_read_b128 v[46:49], v46
	s_waitcnt lgkmcnt(2)
	v_pk_add_f32 v[38:39], v[52:53], v[38:39]
	v_pk_add_f32 v[40:41], v[50:51], v[40:41]
	s_waitcnt lgkmcnt(1)
	v_pk_add_f32 v[22:23], v[38:39], v[22:23]
	v_pk_add_f32 v[24:25], v[40:41], v[24:25]
	s_waitcnt lgkmcnt(0)
	v_pk_add_f32 v[52:53], v[22:23], v[46:47]
	v_pk_add_f32 v[22:23], v[32:33], 0 op_sel_hi:[1,0]
	v_pk_add_f32 v[50:51], v[24:25], v[48:49]
	v_pk_add_f32 v[24:25], v[30:31], 0 op_sel_hi:[1,0]
	v_pk_add_f32 v[22:23], v[22:23], v[36:37]
	v_pk_add_f32 v[24:25], v[24:25], v[34:35]
	v_pk_add_f32 v[28:29], v[22:23], v[28:29]
	v_add_u32_e32 v22, s18, v12
	v_pk_add_f32 v[26:27], v[24:25], v[26:27]
	ds_read_b128 v[22:25], v22
	v_pk_add_f32 v[32:33], v[26:27], v[42:43]
	v_add_u32_e32 v26, s18, v13
	v_pk_add_f32 v[30:31], v[28:29], v[44:45]
	ds_read_b128 v[26:29], v26
	s_waitcnt lgkmcnt(1)
	v_pk_add_f32 v[32:33], v[32:33], v[22:23]
	v_add_u32_e32 v22, s18, v14
	v_pk_add_f32 v[30:31], v[30:31], v[24:25]
	ds_read_b128 v[22:25], v22
	s_waitcnt lgkmcnt(1)
	v_pk_add_f32 v[34:35], v[30:31], v[28:29]
	v_add_u32_e32 v28, s18, v15
	ds_read_b128 v[28:31], v28
	v_pk_add_f32 v[26:27], v[32:33], v[26:27]
	s_waitcnt lgkmcnt(1)
	v_pk_add_f32 v[32:33], v[34:35], v[24:25]
	v_pk_add_f32 v[26:27], v[26:27], v[22:23]
	ds_read_b128 v[22:25], v4 offset:2048
	s_waitcnt lgkmcnt(1)
	v_pk_add_f32 v[54:55], v[32:33], v[30:31]
	v_pk_add_f32 v[56:57], v[26:27], v[28:29]
	ds_read_b128 v[26:29], v4 offset:18432
	ds_read_b128 v[30:33], v4 offset:3072
	s_ashr_i32 s4, s4, 6
	s_waitcnt lgkmcnt(2)
	v_pk_add_f32 v[38:39], v[24:25], 0 op_sel_hi:[1,0]
	v_pk_add_f32 v[40:41], v[22:23], 0 op_sel_hi:[1,0]
	ds_read_b128 v[22:25], v4 offset:34816
	ds_read_b128 v[34:37], v4 offset:19456
	s_waitcnt lgkmcnt(3)
	v_pk_add_f32 v[38:39], v[38:39], v[28:29]
	v_pk_add_f32 v[42:43], v[40:41], v[26:27]
	ds_read_b128 v[26:29], v4 offset:35840
	s_waitcnt lgkmcnt(2)
	v_pk_add_f32 v[46:47], v[38:39], v[24:25]
	ds_read_b128 v[38:41], v4 offset:51200
	v_pk_add_f32 v[48:49], v[42:43], v[22:23]
	v_add_u32_e32 v22, s19, v12
	ds_read_b128 v[22:25], v22
	ds_read_b128 v[42:45], v4 offset:52224
	v_add_u32_e32 v4, s19, v13
	s_waitcnt lgkmcnt(2)
	v_pk_add_f32 v[46:47], v[46:47], v[40:41]
	v_pk_add_f32 v[48:49], v[48:49], v[38:39]
	ds_read_b128 v[38:41], v4
	v_add_u32_e32 v4, s19, v14
	s_waitcnt lgkmcnt(2)
; __device__ __forceinline__ unsigned lane_tb(int fr, int fq) { return (unsigned)((fr * 64 + fq * 16) ^ ((fr >> 3) << 5)); }
; __device__ __forceinline__ void st_bf8(bf16* p, const f32x4 a, const f32x4 b) { *(GAS v4u*)p = (v4u){pk2(a.x, a.y), pk2(a.z, a.w), pk2(b.x, b.y), pk2(b.z, b.w)}; }
;     template <int NR> __device__ __forceinline__ void rows(const int (&rowb)[NR], int fr, const float (&rstd)[NR], const f32x4 (&a)[NR][2][2], int pn, int wc, int fq) const {
; #pragma unroll
;         for (int i = 0; i < NR; ++i) {
;             const float rr = rstd[i];
; #pragma unroll
;             for (int bj = 0; bj < 2; ++bj) {
;                 f32x4 u = a[i][bj][0] * rr, v = a[i][bj][1] * rr;
; #pragma unroll
;                 for (int j = 0; j < 4; ++j) { const float p = fmaxf(u[j], 0.f), q = fmaxf(v[j], 0.f); u[j] = p * p; v[j] = q * q; }
;                 st_bf8((bf16*)((char*)H + tile_ub(rowb[i], (pn << 8) + 64 * wc + 32 * bj, FF) + lane_tb(fr, fq)), u, v);
;             }
;         }
;     }
; template <class RowEpi, int MTL>
; __device__ __forceinline__ void small_gemm_t(Frame& F, const bf16* A  , const bf16* Bt, int N, int K, const RowEpi& R, int i_lo, int i_hi) {
;     ...
;                     for (int ww = 0; ww < 8; ++ww) t += part[(ww * (4 * MTL) + w * 4 + bj * 2 + n) * 64 + lane];
;                     s[bj][n] = t; }
;             const int row1[1] = {MP + rb * 16 * MTL + 16 * w}; const f32x4 a1[1][2][2] = {{{s[0][0], s[0][1]}, {s[1][0], s[1][1]}}};
;             const float rr1[1] = {rsp ? rsqrtf(rsv * (1.f / DM) + EPS) : 1.f};
;             R.template rows<1>(row1, fr, rr1, a1, pn, wc, fq);
;         }
	v_pk_add_f32 v[58:59], v[46:47], v[24:25]
	v_pk_add_f32 v[60:61], v[48:49], v[22:23]
	ds_read_b128 v[22:25], v4
	v_add_u32_e32 v4, s19, v15
	ds_read_b128 v[46:49], v4
	s_waitcnt lgkmcnt(2)
	v_pk_add_f32 v[40:41], v[58:59], v[40:41]
	v_pk_add_f32 v[38:39], v[60:61], v[38:39]
	s_waitcnt lgkmcnt(1)
	v_pk_add_f32 v[24:25], v[40:41], v[24:25]
	v_pk_add_f32 v[22:23], v[38:39], v[22:23]
	s_waitcnt lgkmcnt(0)
	v_pk_add_f32 v[38:39], v[24:25], v[48:49]
	v_pk_add_f32 v[40:41], v[22:23], v[46:47]
	v_pk_add_f32 v[22:23], v[32:33], 0 op_sel_hi:[1,0]
	v_pk_add_f32 v[24:25], v[30:31], 0 op_sel_hi:[1,0]
	v_pk_add_f32 v[22:23], v[22:23], v[36:37]
	v_pk_add_f32 v[24:25], v[24:25], v[34:35]
	v_add_u32_e32 v4, s20, v12
	v_pk_add_f32 v[28:29], v[22:23], v[28:29]
	v_pk_add_f32 v[26:27], v[24:25], v[26:27]
	ds_read_b128 v[22:25], v4
	v_add_u32_e32 v4, s20, v13
	v_pk_add_f32 v[30:31], v[28:29], v[44:45]
	v_pk_add_f32 v[32:33], v[26:27], v[42:43]
	ds_read_b128 v[26:29], v4
	v_add_u32_e32 v4, s20, v14
	s_waitcnt lgkmcnt(1)
	v_pk_add_f32 v[30:31], v[30:31], v[24:25]
	v_pk_add_f32 v[32:33], v[32:33], v[22:23]
	ds_read_b128 v[22:25], v4
	v_add_u32_e32 v4, s20, v15
	s_waitcnt lgkmcnt(1)
	v_pk_add_f32 v[30:31], v[30:31], v[28:29]
	v_pk_add_f32 v[32:33], v[32:33], v[26:27]
	ds_read_b128 v[26:29], v4
	v_mul_f32_e32 v4, 0x4b800000, v21
	v_cndmask_b32_e32 v4, v21, v4, vcc
	s_ashr_i32 s5, s4, 31
	s_lshl_b64 s[14:15], s[10:11], 21
	s_lshl_b32 s10, s23, 7
	v_rsq_f32_e32 v4, v4
	s_lshl_b64 s[4:5], s[4:5], 15
	s_and_b32 s23, s10, 0x4000
	s_and_b32 s10, s10, 0x3800
	s_add_u32 s14, s52, s14
	s_addc_u32 s15, s53, s15
	s_add_u32 s4, s14, s4
	v_mul_f32_e32 v21, 0x45800000, v4
	s_addc_u32 s5, s15, s5
	s_waitcnt lgkmcnt(1)
	v_pk_add_f32 v[24:25], v[30:31], v[24:25]
	v_pk_add_f32 v[22:23], v[32:33], v[22:23]
	v_cndmask_b32_e32 v4, v4, v21, vcc
	s_add_u32 s4, s4, s23
	s_waitcnt lgkmcnt(0)
	v_pk_add_f32 v[28:29], v[24:25], v[28:29]
	v_pk_add_f32 v[26:27], v[22:23], v[26:27]
	v_pk_mul_f32 v[22:23], v[4:5], v[50:51] op_sel_hi:[0,1]
	v_pk_mul_f32 v[24:25], v[4:5], v[52:53] op_sel_hi:[0,1]
	v_pk_mul_f32 v[30:31], v[4:5], v[54:55] op_sel_hi:[0,1]
	v_pk_mul_f32 v[32:33], v[4:5], v[56:57] op_sel_hi:[0,1]
	s_addc_u32 s5, s5, 0
	v_max_f32_e32 v24, 0, v24
	v_max_f32_e32 v32, 0, v32
	v_max_f32_e32 v25, 0, v25
	v_max_f32_e32 v33, 0, v33
	v_max_f32_e32 v22, 0, v22
	v_max_f32_e32 v30, 0, v30
	v_max_f32_e32 v23, 0, v23
	v_max_f32_e32 v31, 0, v31
	s_add_u32 s4, s4, s10
	v_pk_mul_f32 v[24:25], v[24:25], v[24:25]
	v_pk_mul_f32 v[32:33], v[32:33], v[32:33]
	v_pk_mul_f32 v[34:35], v[22:23], v[22:23]
	v_pk_mul_f32 v[30:31], v[30:31], v[30:31]
	s_addc_u32 s5, s5, 0
	v_lshl_add_u64 v[36:37], s[4:5], 0, v[2:3]
	v_cvt_pk_bf16_f32 v22, v24, v25
	v_cvt_pk_bf16_f32 v23, v34, v35
	v_cvt_pk_bf16_f32 v24, v32, v33
	v_cvt_pk_bf16_f32 v25, v30, v31
	global_store_dwordx4 v[36:37], v[22:25], off sc1
	v_pk_mul_f32 v[28:29], v[4:5], v[28:29] op_sel_hi:[0,1]
	v_pk_mul_f32 v[26:27], v[4:5], v[26:27] op_sel_hi:[0,1]
	v_pk_mul_f32 v[22:23], v[4:5], v[38:39] op_sel_hi:[0,1]
	v_pk_mul_f32 v[24:25], v[4:5], v[40:41] op_sel_hi:[0,1]
	v_max_f32_e32 v24, 0, v24
	v_max_f32_e32 v26, 0, v26
	v_max_f32_e32 v25, 0, v25
	v_max_f32_e32 v27, 0, v27
	v_max_f32_e32 v22, 0, v22
	v_max_f32_e32 v28, 0, v28
	v_max_f32_e32 v23, 0, v23
	v_max_f32_e32 v29, 0, v29
	v_pk_mul_f32 v[24:25], v[24:25], v[24:25]
	v_pk_mul_f32 v[26:27], v[26:27], v[26:27]
	v_pk_mul_f32 v[30:31], v[22:23], v[22:23]
	v_pk_mul_f32 v[28:29], v[28:29], v[28:29]
	v_cvt_pk_bf16_f32 v22, v24, v25
	v_cvt_pk_bf16_f32 v23, v30, v31
	v_cvt_pk_bf16_f32 v24, v26, v27
	v_cvt_pk_bf16_f32 v25, v28, v29
	global_store_dwordx4 v[36:37], v[22:25], off offset:1024 sc1
	s_branch .LBB0_2014

; __device__ __forceinline__ unsigned xb_add(unsigned* p, unsigned v) { return __hip_atomic_fetch_add(p, v, __ATOMIC_RELAXED, __HIP_MEMORY_SCOPE_AGENT); }
; __device__ __forceinline__ void xcd_barrier(const XcdBarrier& b) {
;     ...
;         const unsigned old = xb_add(&bar[XB_XSUB(b.x)], 1u);
;         const unsigned gen = old / nloc;
;         if (old + 1u == (gen + 1u) * nloc) {
;             __builtin_amdgcn_fence(__ATOMIC_RELEASE, "agent");
;             asm volatile("s_waitcnt vmcnt(0)" ::: "memory");
;             const unsigned og = xb_add(&bar[XB_TOP], 1u);
;             const unsigned tg = og / nx;
;             if (og + 1u == (tg + 1u) * nx) xb_add(&bar[XB_TOPGEN], 1u);
.LBB0_2054:
	s_andn2_saveexec_b64 s[8:9], s[8:9]
	s_cbranch_execz .LBB0_2074
	s_mov_b64 s[8:9], exec
	s_nop 0
	s_nop 0
	s_waitcnt lgkmcnt(0)
	s_waitcnt vmcnt(0)
	v_mbcnt_lo_u32_b32 v2, s8, 0
	v_mbcnt_hi_u32_b32 v2, s9, v2
	v_cmp_eq_u32_e32 vcc, 0, v2
	s_and_saveexec_b64 s[10:11], vcc
	s_cbranch_execz .LBB0_2057
	s_bcnt1_i32_b64 s3, s[8:9]
	v_mov_b32_e32 v3, 0x7000
	v_mov_b32_e32 v4, s3
	global_atomic_add v3, v3, v4, s[30:31] offset:1024 sc0
